# weight-convert loops: vmcnt ladder counts the 4 readout stores as in flight (11..4) with one drain before the loop
# baseline (speedup 1.0000x reference)
; __device__ __forceinline__ unsigned cvt_pk_bf16(float lo, float hi) { unsigned r; asm volatile("v_cvt_pk_bf16_f32 %0, %1, %2" : "=v"(r) : "v"(lo), "v"(hi)); return r; }
; __device__ __forceinline__ void convert_t(const float* __restrict__ W, int K, int N, bf16_t* __restrict__ Wt, int swiglu, int& cursor, float* tile, int perm) {
;     int bid_ = blockIdx.x, gdim_ = gridDim.x; asm volatile("" : "+s"(bid_), "+s"(gdim_));
;     int tix_ = threadIdx.x; asm volatile("" : "+v"(tix_));
;     const int tid = tix_, G = gdim_; const int ntn = N / 256, nt = (K / 64) * ntn;
;     const int first = cursor; cursor += nt;
;     int id = first + (((int)bid_ - (first % G)) + G) % G;
;     const int last = first + nt * CONV_REP;
;     float4 v[8];
;     if (id < last) { const int tl = (id - first) % nt; const int k0 = (tl / ntn) * 64, n0 = (tl % ntn) * 256;
; #pragma unroll
;         for (int i = 0; i < 8; ++i) { const int idx = tid + 512 * i; const int row = idx >> 6, c4 = idx & 63; v[i] = *(const float4*)(W + (size_t)(k0 + row) * N + n0 + 4 * c4); } }
;     ...
;         for (int p = 0; p < 4; ++p) { const int nl = (tid >> 3) + 64 * p, kq = tid & 7; const float* s = tile + (8 * kq) * 257 + nl;
;             u32x4 w; w.x = cvt_pk_bf16(s[0], s[257]); w.y = cvt_pk_bf16(s[2 * 257], s[3 * 257]); w.z = cvt_pk_bf16(s[4 * 257], s[5 * 257]); w.w = cvt_pk_bf16(s[6 * 257], s[7 * 257]);
;             int n = n0 + nl; if (swiglu) { const int half = n >= DFF ? 1 : 0; const int c = n - half * DFF; n = (c >> 7) * 256 + half * 128 + (c & 127); }
;             { const int pn = n >> 8, half = (n >> 7) & 1, r = n & 127, c5 = r & 31;
;               const int R = perm ? ((r & ~31) + 16 * ((c5 >> 2) & 1) + 4 * (c5 >> 3) + (c5 & 3)) : r;
;               *(u32x4*)((unsigned char*)Wt + ((size_t)pn * (K >> 6) + (k0 >> 6)) * 32768 + half * 16384 + pg8::lds_byte(R, 8 * kq)) = w; } }
.LBB0_5:
	s_or_b64 exec, exec, s[4:5]
	s_mov_b64 s[38:39], s[0:1]
	s_load_dwordx8 s[8:15], s[38:39], 0x0
	s_load_dwordx2 s[36:37], s[38:39], 0x20
	s_load_dwordx2 s[30:31], s[38:39], 0x30
	s_load_dwordx2 s[28:29], s[38:39], 0x48
	s_load_dwordx8 s[16:23], s[38:39], 0x60
	s_load_dwordx4 s[4:7], s[38:39], 0x88
	s_load_dwordx2 s[26:27], s[38:39], 0xa8
	s_mov_b32 s38, s2
	s_mov_b32 s39, s40
	s_mov_b32 s38, s2
	s_mov_b32 s46, s40
	s_abs_i32 s39, s46
	v_cvt_f32_u32_e32 v1, s39
	s_sub_i32 s48, 0, s39
	s_add_i32 s38, s46, s38
	s_ashr_i32 s47, s38, 31
	v_rcp_iflag_f32_e32 v1, v1
	s_abs_i32 s38, s38
	v_mov_b32_e32 v36, v228
	v_mul_f32_e32 v1, 0x4f7ffffe, v1
	v_cvt_u32_f32_e32 v1, v1
	s_nop 0
	v_readfirstlane_b32 s49, v1
	s_mul_i32 s48, s48, s49
	s_mul_hi_u32 s48, s49, s48
	s_add_i32 s49, s49, s48
	s_mul_hi_u32 s48, s38, s49
	s_mul_i32 s48, s48, s39
	s_sub_i32 s38, s38, s48
	s_sub_i32 s48, s38, s39
	s_cmp_ge_u32 s38, s39
	s_cselect_b32 s38, s48, s38
	s_sub_i32 s48, s38, s39
	s_cmp_ge_u32 s38, s39
	s_cselect_b32 s38, s48, s38
	s_xor_b32 s38, s38, s47
	s_sub_i32 s38, s38, s47
	s_cmpk_gt_i32 s38, 0x55f
	s_cbranch_scc1 .LBB0_10
	s_mul_hi_i32 s39, s38, 0x2fa0be83
	s_lshr_b32 s47, s39, 31
	s_ashr_i32 s39, s39, 8
	s_add_i32 s39, s39, s47
	s_mulk_i32 s39, 0x560
	s_sub_i32 s39, s38, s39
	s_sext_i32_i16 s47, s39
	s_mulk_i32 s47, 0x2fa1
	s_lshr_b32 s48, s47, 31
	s_ashr_i32 s47, s47, 19
	s_add_i32 s47, s47, s48
	s_sext_i32_i16 s48, s47
	s_mul_i32 s47, s47, 43
	s_sub_i32 s39, s39, s47
	s_sext_i32_i16 s39, s39
	s_lshl_b32 s50, s48, 6
	s_lshl_b32 s48, s39, 8
	s_ashr_i32 s49, s48, 31
	s_lshl_b64 s[48:49], s[48:49], 2
	s_waitcnt lgkmcnt(0)
	s_add_u32 s48, s14, s48
	v_lshlrev_b32_e32 v37, 4, v36
	s_addc_u32 s49, s15, s49
	v_and_b32_e32 v34, 0x3f0, v37
	v_mov_b32_e32 v35, 0
	v_ashrrev_i32_e32 v1, 6, v36
	v_lshl_add_u64 v[26:27], s[48:49], 0, v[34:35]
	v_add_u32_e32 v2, s50, v1
	s_mov_b32 s47, 0xac00
	v_mad_i64_i32 v[10:11], s[48:49], v2, s47, v[26:27]
	v_add_u32_e32 v2, 0x200, v36
	v_ashrrev_i32_e32 v44, 6, v2
	v_add_u32_e32 v2, s50, v44
	v_mad_i64_i32 v[12:13], s[48:49], v2, s47, v[26:27]
	global_load_dwordx4 v[2:5], v[10:11], off
	global_load_dwordx4 v[6:9], v[12:13], off
	v_add_u32_e32 v10, 0x400, v36
	v_ashrrev_i32_e32 v45, 6, v10
	v_add_u32_e32 v10, s50, v45
	v_mad_i64_i32 v[18:19], s[48:49], v10, s47, v[26:27]
	v_add_u32_e32 v10, 0x600, v36
	v_ashrrev_i32_e32 v46, 6, v10
	v_add_u32_e32 v10, s50, v46
	v_mad_i64_i32 v[20:21], s[48:49], v10, s47, v[26:27]
	global_load_dwordx4 v[10:13], v[18:19], off
	global_load_dwordx4 v[14:17], v[20:21], off
	v_add_u32_e32 v18, 0x800, v36
	v_ashrrev_i32_e32 v47, 6, v18
	v_add_u32_e32 v18, s50, v47
	v_mad_i64_i32 v[28:29], s[48:49], v18, s47, v[26:27]
	v_add_u32_e32 v18, 0xa00, v36
	v_ashrrev_i32_e32 v48, 6, v18
	v_add_u32_e32 v18, s50, v48
	v_mad_i64_i32 v[30:31], s[48:49], v18, s47, v[26:27]
	global_load_dwordx4 v[18:21], v[28:29], off
	global_load_dwordx4 v[22:25], v[30:31], off
	v_add_u32_e32 v28, 0xc00, v36
	v_ashrrev_i32_e32 v49, 6, v28
	v_add_u32_e32 v28, s50, v49
	v_mad_i64_i32 v[38:39], s[48:49], v28, s47, v[26:27]
	v_add_u32_e32 v28, 0xe00, v36
	v_ashrrev_i32_e32 v50, 6, v28
	v_add_u32_e32 v28, s50, v50
	v_mad_i64_i32 v[40:41], s[48:49], v28, s47, v[26:27]
	global_load_dwordx4 v[26:29], v[38:39], off
	global_load_dwordx4 v[30:33], v[40:41], off
	v_ashrrev_i32_e32 v51, 3, v36
	v_lshlrev_b32_e32 v36, 3, v36
	v_and_b32_e32 v38, 56, v36
	v_mul_u32_u24_e32 v38, 0x404, v38
	v_bfe_u32 v40, v36, 5, 1
	v_and_b32_e32 v36, 48, v37
	v_lshlrev_b32_e32 v37, 2, v51
	v_add3_u32 v52, 0, v38, v37
	v_and_b32_e32 v38, 0x60, v51
	v_and_or_b32 v37, v37, 16, v38
	v_lshrrev_b32_e32 v38, 1, v51
	v_and_b32_e32 v39, 3, v51
	v_add_u32_e32 v53, 64, v51
	v_add_u32_e32 v54, 0xc0, v51
	v_and_or_b32 v38, v38, 12, v39
	v_lshl_or_b32 v41, v38, 6, v36
	v_and_b32_e32 v38, 0x60, v53
	v_lshlrev_b32_e32 v39, 2, v53
	v_and_b32_e32 v63, 0x60, v54
	v_lshlrev_b32_e32 v64, 2, v54
	v_lshrrev_b32_e32 v37, 3, v37
	v_and_or_b32 v38, v39, 16, v38
	v_and_or_b32 v63, v64, 16, v63
	v_or_b32_e32 v37, v37, v40
	v_lshrrev_b32_e32 v38, 3, v38
	v_lshrrev_b32_e32 v63, 3, v63
	s_movk_i32 s39, 0x404
	v_lshlrev_b32_e32 v36, 10, v37
	v_lshlrev_b32_e32 v37, 1, v51
	v_or_b32_e32 v38, v38, v40
	v_or_b32_e32 v40, v63, v40
	v_add_u32_e32 v42, 0, v34
	v_mul_lo_u32 v43, v1, s39
	v_mul_lo_u32 v56, v44, s39
	v_mul_lo_u32 v57, v45, s39
	v_mul_lo_u32 v58, v46, s39
	v_mul_lo_u32 v59, v47, s39
	v_mul_lo_u32 v60, v48, s39
	v_mul_lo_u32 v61, v49, s39
	v_mul_lo_u32 v62, v50, s39
	v_and_b32_e32 v55, 32, v37
	v_lshlrev_b32_e32 v38, 10, v38
	v_lshlrev_b32_e32 v40, 10, v40
	v_bitop3_b32 v36, v36, v41, v55 bitop3:0xf6
	v_mov_b32_e32 v37, v35
	v_bitop3_b32 v38, v38, v41, v55 bitop3:0xf6
	v_mov_b32_e32 v39, v35
	v_bitop3_b32 v40, v40, v41, v55 bitop3:0xf6
	v_mov_b32_e32 v41, v35
	v_add_u32_e32 v55, v42, v43
	v_add_u32_e32 v56, v42, v56
	v_add_u32_e32 v57, v42, v57
	v_add_u32_e32 v58, v42, v58
	v_add_u32_e32 v59, v42, v59
	v_add_u32_e32 v60, v42, v60
	v_add_u32_e32 v61, v42, v61
	v_add_u32_e32 v62, v42, v62
	s_movk_i32 s48, 0x157f
	v_mov_b32_e32 v63, 0xffffea80
	v_mov_b32_e32 v64, 0x4000
	v_lshl_add_u64 v[42:43], s[14:15], 0, v[34:35]
	s_waitcnt vmcnt(0)
	s_branch .LBB0_8

; __device__ __forceinline__ void convert_t(const float* __restrict__ W, int K, int N, bf16_t* __restrict__ Wt, int swiglu, int& cursor, float* tile, int perm) {
;     ...
;     for (; id < last; id += G) {
;         const int tl = (id - first) % nt; const int k0 = (tl / ntn) * 64, n0 = (tl % ntn) * 256;
; #pragma unroll
;         for (int i = 0; i < 8; ++i) { const int idx = tid + 512 * i; const int row = idx >> 6, c4 = idx & 63; float* d = tile + row * 257 + 4 * c4; d[0] = v[i].x; d[1] = v[i].y; d[2] = v[i].z; d[3] = v[i].w; }
;         __syncthreads();
;         if (id + G < last) { const int tl2 = (id + G - first) % nt; const int k2 = (tl2 / ntn) * 64, n2 = (tl2 % ntn) * 256;
; #pragma unroll
;             for (int i = 0; i < 8; ++i) { const int idx = tid + 512 * i; const int row = idx >> 6, c4 = idx & 63; v[i] = *(const float4*)(W + (size_t)(k2 + row) * N + n2 + 4 * c4); } }
.LBB0_8:
	s_add_i32 s49, s38, s46
	s_cmpk_gt_i32 s49, 0x55f
	s_cselect_b64 s[14:15], -1, 0
	s_and_b64 vcc, exec, s[14:15]
	s_waitcnt vmcnt(11)
	ds_write2_b32 v55, v2, v3 offset1:1
	ds_write2_b32 v55, v4, v5 offset0:2 offset1:3
	s_waitcnt vmcnt(10)
	ds_write2_b32 v56, v6, v7 offset1:1
	ds_write2_b32 v56, v8, v9 offset0:2 offset1:3
	s_waitcnt vmcnt(9)
	ds_write2_b32 v57, v10, v11 offset1:1
	ds_write2_b32 v57, v12, v13 offset0:2 offset1:3
	s_waitcnt vmcnt(8)
	ds_write2_b32 v58, v14, v15 offset1:1
	ds_write2_b32 v58, v16, v17 offset0:2 offset1:3
	s_waitcnt vmcnt(7)
	ds_write2_b32 v59, v18, v19 offset1:1
	ds_write2_b32 v59, v20, v21 offset0:2 offset1:3
	s_waitcnt vmcnt(6)
	ds_write2_b32 v60, v22, v23 offset1:1
	ds_write2_b32 v60, v24, v25 offset0:2 offset1:3
	s_waitcnt vmcnt(5)
	ds_write2_b32 v61, v26, v27 offset1:1
	ds_write2_b32 v61, v28, v29 offset0:2 offset1:3
	s_waitcnt vmcnt(4)
	ds_write2_b32 v62, v30, v31 offset1:1
	ds_write2_b32 v62, v32, v33 offset0:2 offset1:3
	s_waitcnt lgkmcnt(0)
	s_barrier
	s_cbranch_vccnz .LBB0_7
	s_mul_hi_i32 s39, s49, 0x2fa0be83
	s_lshr_b32 s50, s39, 31
	s_ashr_i32 s39, s39, 8
	s_add_i32 s39, s39, s50
	s_mulk_i32 s39, 0x560
	s_sub_i32 s39, s49, s39
	s_sext_i32_i16 s50, s39
	s_mulk_i32 s50, 0x2fa1
	s_lshr_b32 s51, s50, 31
	s_ashr_i32 s50, s50, 19
	s_add_i32 s50, s50, s51
	s_lshl_b32 s52, s50, 6
	s_mul_i32 s50, s50, 43
	s_sub_i32 s39, s39, s50
	s_sext_i32_i16 s39, s39
	s_lshl_b32 s50, s39, 8
	s_ashr_i32 s51, s50, 31
	v_lshl_add_u64 v[26:27], s[50:51], 2, v[42:43]
	v_add_u32_e32 v2, s52, v1
	v_mad_i64_i32 v[10:11], s[50:51], v2, s47, v[26:27]
	v_add_u32_e32 v2, s52, v44
	v_mad_i64_i32 v[12:13], s[50:51], v2, s47, v[26:27]
	global_load_dwordx4 v[2:5], v[10:11], off
	global_load_dwordx4 v[6:9], v[12:13], off
	v_add_u32_e32 v10, s52, v45
	v_add_u32_e32 v12, s52, v46
	v_add_u32_e32 v18, s52, v47
	v_add_u32_e32 v20, s52, v48
	v_add_u32_e32 v28, s52, v49
	v_add_u32_e32 v30, s52, v50
	v_mad_i64_i32 v[10:11], s[50:51], v10, s47, v[26:27]
	v_mad_i64_i32 v[14:15], s[50:51], v12, s47, v[26:27]
	v_mad_i64_i32 v[18:19], s[50:51], v18, s47, v[26:27]
	v_mad_i64_i32 v[22:23], s[50:51], v20, s47, v[26:27]
	v_mad_i64_i32 v[28:29], s[50:51], v28, s47, v[26:27]
	v_mad_i64_i32 v[30:31], s[50:51], v30, s47, v[26:27]
	global_load_dwordx4 v[10:13], v[10:11], off
	s_nop 0
	global_load_dwordx4 v[14:17], v[14:15], off
	s_nop 0
	global_load_dwordx4 v[18:21], v[18:19], off
	s_nop 0
	global_load_dwordx4 v[22:25], v[22:23], off
	s_nop 0
	global_load_dwordx4 v[26:29], v[28:29], off
	s_nop 0
	global_load_dwordx4 v[30:33], v[30:31], off
	s_branch .LBB0_7
; __device__ __forceinline__ unsigned cvt_pk_bf16(float lo, float hi) { unsigned r; asm volatile("v_cvt_pk_bf16_f32 %0, %1, %2" : "=v"(r) : "v"(lo), "v"(hi)); return r; }
; __device__ __forceinline__ void convert_t(const float* __restrict__ W, int K, int N, bf16_t* __restrict__ Wt, int swiglu, int& cursor, float* tile, int perm) {
;     int bid_ = blockIdx.x, gdim_ = gridDim.x; asm volatile("" : "+s"(bid_), "+s"(gdim_));
;     int tix_ = threadIdx.x; asm volatile("" : "+v"(tix_));
;     const int tid = tix_, G = gdim_; const int ntn = N / 256, nt = (K / 64) * ntn;
;     const int first = cursor; cursor += nt;
;     int id = first + (((int)bid_ - (first % G)) + G) % G;
;     const int last = first + nt * CONV_REP;
;     float4 v[8];
;     if (id < last) { const int tl = (id - first) % nt; const int k0 = (tl / ntn) * 64, n0 = (tl % ntn) * 256;
; #pragma unroll
;         for (int i = 0; i < 8; ++i) { const int idx = tid + 512 * i; const int row = idx >> 6, c4 = idx & 63; v[i] = *(const float4*)(W + (size_t)(k0 + row) * N + n0 + 4 * c4); } }
;     ...
;         for (int p = 0; p < 4; ++p) { const int nl = (tid >> 3) + 64 * p, kq = tid & 7; const float* s = tile + (8 * kq) * 257 + nl;
;             u32x4 w; w.x = cvt_pk_bf16(s[0], s[257]); w.y = cvt_pk_bf16(s[2 * 257], s[3 * 257]); w.z = cvt_pk_bf16(s[4 * 257], s[5 * 257]); w.w = cvt_pk_bf16(s[6 * 257], s[7 * 257]);
;             int n = n0 + nl; if (swiglu) { const int half = n >= DFF ? 1 : 0; const int c = n - half * DFF; n = (c >> 7) * 256 + half * 128 + (c & 127); }
;             { const int pn = n >> 8, half = (n >> 7) & 1, r = n & 127, c5 = r & 31;
;               const int R = perm ? ((r & ~31) + 16 * ((c5 >> 2) & 1) + 4 * (c5 >> 3) + (c5 & 3)) : r;
;               *(u32x4*)((unsigned char*)Wt + ((size_t)pn * (K >> 6) + (k0 >> 6)) * 32768 + half * 16384 + pg8::lds_byte(R, 8 * kq)) = w; } }
.LBB0_10:
	s_waitcnt lgkmcnt(0)
	s_mov_b32 s14, s2
	s_mov_b32 s38, s40
	s_abs_i32 s15, s38
	v_cvt_f32_u32_e32 v1, s15
	s_sub_i32 s39, 0, s15
	v_mov_b32_e32 v38, v228
	v_rcp_iflag_f32_e32 v1, v1
	s_nop 0
	v_mul_f32_e32 v1, 0x4f7ffffe, v1
	v_cvt_u32_f32_e32 v1, v1
	s_nop 0
	v_readfirstlane_b32 s46, v1
	s_mul_i32 s39, s39, s46
	s_mul_hi_u32 s39, s46, s39
	s_add_i32 s46, s46, s39
	s_mul_hi_u32 s39, s46, 0x560
	s_mul_i32 s39, s39, s15
	s_sub_i32 s39, 0x560, s39
	s_sub_i32 s47, s39, s15
	s_cmp_ge_u32 s39, s15
	s_cselect_b32 s39, s47, s39
	s_sub_i32 s47, s39, s15
	s_cmp_ge_u32 s39, s15
	s_cselect_b32 s39, s47, s39
	s_add_i32 s14, s38, s14
	s_sub_i32 s14, s14, s39
	s_ashr_i32 s39, s14, 31
	s_abs_i32 s14, s14
	s_mul_hi_u32 s46, s14, s46
	s_mul_i32 s46, s46, s15
	s_sub_i32 s14, s14, s46
	s_sub_i32 s46, s14, s15
	s_cmp_ge_u32 s14, s15
	s_cselect_b32 s14, s46, s14
	s_sub_i32 s46, s14, s15
	s_cmp_ge_u32 s14, s15
	s_cselect_b32 s14, s46, s14
	s_xor_b32 s14, s14, s39
	s_sub_i32 s39, s14, s39
	s_cmpk_gt_i32 s39, 0x2af
	s_cbranch_scc1 .LBB0_15
	s_add_u32 s14, s26, 0x2b00000
	s_mul_hi_i32 s46, s39, 0x2fa0be83
	s_addc_u32 s15, s27, 0
	s_lshr_b32 s47, s46, 31
	s_lshr_b32 s46, s46, 7
	s_add_i32 s46, s46, s47
	s_mulk_i32 s46, 0x2b0
	s_sub_i32 s46, s39, s46
	s_sext_i32_i16 s47, s46
	s_bfe_u32 s47, s47, 0x3001c
	s_add_i32 s47, s46, s47
	s_sext_i32_i16 s48, s47
	s_and_b32 s47, s47, 0xfff8
	s_sub_i32 s46, s46, s47
	s_sext_i32_i16 s46, s46
	s_lshl_b32 s46, s46, 8
	s_lshl_b32 s48, s48, 3
	s_ashr_i32 s47, s46, 31
	s_andn2_b32 s48, s48, 63
	s_lshl_b64 s[46:47], s[46:47], 2
	v_ashrrev_i32_e32 v1, 6, v38
	s_add_u32 s46, s36, s46
	v_lshlrev_b32_e32 v39, 4, v38
	s_waitcnt vmcnt(11)
	v_add_u32_e32 v2, s48, v1
	s_addc_u32 s47, s37, s47
	v_and_b32_e32 v34, 0x3f0, v39
	v_mov_b32_e32 v35, 0
	v_ashrrev_i32_e32 v3, 31, v2
	s_waitcnt vmcnt(5)
	v_lshl_add_u64 v[26:27], s[46:47], 0, v[34:35]
	v_lshlrev_b64 v[2:3], 13, v[2:3]
	v_lshl_add_u64 v[10:11], v[26:27], 0, v[2:3]
	v_add_u32_e32 v2, 0x200, v38
	v_ashrrev_i32_e32 v46, 6, v2
	v_add_u32_e32 v2, s48, v46
	v_ashrrev_i32_e32 v3, 31, v2
	v_lshlrev_b64 v[2:3], 13, v[2:3]
	v_lshl_add_u64 v[12:13], v[26:27], 0, v[2:3]
	global_load_dwordx4 v[2:5], v[10:11], off
	global_load_dwordx4 v[6:9], v[12:13], off
	v_add_u32_e32 v10, 0x400, v38
	v_ashrrev_i32_e32 v47, 6, v10
	v_add_u32_e32 v10, s48, v47
	v_ashrrev_i32_e32 v11, 31, v10
	v_lshlrev_b64 v[10:11], 13, v[10:11]
	v_lshl_add_u64 v[18:19], v[26:27], 0, v[10:11]
	v_add_u32_e32 v10, 0x600, v38
	v_ashrrev_i32_e32 v48, 6, v10
	v_add_u32_e32 v10, s48, v48
	v_ashrrev_i32_e32 v11, 31, v10
	v_lshlrev_b64 v[10:11], 13, v[10:11]
	v_lshl_add_u64 v[20:21], v[26:27], 0, v[10:11]
	global_load_dwordx4 v[10:13], v[18:19], off
	global_load_dwordx4 v[14:17], v[20:21], off
	v_add_u32_e32 v18, 0x800, v38
	v_ashrrev_i32_e32 v49, 6, v18
	v_add_u32_e32 v18, s48, v49
	v_ashrrev_i32_e32 v19, 31, v18
	v_lshlrev_b64 v[18:19], 13, v[18:19]
	v_lshl_add_u64 v[28:29], v[26:27], 0, v[18:19]
	v_add_u32_e32 v18, 0xa00, v38
	v_ashrrev_i32_e32 v50, 6, v18
	v_add_u32_e32 v18, s48, v50
	v_ashrrev_i32_e32 v19, 31, v18
	v_lshlrev_b64 v[18:19], 13, v[18:19]
	s_waitcnt vmcnt(8)
	v_lshl_add_u64 v[30:31], v[26:27], 0, v[18:19]
	global_load_dwordx4 v[18:21], v[28:29], off
	global_load_dwordx4 v[22:25], v[30:31], off
	v_add_u32_e32 v28, 0xc00, v38
	v_ashrrev_i32_e32 v51, 6, v28
	v_add_u32_e32 v28, s48, v51
	v_ashrrev_i32_e32 v29, 31, v28
	v_lshlrev_b64 v[28:29], 13, v[28:29]
	v_lshl_add_u64 v[36:37], v[26:27], 0, v[28:29]
	v_add_u32_e32 v28, 0xe00, v38
	v_ashrrev_i32_e32 v52, 6, v28
	v_add_u32_e32 v28, s48, v52
	v_ashrrev_i32_e32 v29, 31, v28
	v_lshlrev_b64 v[28:29], 13, v[28:29]
	v_lshl_add_u64 v[40:41], v[26:27], 0, v[28:29]
	global_load_dwordx4 v[26:29], v[36:37], off
	global_load_dwordx4 v[30:33], v[40:41], off
	v_add_u32_e32 v68, 0, v34
	v_lshl_add_u64 v[36:37], s[36:37], 0, v[34:35]
	v_lshlrev_b32_e32 v34, 3, v38
	v_ashrrev_i32_e32 v53, 3, v38
	v_and_b32_e32 v38, 56, v34
	v_mul_u32_u24_e32 v38, 0x404, v38
	v_bfe_u32 v54, v34, 5, 1
	v_lshlrev_b32_e32 v34, 2, v53
	v_add3_u32 v55, 0, v38, v34
	v_lshrrev_b32_e32 v34, 1, v53
	v_and_b32_e32 v38, 3, v53
	v_and_or_b32 v41, v34, 12, v38
	v_lshlrev_b32_e32 v34, 7, v53
	v_and_b32_e32 v34, 0x4000, v34
	v_and_b32_e32 v40, 48, v39
	v_lshl_add_u64 v[38:39], s[14:15], 0, v[34:35]
	v_lshlrev_b32_e32 v34, 6, v41
	v_lshlrev_b32_e32 v41, 1, v53
	v_add_u32_e32 v56, 64, v53
	v_and_b32_e32 v71, 32, v41
	v_or_b32_e32 v70, v34, v40
	v_bitop3_b32 v60, v34, v71, v40 bitop3:0x36
	v_and_b32_e32 v34, 0x60, v56
	v_lshlrev_b32_e32 v40, 2, v56
	v_and_or_b32 v42, v40, 16, v34
	v_lshlrev_b32_e32 v34, 7, v56
	v_and_b32_e32 v34, 0x4000, v34
	v_lshl_add_u64 v[40:41], s[14:15], 0, v[34:35]
	v_lshrrev_b32_e32 v34, 3, v42
	v_or_b32_e32 v34, v34, v54
	v_lshlrev_b32_e32 v34, 10, v34
	v_add_u32_e32 v57, 0x80, v53
	v_bitop3_b32 v34, v34, v70, v71 bitop3:0xf6
	v_and_b32_e32 v59, 0x60, v53
	v_lshl_add_u64 v[40:41], v[40:41], 0, v[34:35]
	v_lshlrev_b32_e32 v34, 2, v57
	v_and_or_b32 v44, v34, 16, v59
	v_lshlrev_b32_e32 v34, 7, v57
	v_and_b32_e32 v34, 0x4000, v34
	v_lshl_add_u64 v[42:43], s[14:15], 0, v[34:35]
	v_lshrrev_b32_e32 v34, 3, v44
	v_or_b32_e32 v34, v34, v54
	v_lshlrev_b32_e32 v34, 10, v34
	v_add_u32_e32 v58, 0xc0, v53
	v_bitop3_b32 v34, v34, v70, v71 bitop3:0xf6
	v_lshl_add_u64 v[42:43], v[42:43], 0, v[34:35]
	v_and_b32_e32 v34, 0x60, v58
	v_lshlrev_b32_e32 v44, 2, v58
	v_and_or_b32 v72, v44, 16, v34
	v_lshlrev_b32_e32 v34, 7, v58
	v_and_b32_e32 v34, 0x4000, v34
	v_lshl_add_u64 v[44:45], s[14:15], 0, v[34:35]
	v_lshrrev_b32_e32 v34, 3, v72
	v_or_b32_e32 v34, v34, v54
	s_movk_i32 s36, 0x404
	v_lshlrev_b32_e32 v34, 10, v34
	v_mul_lo_u32 v61, v1, s36
	v_mul_lo_u32 v62, v46, s36
	v_mul_lo_u32 v63, v47, s36
	v_mul_lo_u32 v64, v48, s36
	v_mul_lo_u32 v65, v49, s36
	v_mul_lo_u32 v66, v50, s36
	v_mul_lo_u32 v67, v51, s36
	v_mul_lo_u32 v69, v52, s36
	v_bitop3_b32 v34, v34, v70, v71 bitop3:0xf6
	v_lshl_add_u64 v[44:45], v[44:45], 0, v[34:35]
	v_add_u32_e32 v61, v68, v61
	v_add_u32_e32 v62, v68, v62
	v_add_u32_e32 v63, v68, v63
	v_add_u32_e32 v64, v68, v64
	v_add_u32_e32 v65, v68, v65
	v_add_u32_e32 v66, v68, v66
	v_add_u32_e32 v67, v68, v67
	v_add_u32_e32 v68, v68, v69
	s_waitcnt vmcnt(0)
	s_branch .LBB0_13

; __device__ __forceinline__ void convert_t(const float* __restrict__ W, int K, int N, bf16_t* __restrict__ Wt, int swiglu, int& cursor, float* tile, int perm) {
;     ...
;     for (; id < last; id += G) {
;         const int tl = (id - first) % nt; const int k0 = (tl / ntn) * 64, n0 = (tl % ntn) * 256;
; #pragma unroll
;         for (int i = 0; i < 8; ++i) { const int idx = tid + 512 * i; const int row = idx >> 6, c4 = idx & 63; float* d = tile + row * 257 + 4 * c4; d[0] = v[i].x; d[1] = v[i].y; d[2] = v[i].z; d[3] = v[i].w; }
;         __syncthreads();
;         if (id + G < last) { const int tl2 = (id + G - first) % nt; const int k2 = (tl2 / ntn) * 64, n2 = (tl2 % ntn) * 256;
; #pragma unroll
;             for (int i = 0; i < 8; ++i) { const int idx = tid + 512 * i; const int row = idx >> 6, c4 = idx & 63; v[i] = *(const float4*)(W + (size_t)(k2 + row) * N + n2 + 4 * c4); } }
.LBB0_13:
	s_add_i32 s46, s38, s39
	s_add_i32 s14, s46, 0x560
	s_cmpk_gt_i32 s14, 0x80f
	s_cselect_b64 s[14:15], -1, 0
	s_and_b64 vcc, exec, s[14:15]
	s_waitcnt vmcnt(11)
	ds_write2_b32 v61, v2, v3 offset1:1
	ds_write2_b32 v61, v4, v5 offset0:2 offset1:3
	s_waitcnt vmcnt(10)
	ds_write2_b32 v62, v6, v7 offset1:1
	ds_write2_b32 v62, v8, v9 offset0:2 offset1:3
	s_waitcnt vmcnt(9)
	ds_write2_b32 v63, v10, v11 offset1:1
	ds_write2_b32 v63, v12, v13 offset0:2 offset1:3
	s_waitcnt vmcnt(8)
	ds_write2_b32 v64, v14, v15 offset1:1
	ds_write2_b32 v64, v16, v17 offset0:2 offset1:3
	s_waitcnt vmcnt(7)
	ds_write2_b32 v65, v18, v19 offset1:1
	ds_write2_b32 v65, v20, v21 offset0:2 offset1:3
	s_waitcnt vmcnt(6)
	ds_write2_b32 v66, v22, v23 offset1:1
	ds_write2_b32 v66, v24, v25 offset0:2 offset1:3
	s_waitcnt vmcnt(5)
	ds_write2_b32 v67, v26, v27 offset1:1
	ds_write2_b32 v67, v28, v29 offset0:2 offset1:3
	s_waitcnt vmcnt(4)
	ds_write2_b32 v68, v30, v31 offset1:1
	ds_write2_b32 v68, v32, v33 offset0:2 offset1:3
	s_waitcnt lgkmcnt(0)
	s_barrier
	s_cbranch_vccnz .LBB0_12
	s_mul_hi_i32 s36, s46, 0x2fa0be83
	s_lshr_b32 s37, s36, 31
	s_ashr_i32 s36, s36, 7
	s_add_i32 s36, s36, s37
	s_mulk_i32 s36, 0x2b0
	s_sub_i32 s36, s46, s36
	s_sext_i32_i16 s37, s36
	s_bfe_u32 s37, s37, 0x3001c
	s_add_i32 s37, s36, s37
	s_sext_i32_i16 s47, s37
	s_and_b32 s37, s37, 0xfff8
	s_lshl_b32 s47, s47, 3
	s_sub_i32 s36, s36, s37
	s_andn2_b32 s47, s47, 63
	s_sext_i32_i16 s36, s36
	s_lshl_b32 s36, s36, 8
	v_add_u32_e32 v2, s47, v1
	s_ashr_i32 s37, s36, 31
	v_ashrrev_i32_e32 v3, 31, v2
	v_lshl_add_u64 v[26:27], s[36:37], 2, v[36:37]
	v_lshlrev_b64 v[2:3], 13, v[2:3]
	v_lshl_add_u64 v[10:11], v[26:27], 0, v[2:3]
	v_add_u32_e32 v2, s47, v46
	v_ashrrev_i32_e32 v3, 31, v2
	v_lshlrev_b64 v[2:3], 13, v[2:3]
	v_lshl_add_u64 v[12:13], v[26:27], 0, v[2:3]
	global_load_dwordx4 v[2:5], v[10:11], off
	global_load_dwordx4 v[6:9], v[12:13], off
	v_add_u32_e32 v10, s47, v47
	v_ashrrev_i32_e32 v11, 31, v10
	v_lshlrev_b64 v[10:11], 13, v[10:11]
	v_lshl_add_u64 v[18:19], v[26:27], 0, v[10:11]
	v_add_u32_e32 v10, s47, v48
	v_ashrrev_i32_e32 v11, 31, v10
	v_lshlrev_b64 v[10:11], 13, v[10:11]
	v_lshl_add_u64 v[20:21], v[26:27], 0, v[10:11]
	global_load_dwordx4 v[10:13], v[18:19], off
	global_load_dwordx4 v[14:17], v[20:21], off
	v_add_u32_e32 v18, s47, v49
	v_ashrrev_i32_e32 v19, 31, v18
	v_lshlrev_b64 v[18:19], 13, v[18:19]
	v_lshl_add_u64 v[28:29], v[26:27], 0, v[18:19]
	v_add_u32_e32 v18, s47, v50
	v_ashrrev_i32_e32 v19, 31, v18
	v_lshlrev_b64 v[18:19], 13, v[18:19]
	v_lshl_add_u64 v[30:31], v[26:27], 0, v[18:19]
	global_load_dwordx4 v[18:21], v[28:29], off
	global_load_dwordx4 v[22:25], v[30:31], off
	v_add_u32_e32 v28, s47, v51
	v_ashrrev_i32_e32 v29, 31, v28
	v_lshlrev_b64 v[28:29], 13, v[28:29]
	v_lshl_add_u64 v[70:71], v[26:27], 0, v[28:29]
	v_add_u32_e32 v28, s47, v52
	v_ashrrev_i32_e32 v29, 31, v28
	v_lshlrev_b64 v[28:29], 13, v[28:29]
	v_lshl_add_u64 v[72:73], v[26:27], 0, v[28:29]
	global_load_dwordx4 v[26:29], v[70:71], off
	global_load_dwordx4 v[30:33], v[72:73], off
	s_branch .LBB0_12
; __device__ __forceinline__ unsigned cvt_pk_bf16(float lo, float hi) { unsigned r; asm volatile("v_cvt_pk_bf16_f32 %0, %1, %2" : "=v"(r) : "v"(lo), "v"(hi)); return r; }
; __device__ __forceinline__ void convert_t(const float* __restrict__ W, int K, int N, bf16_t* __restrict__ Wt, int swiglu, int& cursor, float* tile, int perm) {
;     ...
;     const int tid = tix_, G = gdim_; const int ntn = N / 256, nt = (K / 64) * ntn;
;     const int first = cursor; cursor += nt;
;     int id = first + (((int)bid_ - (first % G)) + G) % G;
;     const int last = first + nt * CONV_REP;
;     float4 v[8];
;     if (id < last) { const int tl = (id - first) % nt; const int k0 = (tl / ntn) * 64, n0 = (tl % ntn) * 256;
; #pragma unroll
;         for (int i = 0; i < 8; ++i) { const int idx = tid + 512 * i; const int row = idx >> 6, c4 = idx & 63; v[i] = *(const float4*)(W + (size_t)(k0 + row) * N + n0 + 4 * c4); } }
;     ...
;         for (int p = 0; p < 4; ++p) { const int nl = (tid >> 3) + 64 * p, kq = tid & 7; const float* s = tile + (8 * kq) * 257 + nl;
;             u32x4 w; w.x = cvt_pk_bf16(s[0], s[257]); w.y = cvt_pk_bf16(s[2 * 257], s[3 * 257]); w.z = cvt_pk_bf16(s[4 * 257], s[5 * 257]); w.w = cvt_pk_bf16(s[6 * 257], s[7 * 257]);
;             int n = n0 + nl; if (swiglu) { const int half = n >= DFF ? 1 : 0; const int c = n - half * DFF; n = (c >> 7) * 256 + half * 128 + (c & 127); }
;             { const int pn = n >> 8, half = (n >> 7) & 1, r = n & 127, c5 = r & 31;
;               const int R = perm ? ((r & ~31) + 16 * ((c5 >> 2) & 1) + 4 * (c5 >> 3) + (c5 & 3)) : r;
;               *(u32x4*)((unsigned char*)Wt + ((size_t)pn * (K >> 6) + (k0 >> 6)) * 32768 + half * 16384 + pg8::lds_byte(R, 8 * kq)) = w; } }
.LBB0_15:
	s_mov_b32 s14, s2
	s_mov_b32 s38, s40
	s_abs_i32 s15, s38
	v_cvt_f32_u32_e32 v1, s15
	s_sub_i32 s36, 0, s15
	v_mov_b32_e32 v38, v228
	v_rcp_iflag_f32_e32 v1, v1
	s_nop 0
	v_mul_f32_e32 v1, 0x4f7ffffe, v1
	v_cvt_u32_f32_e32 v1, v1
	s_nop 0
	v_readfirstlane_b32 s37, v1
	s_mul_i32 s36, s36, s37
	s_mul_hi_u32 s36, s37, s36
	s_add_i32 s37, s37, s36
	s_mul_hi_u32 s36, s37, 0x810
	s_mul_i32 s36, s36, s15
	s_sub_i32 s36, 0x810, s36
	s_sub_i32 s39, s36, s15
	s_cmp_ge_u32 s36, s15
	s_cselect_b32 s36, s39, s36
	s_sub_i32 s39, s36, s15
	s_cmp_ge_u32 s36, s15
	s_cselect_b32 s36, s39, s36
	s_add_i32 s14, s38, s14
	s_sub_i32 s14, s14, s36
	s_ashr_i32 s36, s14, 31
	s_abs_i32 s14, s14
	s_mul_hi_u32 s37, s14, s37
	s_mul_i32 s37, s37, s15
	s_sub_i32 s14, s14, s37
	s_sub_i32 s37, s14, s15
	s_cmp_ge_u32 s14, s15
	s_cselect_b32 s14, s37, s14
	s_sub_i32 s37, s14, s15
	s_cmp_ge_u32 s14, s15
	s_cselect_b32 s14, s37, s14
	s_xor_b32 s14, s14, s36
	s_sub_i32 s36, s14, s36
	s_cmpk_gt_i32 s36, 0x53f
	s_cbranch_scc1 .LBB0_20
	s_add_u32 s14, s26, 0x4080000
	s_mul_hi_i32 s37, s36, 0x30c30c31
	s_addc_u32 s15, s27, 0
	s_lshr_b32 s39, s37, 31
	s_ashr_i32 s37, s37, 8
	s_add_i32 s37, s37, s39
	s_mulk_i32 s37, 0x540
	s_sub_i32 s37, s36, s37
	s_sext_i32_i16 s39, s37
	s_mulk_i32 s39, 0xc30d
	s_lshr_b32 s39, s39, 16
	s_add_i32 s39, s39, s37
	s_sext_i32_i16 s46, s39
	s_ashr_i32 s46, s46, 5
	s_bfe_u32 s39, s39, 0x1000f
	s_add_i32 s39, s46, s39
	s_sext_i32_i16 s46, s39
	s_mul_i32 s39, s39, 42
	s_sub_i32 s37, s37, s39
	s_sext_i32_i16 s37, s37
	s_lshl_b32 s48, s46, 6
	s_lshl_b32 s46, s37, 8
	s_ashr_i32 s47, s46, 31
	s_lshl_b64 s[46:47], s[46:47], 2
	s_add_u32 s46, s30, s46
	v_lshlrev_b32_e32 v39, 4, v38
	s_addc_u32 s47, s31, s47
	v_and_b32_e32 v34, 0x3f0, v39
	v_mov_b32_e32 v35, 0
	v_ashrrev_i32_e32 v1, 6, v38
	s_waitcnt vmcnt(5)
	v_lshl_add_u64 v[26:27], s[46:47], 0, v[34:35]
	v_add_u32_e32 v2, s48, v1
	s_mov_b32 s39, 0xa800
	v_mad_i64_i32 v[10:11], s[46:47], v2, s39, v[26:27]
	v_add_u32_e32 v2, 0x200, v38
	v_ashrrev_i32_e32 v52, 6, v2
	v_add_u32_e32 v2, s48, v52
	v_mad_i64_i32 v[12:13], s[46:47], v2, s39, v[26:27]
	global_load_dwordx4 v[2:5], v[10:11], off
	global_load_dwordx4 v[6:9], v[12:13], off
	v_add_u32_e32 v10, 0x400, v38
	v_ashrrev_i32_e32 v53, 6, v10
	v_add_u32_e32 v10, s48, v53
	v_mad_i64_i32 v[18:19], s[46:47], v10, s39, v[26:27]
	v_add_u32_e32 v10, 0x600, v38
	v_ashrrev_i32_e32 v54, 6, v10
	v_add_u32_e32 v10, s48, v54
	v_mad_i64_i32 v[20:21], s[46:47], v10, s39, v[26:27]
	global_load_dwordx4 v[10:13], v[18:19], off
	global_load_dwordx4 v[14:17], v[20:21], off
	v_add_u32_e32 v18, 0x800, v38
	v_ashrrev_i32_e32 v55, 6, v18
	v_add_u32_e32 v18, s48, v55
	v_mad_i64_i32 v[28:29], s[46:47], v18, s39, v[26:27]
	v_add_u32_e32 v18, 0xa00, v38
	v_ashrrev_i32_e32 v56, 6, v18
	v_add_u32_e32 v18, s48, v56
	s_waitcnt vmcnt(8)
	v_mad_i64_i32 v[30:31], s[46:47], v18, s39, v[26:27]
	global_load_dwordx4 v[18:21], v[28:29], off
	global_load_dwordx4 v[22:25], v[30:31], off
	v_add_u32_e32 v28, 0xc00, v38
	v_ashrrev_i32_e32 v57, 6, v28
	v_add_u32_e32 v28, s48, v57
	v_mad_i64_i32 v[36:37], s[46:47], v28, s39, v[26:27]
	v_add_u32_e32 v28, 0xe00, v38
	v_ashrrev_i32_e32 v58, 6, v28
	v_add_u32_e32 v28, s48, v58
	v_mad_i64_i32 v[40:41], s[46:47], v28, s39, v[26:27]
	global_load_dwordx4 v[26:29], v[36:37], off
	global_load_dwordx4 v[30:33], v[40:41], off
	v_add_u32_e32 v74, 0, v34
	v_lshl_add_u64 v[36:37], s[30:31], 0, v[34:35]
	v_lshlrev_b32_e32 v34, 3, v38
	v_ashrrev_i32_e32 v59, 3, v38
	v_and_b32_e32 v38, 56, v34
	v_mul_u32_u24_e32 v38, 0x404, v38
	v_bfe_u32 v60, v34, 5, 1
	v_and_b32_e32 v34, 48, v39
	v_lshlrev_b32_e32 v39, 2, v59
	v_add3_u32 v61, 0, v38, v39
	v_lshrrev_b32_e32 v38, 1, v59
	v_and_b32_e32 v39, 3, v59
	v_and_or_b32 v40, v38, 12, v39
	v_lshlrev_b32_e32 v41, 1, v59
	v_add_u32_e32 v62, 64, v59
	v_lshlrev_b32_e32 v40, 6, v40
	v_and_b32_e32 v51, 32, v41
	v_or_b32_e32 v50, v40, v34
	v_bitop3_b32 v66, v40, v51, v34 bitop3:0x36
	v_and_b32_e32 v34, 0x60, v62
	v_lshlrev_b32_e32 v40, 2, v62
	v_and_or_b32 v34, v40, 16, v34
	v_lshrrev_b32_e32 v34, 3, v34
	v_or_b32_e32 v34, v34, v60
	v_add_u32_e32 v63, 0x80, v59
	v_lshlrev_b32_e32 v34, 10, v34
	v_and_b32_e32 v65, 0x60, v59
	v_bitop3_b32 v42, v34, v50, v51 bitop3:0xf6
	v_lshlrev_b32_e32 v34, 2, v63
	v_and_or_b32 v34, v34, 16, v65
	v_lshrrev_b32_e32 v34, 3, v34
	v_or_b32_e32 v34, v34, v60
	v_add_u32_e32 v64, 0xc0, v59
	v_lshlrev_b32_e32 v34, 10, v34
	v_bitop3_b32 v46, v34, v50, v51 bitop3:0xf6
	v_and_b32_e32 v34, 0x60, v64
	v_lshlrev_b32_e32 v48, 2, v64
	v_and_or_b32 v34, v48, 16, v34
	v_lshrrev_b32_e32 v34, 3, v34
	s_movk_i32 s30, 0x404
	v_or_b32_e32 v34, v34, v60
	v_mul_lo_u32 v67, v1, s30
	v_mul_lo_u32 v68, v52, s30
	v_mul_lo_u32 v69, v53, s30
	v_mul_lo_u32 v70, v54, s30
	v_mul_lo_u32 v71, v55, s30
	v_mul_lo_u32 v72, v56, s30
	v_mul_lo_u32 v73, v57, s30
	v_mul_lo_u32 v75, v58, s30
	v_lshlrev_b32_e32 v38, 7, v59
	v_lshlrev_b32_e32 v40, 7, v62
	v_lshlrev_b32_e32 v44, 7, v63
	v_lshlrev_b32_e32 v48, 7, v64
	v_lshlrev_b32_e32 v34, 10, v34
	v_and_b32_e32 v38, 0x4000, v38
	v_mov_b32_e32 v39, v35
	v_and_b32_e32 v40, 0x4000, v40
	v_mov_b32_e32 v41, v35
	v_mov_b32_e32 v43, v35
	v_and_b32_e32 v44, 0x4000, v44
	v_mov_b32_e32 v45, v35
	v_mov_b32_e32 v47, v35
	v_and_b32_e32 v48, 0x4000, v48
	v_mov_b32_e32 v49, v35
	v_bitop3_b32 v50, v34, v50, v51 bitop3:0xf6
	v_mov_b32_e32 v51, v35
	v_add_u32_e32 v67, v74, v67
	v_add_u32_e32 v68, v74, v68
	v_add_u32_e32 v69, v74, v69
	v_add_u32_e32 v70, v74, v70
	v_add_u32_e32 v71, v74, v71
	v_add_u32_e32 v72, v74, v72
	v_add_u32_e32 v73, v74, v73
	v_add_u32_e32 v74, v74, v75
	s_waitcnt vmcnt(0)
	s_branch .LBB0_18

; __device__ __forceinline__ void convert_t(const float* __restrict__ W, int K, int N, bf16_t* __restrict__ Wt, int swiglu, int& cursor, float* tile, int perm) {
;     ...
;     for (; id < last; id += G) {
;         const int tl = (id - first) % nt; const int k0 = (tl / ntn) * 64, n0 = (tl % ntn) * 256;
; #pragma unroll
;         for (int i = 0; i < 8; ++i) { const int idx = tid + 512 * i; const int row = idx >> 6, c4 = idx & 63; float* d = tile + row * 257 + 4 * c4; d[0] = v[i].x; d[1] = v[i].y; d[2] = v[i].z; d[3] = v[i].w; }
;         __syncthreads();
;         if (id + G < last) { const int tl2 = (id + G - first) % nt; const int k2 = (tl2 / ntn) * 64, n2 = (tl2 % ntn) * 256;
; #pragma unroll
;             for (int i = 0; i < 8; ++i) { const int idx = tid + 512 * i; const int row = idx >> 6, c4 = idx & 63; v[i] = *(const float4*)(W + (size_t)(k2 + row) * N + n2 + 4 * c4); } }
.LBB0_18:
	s_add_i32 s46, s38, s36
	s_add_i32 s30, s46, 0x810
	s_cmpk_gt_i32 s30, 0xd4f
	s_cselect_b64 s[30:31], -1, 0
	s_and_b64 vcc, exec, s[30:31]
	s_waitcnt vmcnt(11)
	ds_write2_b32 v67, v2, v3 offset1:1
	ds_write2_b32 v67, v4, v5 offset0:2 offset1:3
	s_waitcnt vmcnt(10)
	ds_write2_b32 v68, v6, v7 offset1:1
	ds_write2_b32 v68, v8, v9 offset0:2 offset1:3
	s_waitcnt vmcnt(9)
	ds_write2_b32 v69, v10, v11 offset1:1
	ds_write2_b32 v69, v12, v13 offset0:2 offset1:3
	s_waitcnt vmcnt(8)
	ds_write2_b32 v70, v14, v15 offset1:1
	ds_write2_b32 v70, v16, v17 offset0:2 offset1:3
	s_waitcnt vmcnt(7)
	ds_write2_b32 v71, v18, v19 offset1:1
	ds_write2_b32 v71, v20, v21 offset0:2 offset1:3
	s_waitcnt vmcnt(6)
	ds_write2_b32 v72, v22, v23 offset1:1
	ds_write2_b32 v72, v24, v25 offset0:2 offset1:3
	s_waitcnt vmcnt(5)
	ds_write2_b32 v73, v26, v27 offset1:1
	ds_write2_b32 v73, v28, v29 offset0:2 offset1:3
	s_waitcnt vmcnt(4)
	ds_write2_b32 v74, v30, v31 offset1:1
	ds_write2_b32 v74, v32, v33 offset0:2 offset1:3
	s_waitcnt lgkmcnt(0)
	s_barrier
	s_cbranch_vccnz .LBB0_17
	s_mul_hi_i32 s37, s46, 0x30c30c31
	s_lshr_b32 s47, s37, 31
	s_ashr_i32 s37, s37, 8
	s_add_i32 s37, s37, s47
	s_mulk_i32 s37, 0x540
	s_sub_i32 s37, s46, s37
	s_sext_i32_i16 s47, s37
	s_mulk_i32 s47, 0xc30d
	s_lshr_b32 s47, s47, 16
	s_add_i32 s47, s47, s37
	s_sext_i32_i16 s48, s47
	s_ashr_i32 s48, s48, 5
	s_bfe_u32 s47, s47, 0x1000f
	s_add_i32 s47, s48, s47
	s_sext_i32_i16 s48, s47
	s_mul_i32 s47, s47, 42
	s_sub_i32 s37, s37, s47
	s_sext_i32_i16 s37, s37
	s_lshl_b32 s50, s48, 6
	s_lshl_b32 s48, s37, 8
	s_ashr_i32 s49, s48, 31
	v_lshl_add_u64 v[26:27], s[48:49], 2, v[36:37]
	v_add_u32_e32 v2, s50, v1
	v_mad_i64_i32 v[10:11], s[48:49], v2, s39, v[26:27]
	v_add_u32_e32 v2, s50, v52
	v_mad_i64_i32 v[12:13], s[48:49], v2, s39, v[26:27]
	global_load_dwordx4 v[2:5], v[10:11], off
	global_load_dwordx4 v[6:9], v[12:13], off
	v_add_u32_e32 v10, s50, v53
	v_mad_i64_i32 v[18:19], s[48:49], v10, s39, v[26:27]
	v_add_u32_e32 v10, s50, v54
	v_mad_i64_i32 v[20:21], s[48:49], v10, s39, v[26:27]
	global_load_dwordx4 v[10:13], v[18:19], off
	global_load_dwordx4 v[14:17], v[20:21], off
	v_add_u32_e32 v18, s50, v55
	v_mad_i64_i32 v[28:29], s[48:49], v18, s39, v[26:27]
	v_add_u32_e32 v18, s50, v56
	v_mad_i64_i32 v[30:31], s[48:49], v18, s39, v[26:27]
	global_load_dwordx4 v[18:21], v[28:29], off
	global_load_dwordx4 v[22:25], v[30:31], off
	v_add_u32_e32 v28, s50, v57
	v_mad_i64_i32 v[76:77], s[48:49], v28, s39, v[26:27]
	v_add_u32_e32 v28, s50, v58
	v_mad_i64_i32 v[78:79], s[48:49], v28, s39, v[26:27]
	global_load_dwordx4 v[26:29], v[76:77], off
	global_load_dwordx4 v[30:33], v[78:79], off
	s_branch .LBB0_17
; __device__ __forceinline__ unsigned cvt_pk_bf16(float lo, float hi) { unsigned r; asm volatile("v_cvt_pk_bf16_f32 %0, %1, %2" : "=v"(r) : "v"(lo), "v"(hi)); return r; }
; __device__ __forceinline__ void convert_t(const float* __restrict__ W, int K, int N, bf16_t* __restrict__ Wt, int swiglu, int& cursor, float* tile, int perm) {
;     ...
;     const int tid = tix_, G = gdim_; const int ntn = N / 256, nt = (K / 64) * ntn;
;     const int first = cursor; cursor += nt;
;     int id = first + (((int)bid_ - (first % G)) + G) % G;
;     const int last = first + nt * CONV_REP;
;     float4 v[8];
;     if (id < last) { const int tl = (id - first) % nt; const int k0 = (tl / ntn) * 64, n0 = (tl % ntn) * 256;
; #pragma unroll
;         for (int i = 0; i < 8; ++i) { const int idx = tid + 512 * i; const int row = idx >> 6, c4 = idx & 63; v[i] = *(const float4*)(W + (size_t)(k0 + row) * N + n0 + 4 * c4); } }
;     ...
;         for (int p = 0; p < 4; ++p) { const int nl = (tid >> 3) + 64 * p, kq = tid & 7; const float* s = tile + (8 * kq) * 257 + nl;
;             u32x4 w; w.x = cvt_pk_bf16(s[0], s[257]); w.y = cvt_pk_bf16(s[2 * 257], s[3 * 257]); w.z = cvt_pk_bf16(s[4 * 257], s[5 * 257]); w.w = cvt_pk_bf16(s[6 * 257], s[7 * 257]);
;             int n = n0 + nl; if (swiglu) { const int half = n >= DFF ? 1 : 0; const int c = n - half * DFF; n = (c >> 7) * 256 + half * 128 + (c & 127); }
;             { const int pn = n >> 8, half = (n >> 7) & 1, r = n & 127, c5 = r & 31;
;               const int R = perm ? ((r & ~31) + 16 * ((c5 >> 2) & 1) + 4 * (c5 >> 3) + (c5 & 3)) : r;
;               *(u32x4*)((unsigned char*)Wt + ((size_t)pn * (K >> 6) + (k0 >> 6)) * 32768 + half * 16384 + pg8::lds_byte(R, 8 * kq)) = w; } }
.LBB0_20:
	s_mov_b32 s14, s2
	s_mov_b32 s36, s40
	s_abs_i32 s15, s36
	v_cvt_f32_u32_e32 v1, s15
	s_sub_i32 s30, 0, s15
	v_mov_b32_e32 v38, v228
	v_rcp_iflag_f32_e32 v1, v1
	s_nop 0
	v_mul_f32_e32 v1, 0x4f7ffffe, v1
	v_cvt_u32_f32_e32 v1, v1
	s_nop 0
	v_readfirstlane_b32 s31, v1
	s_mul_i32 s30, s30, s31
	s_mul_hi_u32 s30, s31, s30
	s_add_i32 s31, s31, s30
	s_mul_hi_u32 s30, s31, 0xd50
	s_mul_i32 s30, s30, s15
	s_sub_i32 s30, 0xd50, s30
	s_sub_i32 s37, s30, s15
	s_cmp_ge_u32 s30, s15
	s_cselect_b32 s30, s37, s30
	s_sub_i32 s37, s30, s15
	s_cmp_ge_u32 s30, s15
	s_cselect_b32 s30, s37, s30
	s_add_i32 s14, s36, s14
	s_sub_i32 s14, s14, s30
	s_ashr_i32 s30, s14, 31
	s_abs_i32 s14, s14
	s_mul_hi_u32 s31, s14, s31
	s_mul_i32 s31, s31, s15
	s_sub_i32 s14, s14, s31
	s_sub_i32 s31, s14, s15
	s_cmp_ge_u32 s14, s15
	s_cselect_b32 s14, s31, s14
	s_sub_i32 s31, s14, s15
	s_cmp_ge_u32 s14, s15
	s_cselect_b32 s14, s31, s14
	s_xor_b32 s14, s14, s30
	s_sub_i32 s30, s14, s30
	s_cmpk_gt_i32 s30, 0xff
	s_cbranch_scc1 .LBB0_25
	s_add_u32 s14, s26, 0x6a80000
	s_addc_u32 s15, s27, 0
	s_ashr_i32 s31, s30, 31
	s_lshr_b32 s31, s31, 24
	s_add_i32 s31, s30, s31
	s_and_b32 s31, s31, 0xff00
	s_sub_i32 s31, s30, s31
	s_sext_i32_i16 s37, s31
	s_bfe_u32 s37, s37, 0x3001c
	s_add_i32 s37, s31, s37
	s_sext_i32_i16 s38, s37
	s_and_b32 s37, s37, 0xfff8
	s_sub_i32 s31, s31, s37
	s_lshl_b32 s38, s38, 3
	s_sext_i32_i16 s31, s31
	s_and_b32 s46, s38, 0xffffffc0
	s_lshl_b32 s38, s31, 8
	s_ashr_i32 s39, s38, 31
	s_lshl_b64 s[38:39], s[38:39], 2
	v_ashrrev_i32_e32 v1, 6, v38
	s_add_u32 s38, s18, s38
	v_lshlrev_b32_e32 v39, 4, v38
	s_waitcnt vmcnt(11)
	v_add_u32_e32 v2, s46, v1
	s_addc_u32 s39, s19, s39
	v_and_b32_e32 v34, 0x3f0, v39
	v_mov_b32_e32 v35, 0
	v_ashrrev_i32_e32 v3, 31, v2
	s_waitcnt vmcnt(5)
	v_lshl_add_u64 v[26:27], s[38:39], 0, v[34:35]
	v_lshlrev_b64 v[2:3], 13, v[2:3]
	v_lshl_add_u64 v[10:11], v[26:27], 0, v[2:3]
	v_add_u32_e32 v2, 0x200, v38
	v_ashrrev_i32_e32 v52, 6, v2
	v_add_u32_e32 v2, s46, v52
	v_ashrrev_i32_e32 v3, 31, v2
	v_lshlrev_b64 v[2:3], 13, v[2:3]
	v_lshl_add_u64 v[12:13], v[26:27], 0, v[2:3]
	global_load_dwordx4 v[2:5], v[10:11], off
	global_load_dwordx4 v[6:9], v[12:13], off
	v_add_u32_e32 v10, 0x400, v38
	v_ashrrev_i32_e32 v53, 6, v10
	v_add_u32_e32 v10, s46, v53
	v_ashrrev_i32_e32 v11, 31, v10
	v_lshlrev_b64 v[10:11], 13, v[10:11]
	v_lshl_add_u64 v[18:19], v[26:27], 0, v[10:11]
	v_add_u32_e32 v10, 0x600, v38
	v_ashrrev_i32_e32 v54, 6, v10
	v_add_u32_e32 v10, s46, v54
	v_ashrrev_i32_e32 v11, 31, v10
	v_lshlrev_b64 v[10:11], 13, v[10:11]
	v_lshl_add_u64 v[20:21], v[26:27], 0, v[10:11]
	global_load_dwordx4 v[10:13], v[18:19], off
	global_load_dwordx4 v[14:17], v[20:21], off
	v_add_u32_e32 v18, 0x800, v38
	v_ashrrev_i32_e32 v55, 6, v18
	v_add_u32_e32 v18, s46, v55
	v_ashrrev_i32_e32 v19, 31, v18
	v_lshlrev_b64 v[18:19], 13, v[18:19]
	v_lshl_add_u64 v[28:29], v[26:27], 0, v[18:19]
	v_add_u32_e32 v18, 0xa00, v38
	v_ashrrev_i32_e32 v56, 6, v18
	v_add_u32_e32 v18, s46, v56
	v_ashrrev_i32_e32 v19, 31, v18
	v_lshlrev_b64 v[18:19], 13, v[18:19]
	s_waitcnt vmcnt(8)
	v_lshl_add_u64 v[30:31], v[26:27], 0, v[18:19]
	global_load_dwordx4 v[18:21], v[28:29], off
	global_load_dwordx4 v[22:25], v[30:31], off
	v_add_u32_e32 v28, 0xc00, v38
	v_ashrrev_i32_e32 v57, 6, v28
	v_add_u32_e32 v28, s46, v57
	v_ashrrev_i32_e32 v29, 31, v28
	v_lshlrev_b64 v[28:29], 13, v[28:29]
	v_lshl_add_u64 v[36:37], v[26:27], 0, v[28:29]
	v_add_u32_e32 v28, 0xe00, v38
	v_ashrrev_i32_e32 v58, 6, v28
	v_add_u32_e32 v28, s46, v58
	v_ashrrev_i32_e32 v29, 31, v28
	v_lshlrev_b64 v[28:29], 13, v[28:29]
	v_lshl_add_u64 v[40:41], v[26:27], 0, v[28:29]
	global_load_dwordx4 v[26:29], v[36:37], off
	global_load_dwordx4 v[30:33], v[40:41], off
	v_add_u32_e32 v74, 0, v34
	v_lshl_add_u64 v[36:37], s[18:19], 0, v[34:35]
	v_lshlrev_b32_e32 v34, 3, v38
	v_ashrrev_i32_e32 v59, 3, v38
	v_and_b32_e32 v38, 56, v34
	v_mul_u32_u24_e32 v38, 0x404, v38
	v_bfe_u32 v60, v34, 5, 1
	v_and_b32_e32 v34, 48, v39
	v_lshlrev_b32_e32 v39, 2, v59
	v_add3_u32 v61, 0, v38, v39
	v_lshrrev_b32_e32 v38, 1, v59
	v_and_b32_e32 v39, 3, v59
	v_and_or_b32 v40, v38, 12, v39
	v_lshlrev_b32_e32 v41, 1, v59
	v_add_u32_e32 v62, 64, v59
	v_lshlrev_b32_e32 v40, 6, v40
	v_and_b32_e32 v51, 32, v41
	v_or_b32_e32 v50, v40, v34
	v_bitop3_b32 v66, v40, v51, v34 bitop3:0x36
	v_and_b32_e32 v34, 0x60, v62
	v_lshlrev_b32_e32 v40, 2, v62
	v_and_or_b32 v34, v40, 16, v34
	v_lshrrev_b32_e32 v34, 3, v34
	v_or_b32_e32 v34, v34, v60
	v_add_u32_e32 v63, 0x80, v59
	v_lshlrev_b32_e32 v34, 10, v34
	v_and_b32_e32 v65, 0x60, v59
	v_bitop3_b32 v42, v34, v50, v51 bitop3:0xf6
	v_lshlrev_b32_e32 v34, 2, v63
	v_and_or_b32 v34, v34, 16, v65
	v_lshrrev_b32_e32 v34, 3, v34
	v_or_b32_e32 v34, v34, v60
	v_add_u32_e32 v64, 0xc0, v59
	v_lshlrev_b32_e32 v34, 10, v34
	v_bitop3_b32 v46, v34, v50, v51 bitop3:0xf6
	v_and_b32_e32 v34, 0x60, v64
	v_lshlrev_b32_e32 v48, 2, v64
	v_and_or_b32 v34, v48, 16, v34
	v_lshrrev_b32_e32 v34, 3, v34
	s_movk_i32 s18, 0x404
	v_or_b32_e32 v34, v34, v60
	v_mul_lo_u32 v67, v1, s18
	v_mul_lo_u32 v68, v52, s18
	v_mul_lo_u32 v69, v53, s18
	v_mul_lo_u32 v70, v54, s18
	v_mul_lo_u32 v71, v55, s18
	v_mul_lo_u32 v72, v56, s18
	v_mul_lo_u32 v73, v57, s18
	v_mul_lo_u32 v75, v58, s18
	v_lshlrev_b32_e32 v38, 7, v59
	v_lshlrev_b32_e32 v40, 7, v62
	v_lshlrev_b32_e32 v44, 7, v63
	v_lshlrev_b32_e32 v48, 7, v64
	v_lshlrev_b32_e32 v34, 10, v34
	v_and_b32_e32 v38, 0x4000, v38
	v_mov_b32_e32 v39, v35
	v_and_b32_e32 v40, 0x4000, v40
	v_mov_b32_e32 v41, v35
	v_mov_b32_e32 v43, v35
	v_and_b32_e32 v44, 0x4000, v44
	v_mov_b32_e32 v45, v35
	v_mov_b32_e32 v47, v35
	v_and_b32_e32 v48, 0x4000, v48
	v_mov_b32_e32 v49, v35
	v_bitop3_b32 v50, v34, v50, v51 bitop3:0xf6
	v_mov_b32_e32 v51, v35
	v_add_u32_e32 v67, v74, v67
	v_add_u32_e32 v68, v74, v68
	v_add_u32_e32 v69, v74, v69
	v_add_u32_e32 v70, v74, v70
	v_add_u32_e32 v71, v74, v71
	v_add_u32_e32 v72, v74, v72
	v_add_u32_e32 v73, v74, v73
	v_add_u32_e32 v74, v74, v75
	s_waitcnt vmcnt(0)
	s_branch .LBB0_23

; __device__ __forceinline__ void convert_t(const float* __restrict__ W, int K, int N, bf16_t* __restrict__ Wt, int swiglu, int& cursor, float* tile, int perm) {
;     ...
;     for (; id < last; id += G) {
;         const int tl = (id - first) % nt; const int k0 = (tl / ntn) * 64, n0 = (tl % ntn) * 256;
; #pragma unroll
;         for (int i = 0; i < 8; ++i) { const int idx = tid + 512 * i; const int row = idx >> 6, c4 = idx & 63; float* d = tile + row * 257 + 4 * c4; d[0] = v[i].x; d[1] = v[i].y; d[2] = v[i].z; d[3] = v[i].w; }
;         __syncthreads();
;         if (id + G < last) { const int tl2 = (id + G - first) % nt; const int k2 = (tl2 / ntn) * 64, n2 = (tl2 % ntn) * 256;
; #pragma unroll
;             for (int i = 0; i < 8; ++i) { const int idx = tid + 512 * i; const int row = idx >> 6, c4 = idx & 63; v[i] = *(const float4*)(W + (size_t)(k2 + row) * N + n2 + 4 * c4); } }
.LBB0_23:
	s_add_i32 s37, s36, s30
	s_add_i32 s18, s37, 0xd50
	s_cmpk_gt_i32 s18, 0xe4f
	s_cselect_b64 s[18:19], -1, 0
	s_and_b64 vcc, exec, s[18:19]
	s_waitcnt vmcnt(11)
	ds_write2_b32 v67, v2, v3 offset1:1
	ds_write2_b32 v67, v4, v5 offset0:2 offset1:3
	s_waitcnt vmcnt(10)
	ds_write2_b32 v68, v6, v7 offset1:1
	ds_write2_b32 v68, v8, v9 offset0:2 offset1:3
	s_waitcnt vmcnt(9)
	ds_write2_b32 v69, v10, v11 offset1:1
	ds_write2_b32 v69, v12, v13 offset0:2 offset1:3
	s_waitcnt vmcnt(8)
	ds_write2_b32 v70, v14, v15 offset1:1
	ds_write2_b32 v70, v16, v17 offset0:2 offset1:3
	s_waitcnt vmcnt(7)
	ds_write2_b32 v71, v18, v19 offset1:1
	ds_write2_b32 v71, v20, v21 offset0:2 offset1:3
	s_waitcnt vmcnt(6)
	ds_write2_b32 v72, v22, v23 offset1:1
	ds_write2_b32 v72, v24, v25 offset0:2 offset1:3
	s_waitcnt vmcnt(5)
	ds_write2_b32 v73, v26, v27 offset1:1
	ds_write2_b32 v73, v28, v29 offset0:2 offset1:3
	s_waitcnt vmcnt(4)
	ds_write2_b32 v74, v30, v31 offset1:1
	ds_write2_b32 v74, v32, v33 offset0:2 offset1:3
	s_waitcnt lgkmcnt(0)
	s_barrier
	s_cbranch_vccnz .LBB0_22
	s_ashr_i32 s31, s37, 31
	s_lshr_b32 s31, s31, 24
	s_add_i32 s31, s37, s31
	s_and_b32 s31, s31, 0xff00
	s_sub_i32 s31, s37, s31
	s_sext_i32_i16 s38, s31
	s_bfe_u32 s38, s38, 0x3001c
	s_add_i32 s38, s31, s38
	s_sext_i32_i16 s39, s38
	s_and_b32 s38, s38, 0xfff8
	s_lshl_b32 s39, s39, 3
	s_sub_i32 s31, s31, s38
	s_and_b32 s46, s39, 0xffffffc0
	s_sext_i32_i16 s31, s31
	s_lshl_b32 s38, s31, 8
	v_add_u32_e32 v2, s46, v1
	s_ashr_i32 s39, s38, 31
	v_ashrrev_i32_e32 v3, 31, v2
	v_lshl_add_u64 v[26:27], s[38:39], 2, v[36:37]
	v_lshlrev_b64 v[2:3], 13, v[2:3]
	v_lshl_add_u64 v[10:11], v[26:27], 0, v[2:3]
	v_add_u32_e32 v2, s46, v52
	v_ashrrev_i32_e32 v3, 31, v2
	v_lshlrev_b64 v[2:3], 13, v[2:3]
	v_lshl_add_u64 v[12:13], v[26:27], 0, v[2:3]
	global_load_dwordx4 v[2:5], v[10:11], off
	global_load_dwordx4 v[6:9], v[12:13], off
	v_add_u32_e32 v10, s46, v53
	v_ashrrev_i32_e32 v11, 31, v10
	v_lshlrev_b64 v[10:11], 13, v[10:11]
	v_lshl_add_u64 v[18:19], v[26:27], 0, v[10:11]
	v_add_u32_e32 v10, s46, v54
	v_ashrrev_i32_e32 v11, 31, v10
	v_lshlrev_b64 v[10:11], 13, v[10:11]
	v_lshl_add_u64 v[20:21], v[26:27], 0, v[10:11]
	global_load_dwordx4 v[10:13], v[18:19], off
	global_load_dwordx4 v[14:17], v[20:21], off
	v_add_u32_e32 v18, s46, v55
	v_ashrrev_i32_e32 v19, 31, v18
	v_lshlrev_b64 v[18:19], 13, v[18:19]
	v_lshl_add_u64 v[28:29], v[26:27], 0, v[18:19]
	v_add_u32_e32 v18, s46, v56
	v_ashrrev_i32_e32 v19, 31, v18
	v_lshlrev_b64 v[18:19], 13, v[18:19]
	v_lshl_add_u64 v[30:31], v[26:27], 0, v[18:19]
	global_load_dwordx4 v[18:21], v[28:29], off
	global_load_dwordx4 v[22:25], v[30:31], off
	v_add_u32_e32 v28, s46, v57
	v_ashrrev_i32_e32 v29, 31, v28
	v_lshlrev_b64 v[28:29], 13, v[28:29]
	v_lshl_add_u64 v[76:77], v[26:27], 0, v[28:29]
	v_add_u32_e32 v28, s46, v58
	v_ashrrev_i32_e32 v29, 31, v28
	v_lshlrev_b64 v[28:29], 13, v[28:29]
	v_lshl_add_u64 v[78:79], v[26:27], 0, v[28:29]
	global_load_dwordx4 v[26:29], v[76:77], off
	global_load_dwordx4 v[30:33], v[78:79], off
	s_branch .LBB0_22

; __device__ __forceinline__ unsigned cvt_pk_bf16(float lo, float hi) { unsigned r; asm volatile("v_cvt_pk_bf16_f32 %0, %1, %2" : "=v"(r) : "v"(lo), "v"(hi)); return r; }
; __device__ __forceinline__ void convert_t(const float* __restrict__ W, int K, int N, bf16_t* __restrict__ Wt, int swiglu, int& cursor, float* tile, int perm) {
;     ...
;     const int tid = tix_, G = gdim_; const int ntn = N / 256, nt = (K / 64) * ntn;
;     const int first = cursor; cursor += nt;
;     int id = first + (((int)bid_ - (first % G)) + G) % G;
;     const int last = first + nt * CONV_REP;
;     float4 v[8];
;     if (id < last) { const int tl = (id - first) % nt; const int k0 = (tl / ntn) * 64, n0 = (tl % ntn) * 256;
; #pragma unroll
;         for (int i = 0; i < 8; ++i) { const int idx = tid + 512 * i; const int row = idx >> 6, c4 = idx & 63; v[i] = *(const float4*)(W + (size_t)(k0 + row) * N + n0 + 4 * c4); } }
;     ...
;         for (int p = 0; p < 4; ++p) { const int nl = (tid >> 3) + 64 * p, kq = tid & 7; const float* s = tile + (8 * kq) * 257 + nl;
;             u32x4 w; w.x = cvt_pk_bf16(s[0], s[257]); w.y = cvt_pk_bf16(s[2 * 257], s[3 * 257]); w.z = cvt_pk_bf16(s[4 * 257], s[5 * 257]); w.w = cvt_pk_bf16(s[6 * 257], s[7 * 257]);
;             int n = n0 + nl; if (swiglu) { const int half = n >= DFF ? 1 : 0; const int c = n - half * DFF; n = (c >> 7) * 256 + half * 128 + (c & 127); }
;             { const int pn = n >> 8, half = (n >> 7) & 1, r = n & 127, c5 = r & 31;
;               const int R = perm ? ((r & ~31) + 16 * ((c5 >> 2) & 1) + 4 * (c5 >> 3) + (c5 & 3)) : r;
;               *(u32x4*)((unsigned char*)Wt + ((size_t)pn * (K >> 6) + (k0 >> 6)) * 32768 + half * 16384 + pg8::lds_byte(R, 8 * kq)) = w; } }
.LBB0_27:
	s_mov_b32 s18, s2
	s_mov_b32 s46, s40
	s_abs_i32 s19, s46
	v_cvt_f32_u32_e32 v1, s19
	s_sub_i32 s30, 0, s19
	s_add_i32 s47, s38, 0x80
	v_mov_b32_e32 v38, v228
	v_rcp_iflag_f32_e32 v1, v1
	s_nop 0
	v_mul_f32_e32 v1, 0x4f7ffffe, v1
	v_cvt_u32_f32_e32 v1, v1
	s_nop 0
	v_readfirstlane_b32 s31, v1
	s_mul_i32 s30, s30, s31
	s_mul_hi_u32 s30, s31, s30
	s_add_i32 s31, s31, s30
	s_mul_hi_u32 s30, s38, s31
	s_mul_i32 s30, s30, s19
	s_sub_i32 s30, s38, s30
	s_sub_i32 s48, s30, s19
	s_cmp_ge_u32 s30, s19
	s_cselect_b32 s30, s48, s30
	s_sub_i32 s48, s30, s19
	s_cmp_ge_u32 s30, s19
	s_cselect_b32 s30, s48, s30
	s_add_i32 s18, s46, s18
	s_sub_i32 s18, s18, s30
	s_ashr_i32 s49, s18, 31
	s_abs_i32 s18, s18
	s_mul_hi_u32 s30, s18, s31
	s_mul_i32 s30, s30, s19
	s_sub_i32 s18, s18, s30
	s_sub_i32 s30, s18, s19
	s_cmp_ge_u32 s18, s19
	s_cselect_b32 s18, s30, s18
	s_sub_i32 s30, s18, s19
	s_cmp_ge_u32 s18, s19
	s_cselect_b32 s18, s30, s18
	s_xor_b32 s50, s18, s49
	s_sub_i32 s48, s50, s49
	s_cmpk_gt_i32 s48, 0x7f
	s_cbranch_scc1 .LBB0_26
	s_lshl_b64 s[18:19], s[14:15], 22
	s_add_u32 s18, s36, s18
	s_addc_u32 s19, s37, s19
	s_lshl_b64 s[30:31], s[14:15], 23
	s_add_u32 s30, s20, s30
	s_addc_u32 s31, s21, s31
	s_ashr_i32 s51, s48, 31
	s_lshr_b32 s51, s51, 25
	s_add_i32 s51, s48, s51
	s_and_b32 s51, s51, 0xff80
	s_sub_i32 s51, s48, s51
	s_bfe_i32 s52, s51, 0x80000
	s_bfe_u32 s52, s52, 0x3000c
	s_add_i32 s52, s51, s52
	s_bfe_i32 s53, s52, 0x80000
	s_and_b32 s52, s52, 0xf8
	s_sub_i32 s51, s51, s52
	s_sext_i32_i16 s53, s53
	s_sext_i32_i8 s51, s51
	s_lshl_b32 s53, s53, 3
	s_lshl_b32 s52, s51, 8
	s_and_b32 s54, s53, 0xffffffc0
	s_ashr_i32 s53, s52, 31
	s_waitcnt vmcnt(11)
	v_add_u32_e32 v4, 0x200, v38
	s_waitcnt vmcnt(9)
	v_add_u32_e32 v10, 0x400, v38
	v_add_u32_e32 v12, 0x600, v38
	s_waitcnt vmcnt(7)
	v_add_u32_e32 v18, 0x800, v38
	v_add_u32_e32 v20, 0xa00, v38
	s_waitcnt vmcnt(5)
	v_add_u32_e32 v28, 0xc00, v38
	s_waitcnt vmcnt(4)
	v_add_u32_e32 v30, 0xe00, v38
	s_lshl_b64 s[52:53], s[52:53], 2
	v_ashrrev_i32_e32 v1, 6, v38
	v_ashrrev_i32_e32 v52, 6, v4
	v_ashrrev_i32_e32 v53, 6, v10
	v_ashrrev_i32_e32 v54, 6, v12
	v_ashrrev_i32_e32 v55, 6, v18
	v_ashrrev_i32_e32 v56, 6, v20
	v_ashrrev_i32_e32 v57, 6, v28
	v_ashrrev_i32_e32 v58, 6, v30
	s_add_u32 s52, s30, s52
	v_lshlrev_b32_e32 v39, 4, v38
	v_add_u32_e32 v2, s54, v1
	v_add_u32_e32 v4, s54, v52
	v_add_u32_e32 v10, s54, v53
	v_add_u32_e32 v12, s54, v54
	v_add_u32_e32 v18, s54, v55
	v_add_u32_e32 v20, s54, v56
	v_add_u32_e32 v28, s54, v57
	v_add_u32_e32 v30, s54, v58
	s_addc_u32 s53, s31, s53
	v_and_b32_e32 v34, 0x3f0, v39
	v_ashrrev_i32_e32 v3, 31, v2
	v_ashrrev_i32_e32 v5, 31, v4
	v_ashrrev_i32_e32 v11, 31, v10
	v_ashrrev_i32_e32 v13, 31, v12
	v_ashrrev_i32_e32 v19, 31, v18
	v_ashrrev_i32_e32 v21, 31, v20
	v_ashrrev_i32_e32 v29, 31, v28
	v_ashrrev_i32_e32 v31, 31, v30
	v_lshl_add_u64 v[26:27], s[52:53], 0, v[34:35]
	v_lshlrev_b64 v[2:3], 13, v[2:3]
	v_lshlrev_b64 v[4:5], 13, v[4:5]
	v_lshlrev_b64 v[10:11], 13, v[10:11]
	v_lshlrev_b64 v[12:13], 13, v[12:13]
	v_lshlrev_b64 v[18:19], 13, v[18:19]
	v_lshlrev_b64 v[20:21], 13, v[20:21]
	v_lshlrev_b64 v[28:29], 13, v[28:29]
	v_lshlrev_b64 v[30:31], 13, v[30:31]
	v_lshl_add_u64 v[2:3], v[26:27], 0, v[2:3]
	v_lshl_add_u64 v[6:7], v[26:27], 0, v[4:5]
	v_lshl_add_u64 v[10:11], v[26:27], 0, v[10:11]
	v_lshl_add_u64 v[14:15], v[26:27], 0, v[12:13]
	v_lshl_add_u64 v[18:19], v[26:27], 0, v[18:19]
	v_lshl_add_u64 v[22:23], v[26:27], 0, v[20:21]
	v_lshl_add_u64 v[28:29], v[26:27], 0, v[28:29]
	v_lshl_add_u64 v[30:31], v[26:27], 0, v[30:31]
	global_load_dwordx4 v[2:5], v[2:3], off
	s_nop 0
	global_load_dwordx4 v[6:9], v[6:7], off
	s_nop 0
	global_load_dwordx4 v[10:13], v[10:11], off
	s_nop 0
	global_load_dwordx4 v[14:17], v[14:15], off
	s_nop 0
	global_load_dwordx4 v[18:21], v[18:19], off
	s_nop 0
	global_load_dwordx4 v[22:25], v[22:23], off
	s_nop 0
	global_load_dwordx4 v[26:29], v[28:29], off
	s_nop 0
	global_load_dwordx4 v[30:33], v[30:31], off
	v_add_u32_e32 v74, 0, v34
	v_lshl_add_u64 v[36:37], s[30:31], 0, v[34:35]
	v_lshlrev_b32_e32 v34, 3, v38
	v_ashrrev_i32_e32 v59, 3, v38
	v_and_b32_e32 v38, 56, v34
	v_mul_u32_u24_e32 v38, 0x404, v38
	v_bfe_u32 v60, v34, 5, 1
	v_and_b32_e32 v34, 48, v39
	v_lshlrev_b32_e32 v39, 2, v59
	v_add3_u32 v61, 0, v38, v39
	v_lshrrev_b32_e32 v38, 1, v59
	v_and_b32_e32 v39, 3, v59
	v_and_or_b32 v40, v38, 12, v39
	v_lshlrev_b32_e32 v41, 1, v59
	v_add_u32_e32 v62, 64, v59
	v_lshlrev_b32_e32 v40, 6, v40
	v_and_b32_e32 v51, 32, v41
	v_or_b32_e32 v50, v40, v34
	v_bitop3_b32 v66, v40, v51, v34 bitop3:0x36
	v_and_b32_e32 v34, 0x60, v62
	v_lshlrev_b32_e32 v40, 2, v62
	v_and_or_b32 v34, v40, 16, v34
	v_lshrrev_b32_e32 v34, 3, v34
	v_or_b32_e32 v34, v34, v60
	v_add_u32_e32 v63, 0x80, v59
	v_lshlrev_b32_e32 v34, 10, v34
	v_and_b32_e32 v65, 0x60, v59
	v_bitop3_b32 v42, v34, v50, v51 bitop3:0xf6
	v_lshlrev_b32_e32 v34, 2, v63
	v_and_or_b32 v34, v34, 16, v65
	v_lshrrev_b32_e32 v34, 3, v34
	v_or_b32_e32 v34, v34, v60
	v_add_u32_e32 v64, 0xc0, v59
	v_lshlrev_b32_e32 v34, 10, v34
	v_bitop3_b32 v46, v34, v50, v51 bitop3:0xf6
	v_and_b32_e32 v34, 0x60, v64
	v_lshlrev_b32_e32 v48, 2, v64
	v_and_or_b32 v34, v48, 16, v34
	v_lshrrev_b32_e32 v34, 3, v34
	v_or_b32_e32 v34, v34, v60
	v_mul_lo_u32 v67, v1, s39
	v_mul_lo_u32 v68, v52, s39
	v_mul_lo_u32 v69, v53, s39
	v_mul_lo_u32 v70, v54, s39
	v_mul_lo_u32 v71, v55, s39
	v_mul_lo_u32 v72, v56, s39
	v_mul_lo_u32 v73, v57, s39
	v_mul_lo_u32 v75, v58, s39
	v_lshlrev_b32_e32 v38, 7, v59
	v_lshlrev_b32_e32 v40, 7, v62
	v_lshlrev_b32_e32 v44, 7, v63
	v_lshlrev_b32_e32 v48, 7, v64
	v_lshlrev_b32_e32 v34, 10, v34
	s_add_i32 s30, s46, s50
	v_and_b32_e32 v38, 0x4000, v38
	v_mov_b32_e32 v39, v35
	v_and_b32_e32 v40, 0x4000, v40
	v_mov_b32_e32 v41, v35
	v_mov_b32_e32 v43, v35
	v_and_b32_e32 v44, 0x4000, v44
	v_mov_b32_e32 v45, v35
	v_mov_b32_e32 v47, v35
	v_and_b32_e32 v48, 0x4000, v48
	v_mov_b32_e32 v49, v35
	v_bitop3_b32 v50, v34, v50, v51 bitop3:0xf6
	v_mov_b32_e32 v51, v35
	s_sub_i32 s49, s30, s49
	v_add_u32_e32 v67, v74, v67
	v_add_u32_e32 v68, v74, v68
	v_add_u32_e32 v69, v74, v69
	v_add_u32_e32 v70, v74, v70
	v_add_u32_e32 v71, v74, v71
	v_add_u32_e32 v72, v74, v72
	v_add_u32_e32 v73, v74, v73
	v_add_u32_e32 v74, v74, v75
	s_waitcnt vmcnt(0)
	s_branch .LBB0_30

; __device__ __forceinline__ void convert_t(const float* __restrict__ W, int K, int N, bf16_t* __restrict__ Wt, int swiglu, int& cursor, float* tile, int perm) {
;     ...
;     for (; id < last; id += G) {
;         const int tl = (id - first) % nt; const int k0 = (tl / ntn) * 64, n0 = (tl % ntn) * 256;
; #pragma unroll
;         for (int i = 0; i < 8; ++i) { const int idx = tid + 512 * i; const int row = idx >> 6, c4 = idx & 63; float* d = tile + row * 257 + 4 * c4; d[0] = v[i].x; d[1] = v[i].y; d[2] = v[i].z; d[3] = v[i].w; }
;         __syncthreads();
;         if (id + G < last) { const int tl2 = (id + G - first) % nt; const int k2 = (tl2 / ntn) * 64, n2 = (tl2 % ntn) * 256;
; #pragma unroll
;             for (int i = 0; i < 8; ++i) { const int idx = tid + 512 * i; const int row = idx >> 6, c4 = idx & 63; v[i] = *(const float4*)(W + (size_t)(k2 + row) * N + n2 + 4 * c4); } }
.LBB0_30:
	s_add_i32 s30, s38, s49
	s_cmp_ge_i32 s30, s47
	s_waitcnt vmcnt(11)
	ds_write2_b32 v67, v2, v3 offset1:1
	ds_write2_b32 v67, v4, v5 offset0:2 offset1:3
	s_waitcnt vmcnt(10)
	ds_write2_b32 v68, v6, v7 offset1:1
	ds_write2_b32 v68, v8, v9 offset0:2 offset1:3
	s_waitcnt vmcnt(9)
	ds_write2_b32 v69, v10, v11 offset1:1
	ds_write2_b32 v69, v12, v13 offset0:2 offset1:3
	s_waitcnt vmcnt(8)
	ds_write2_b32 v70, v14, v15 offset1:1
	ds_write2_b32 v70, v16, v17 offset0:2 offset1:3
	s_waitcnt vmcnt(7)
	ds_write2_b32 v71, v18, v19 offset1:1
	ds_write2_b32 v71, v20, v21 offset0:2 offset1:3
	s_waitcnt vmcnt(6)
	ds_write2_b32 v72, v22, v23 offset1:1
	ds_write2_b32 v72, v24, v25 offset0:2 offset1:3
	s_waitcnt vmcnt(5)
	ds_write2_b32 v73, v26, v27 offset1:1
	ds_write2_b32 v73, v28, v29 offset0:2 offset1:3
	s_waitcnt vmcnt(4)
	ds_write2_b32 v74, v30, v31 offset1:1
	ds_write2_b32 v74, v32, v33 offset0:2 offset1:3
	s_waitcnt lgkmcnt(0)
	s_barrier
	s_cbranch_scc1 .LBB0_29
	s_ashr_i32 s30, s49, 31
	s_lshr_b32 s30, s30, 25
	s_add_i32 s30, s49, s30
	s_and_b32 s30, s30, 0xff80
	s_sub_i32 s30, s49, s30
	s_bfe_i32 s31, s30, 0x80000
	s_bfe_u32 s31, s31, 0x3000c
	s_add_i32 s31, s30, s31
	s_bfe_i32 s50, s31, 0x80000
	s_sext_i32_i16 s50, s50
	s_and_b32 s31, s31, 0xf8
	s_lshl_b32 s50, s50, 3
	s_sub_i32 s30, s30, s31
	s_andn2_b32 s50, s50, 63
	s_sext_i32_i8 s30, s30
	s_lshl_b32 s30, s30, 8
	v_add_u32_e32 v2, s50, v1
	s_ashr_i32 s31, s30, 31
	v_ashrrev_i32_e32 v3, 31, v2
	v_lshl_add_u64 v[26:27], s[30:31], 2, v[36:37]
	v_lshlrev_b64 v[2:3], 13, v[2:3]
	v_lshl_add_u64 v[10:11], v[26:27], 0, v[2:3]
	v_add_u32_e32 v2, s50, v52
	v_ashrrev_i32_e32 v3, 31, v2
	v_lshlrev_b64 v[2:3], 13, v[2:3]
	v_lshl_add_u64 v[12:13], v[26:27], 0, v[2:3]
	global_load_dwordx4 v[2:5], v[10:11], off
	global_load_dwordx4 v[6:9], v[12:13], off
	v_add_u32_e32 v10, s50, v53
	v_ashrrev_i32_e32 v11, 31, v10
	v_lshlrev_b64 v[10:11], 13, v[10:11]
	v_lshl_add_u64 v[18:19], v[26:27], 0, v[10:11]
	v_add_u32_e32 v10, s50, v54
	v_ashrrev_i32_e32 v11, 31, v10
	v_lshlrev_b64 v[10:11], 13, v[10:11]
	v_lshl_add_u64 v[20:21], v[26:27], 0, v[10:11]
	global_load_dwordx4 v[10:13], v[18:19], off
	global_load_dwordx4 v[14:17], v[20:21], off
	v_add_u32_e32 v18, s50, v55
	v_ashrrev_i32_e32 v19, 31, v18
	v_lshlrev_b64 v[18:19], 13, v[18:19]
	v_lshl_add_u64 v[28:29], v[26:27], 0, v[18:19]
	v_add_u32_e32 v18, s50, v56
	v_ashrrev_i32_e32 v19, 31, v18
	v_lshlrev_b64 v[18:19], 13, v[18:19]
	v_lshl_add_u64 v[30:31], v[26:27], 0, v[18:19]
	global_load_dwordx4 v[18:21], v[28:29], off
	global_load_dwordx4 v[22:25], v[30:31], off
	v_add_u32_e32 v28, s50, v57
	v_ashrrev_i32_e32 v29, 31, v28
	v_lshlrev_b64 v[28:29], 13, v[28:29]
	v_lshl_add_u64 v[76:77], v[26:27], 0, v[28:29]
	v_add_u32_e32 v28, s50, v58
	v_ashrrev_i32_e32 v29, 31, v28
	v_lshlrev_b64 v[28:29], 13, v[28:29]
	v_lshl_add_u64 v[78:79], v[26:27], 0, v[28:29]
	global_load_dwordx4 v[26:29], v[76:77], off
	global_load_dwordx4 v[30:33], v[78:79], off
	s_branch .LBB0_29
; __device__ __forceinline__ unsigned cvt_pk_bf16(float lo, float hi) { unsigned r; asm volatile("v_cvt_pk_bf16_f32 %0, %1, %2" : "=v"(r) : "v"(lo), "v"(hi)); return r; }
; __device__ __forceinline__ void convert_t(const float* __restrict__ W, int K, int N, bf16_t* __restrict__ Wt, int swiglu, int& cursor, float* tile, int perm) {
;     ...
;     const int tid = tix_, G = gdim_; const int ntn = N / 256, nt = (K / 64) * ntn;
;     const int first = cursor; cursor += nt;
;     int id = first + (((int)bid_ - (first % G)) + G) % G;
;     const int last = first + nt * CONV_REP;
;     float4 v[8];
;     if (id < last) { const int tl = (id - first) % nt; const int k0 = (tl / ntn) * 64, n0 = (tl % ntn) * 256;
; #pragma unroll
;         for (int i = 0; i < 8; ++i) { const int idx = tid + 512 * i; const int row = idx >> 6, c4 = idx & 63; v[i] = *(const float4*)(W + (size_t)(k0 + row) * N + n0 + 4 * c4); } }
;     ...
;         for (int p = 0; p < 4; ++p) { const int nl = (tid >> 3) + 64 * p, kq = tid & 7; const float* s = tile + (8 * kq) * 257 + nl;
;             u32x4 w; w.x = cvt_pk_bf16(s[0], s[257]); w.y = cvt_pk_bf16(s[2 * 257], s[3 * 257]); w.z = cvt_pk_bf16(s[4 * 257], s[5 * 257]); w.w = cvt_pk_bf16(s[6 * 257], s[7 * 257]);
;             int n = n0 + nl; if (swiglu) { const int half = n >= DFF ? 1 : 0; const int c = n - half * DFF; n = (c >> 7) * 256 + half * 128 + (c & 127); }
;             { const int pn = n >> 8, half = (n >> 7) & 1, r = n & 127, c5 = r & 31;
;               const int R = perm ? ((r & ~31) + 16 * ((c5 >> 2) & 1) + 4 * (c5 >> 3) + (c5 & 3)) : r;
;               *(u32x4*)((unsigned char*)Wt + ((size_t)pn * (K >> 6) + (k0 >> 6)) * 32768 + half * 16384 + pg8::lds_byte(R, 8 * kq)) = w; } }
.LBB0_32:
	s_mov_b32 s30, s40
	s_mov_b32 s14, s2
	s_abs_i32 s15, s30
	v_cvt_f32_u32_e32 v1, s15
	s_sub_i32 s18, 0, s15
	v_mov_b32_e32 v38, v228
	v_rcp_iflag_f32_e32 v1, v1
	s_nop 0
	v_mul_f32_e32 v1, 0x4f7ffffe, v1
	v_cvt_u32_f32_e32 v1, v1
	s_nop 0
	v_readfirstlane_b32 s19, v1
	s_mul_i32 s18, s18, s19
	s_mul_hi_u32 s18, s19, s18
	s_add_i32 s19, s19, s18
	s_mul_hi_u32 s18, s19, 0xfd0
	s_mul_i32 s18, s18, s15
	s_sub_i32 s18, 0xfd0, s18
	s_sub_i32 s20, s18, s15
	s_cmp_ge_u32 s18, s15
	s_cselect_b32 s18, s20, s18
	s_sub_i32 s20, s18, s15
	s_cmp_ge_u32 s18, s15
	s_cselect_b32 s18, s20, s18
	s_add_i32 s14, s30, s14
	s_sub_i32 s14, s14, s18
	s_ashr_i32 s18, s14, 31
	s_abs_i32 s14, s14
	s_mul_hi_u32 s19, s14, s19
	s_mul_i32 s19, s19, s15
	s_sub_i32 s14, s14, s19
	s_sub_i32 s19, s14, s15
	s_cmp_ge_u32 s14, s15
	s_cselect_b32 s14, s19, s14
	s_sub_i32 s19, s14, s15
	s_cmp_ge_u32 s14, s15
	s_cselect_b32 s14, s19, s14
	s_xor_b32 s14, s14, s18
	s_sub_i32 s20, s14, s18
	s_cmpk_gt_i32 s20, 0xff
	s_cbranch_scc1 .LBB0_37
	s_add_u32 s14, s26, 0x7e80000
	s_addc_u32 s15, s27, 0
	s_ashr_i32 s18, s20, 31
	s_lshr_b32 s18, s18, 24
	s_add_i32 s18, s20, s18
	s_and_b32 s18, s18, 0xff00
	s_sub_i32 s18, s20, s18
	s_sext_i32_i16 s19, s18
	s_bfe_u32 s19, s19, 0x3001c
	s_add_i32 s19, s18, s19
	s_sext_i32_i16 s21, s19
	s_and_b32 s19, s19, 0xfff8
	s_sub_i32 s18, s18, s19
	s_sext_i32_i16 s18, s18
	s_lshl_b32 s18, s18, 8
	s_lshl_b32 s21, s21, 3
	s_ashr_i32 s19, s18, 31
	s_andn2_b32 s21, s21, 63
	s_lshl_b64 s[18:19], s[18:19], 2
	v_ashrrev_i32_e32 v1, 6, v38
	s_add_u32 s18, s22, s18
	v_lshlrev_b32_e32 v39, 4, v38
	s_waitcnt vmcnt(11)
	v_add_u32_e32 v2, s21, v1
	s_addc_u32 s19, s23, s19
	v_and_b32_e32 v34, 0x3f0, v39
	v_mov_b32_e32 v35, 0
	v_ashrrev_i32_e32 v3, 31, v2
	s_waitcnt vmcnt(5)
	v_lshl_add_u64 v[26:27], s[18:19], 0, v[34:35]
	v_lshlrev_b64 v[2:3], 13, v[2:3]
	v_lshl_add_u64 v[10:11], v[26:27], 0, v[2:3]
	v_add_u32_e32 v2, 0x200, v38
	v_ashrrev_i32_e32 v52, 6, v2
	v_add_u32_e32 v2, s21, v52
	v_ashrrev_i32_e32 v3, 31, v2
	v_lshlrev_b64 v[2:3], 13, v[2:3]
	v_lshl_add_u64 v[12:13], v[26:27], 0, v[2:3]
	global_load_dwordx4 v[2:5], v[10:11], off
	global_load_dwordx4 v[6:9], v[12:13], off
	v_add_u32_e32 v10, 0x400, v38
	v_ashrrev_i32_e32 v53, 6, v10
	v_add_u32_e32 v10, s21, v53
	v_ashrrev_i32_e32 v11, 31, v10
	v_lshlrev_b64 v[10:11], 13, v[10:11]
	v_lshl_add_u64 v[18:19], v[26:27], 0, v[10:11]
	v_add_u32_e32 v10, 0x600, v38
	v_ashrrev_i32_e32 v54, 6, v10
	v_add_u32_e32 v10, s21, v54
	v_ashrrev_i32_e32 v11, 31, v10
	v_lshlrev_b64 v[10:11], 13, v[10:11]
	v_lshl_add_u64 v[20:21], v[26:27], 0, v[10:11]
	global_load_dwordx4 v[10:13], v[18:19], off
	global_load_dwordx4 v[14:17], v[20:21], off
	v_add_u32_e32 v18, 0x800, v38
	v_ashrrev_i32_e32 v55, 6, v18
	v_add_u32_e32 v18, s21, v55
	v_ashrrev_i32_e32 v19, 31, v18
	v_lshlrev_b64 v[18:19], 13, v[18:19]
	v_lshl_add_u64 v[28:29], v[26:27], 0, v[18:19]
	v_add_u32_e32 v18, 0xa00, v38
	v_ashrrev_i32_e32 v56, 6, v18
	v_add_u32_e32 v18, s21, v56
	v_ashrrev_i32_e32 v19, 31, v18
	v_lshlrev_b64 v[18:19], 13, v[18:19]
	s_waitcnt vmcnt(8)
	v_lshl_add_u64 v[30:31], v[26:27], 0, v[18:19]
	global_load_dwordx4 v[18:21], v[28:29], off
	global_load_dwordx4 v[22:25], v[30:31], off
	v_add_u32_e32 v28, 0xc00, v38
	v_ashrrev_i32_e32 v57, 6, v28
	v_add_u32_e32 v28, s21, v57
	v_ashrrev_i32_e32 v29, 31, v28
	v_lshlrev_b64 v[28:29], 13, v[28:29]
	v_lshl_add_u64 v[36:37], v[26:27], 0, v[28:29]
	v_add_u32_e32 v28, 0xe00, v38
	v_ashrrev_i32_e32 v58, 6, v28
	v_add_u32_e32 v28, s21, v58
	v_ashrrev_i32_e32 v29, 31, v28
	v_lshlrev_b64 v[28:29], 13, v[28:29]
	v_lshl_add_u64 v[40:41], v[26:27], 0, v[28:29]
	global_load_dwordx4 v[26:29], v[36:37], off
	global_load_dwordx4 v[30:33], v[40:41], off
	v_add_u32_e32 v74, 0, v34
	v_lshl_add_u64 v[36:37], s[22:23], 0, v[34:35]
	v_lshlrev_b32_e32 v34, 3, v38
	v_ashrrev_i32_e32 v59, 3, v38
	v_and_b32_e32 v38, 56, v34
	v_mul_u32_u24_e32 v38, 0x404, v38
	v_bfe_u32 v60, v34, 5, 1
	v_and_b32_e32 v34, 48, v39
	v_lshlrev_b32_e32 v39, 2, v59
	v_add3_u32 v61, 0, v38, v39
	v_lshrrev_b32_e32 v38, 1, v59
	v_and_b32_e32 v39, 3, v59
	v_and_or_b32 v40, v38, 12, v39
	v_lshlrev_b32_e32 v41, 1, v59
	v_add_u32_e32 v62, 64, v59
	v_lshlrev_b32_e32 v40, 6, v40
	v_and_b32_e32 v51, 32, v41
	v_or_b32_e32 v50, v40, v34
	v_bitop3_b32 v66, v40, v51, v34 bitop3:0x36
	v_and_b32_e32 v34, 0x60, v62
	v_lshlrev_b32_e32 v40, 2, v62
	v_and_or_b32 v34, v40, 16, v34
	v_lshrrev_b32_e32 v34, 3, v34
	v_or_b32_e32 v34, v34, v60
	v_add_u32_e32 v63, 0x80, v59
	v_lshlrev_b32_e32 v34, 10, v34
	v_and_b32_e32 v65, 0x60, v59
	v_bitop3_b32 v42, v34, v50, v51 bitop3:0xf6
	v_lshlrev_b32_e32 v34, 2, v63
	v_and_or_b32 v34, v34, 16, v65
	v_lshrrev_b32_e32 v34, 3, v34
	v_or_b32_e32 v34, v34, v60
	v_add_u32_e32 v64, 0xc0, v59
	v_lshlrev_b32_e32 v34, 10, v34
	v_bitop3_b32 v46, v34, v50, v51 bitop3:0xf6
	v_and_b32_e32 v34, 0x60, v64
	v_lshlrev_b32_e32 v48, 2, v64
	v_and_or_b32 v34, v48, 16, v34
	v_lshrrev_b32_e32 v34, 3, v34
	s_movk_i32 s18, 0x404
	v_or_b32_e32 v34, v34, v60
	v_mul_lo_u32 v67, v1, s18
	v_mul_lo_u32 v68, v52, s18
	v_mul_lo_u32 v69, v53, s18
	v_mul_lo_u32 v70, v54, s18
	v_mul_lo_u32 v71, v55, s18
	v_mul_lo_u32 v72, v56, s18
	v_mul_lo_u32 v73, v57, s18
	v_mul_lo_u32 v75, v58, s18
	v_lshlrev_b32_e32 v38, 7, v59
	v_lshlrev_b32_e32 v40, 7, v62
	v_lshlrev_b32_e32 v44, 7, v63
	v_lshlrev_b32_e32 v48, 7, v64
	v_lshlrev_b32_e32 v34, 10, v34
	v_and_b32_e32 v38, 0x4000, v38
	v_mov_b32_e32 v39, v35
	v_and_b32_e32 v40, 0x4000, v40
	v_mov_b32_e32 v41, v35
	v_mov_b32_e32 v43, v35
	v_and_b32_e32 v44, 0x4000, v44
	v_mov_b32_e32 v45, v35
	v_mov_b32_e32 v47, v35
	v_and_b32_e32 v48, 0x4000, v48
	v_mov_b32_e32 v49, v35
	v_bitop3_b32 v50, v34, v50, v51 bitop3:0xf6
	v_mov_b32_e32 v51, v35
	v_add_u32_e32 v67, v74, v67
	v_add_u32_e32 v68, v74, v68
	v_add_u32_e32 v69, v74, v69
	v_add_u32_e32 v70, v74, v70
	v_add_u32_e32 v71, v74, v71
	v_add_u32_e32 v72, v74, v72
	v_add_u32_e32 v73, v74, v73
	v_add_u32_e32 v74, v74, v75
	s_waitcnt vmcnt(0)
	s_branch .LBB0_35

; __device__ __forceinline__ void convert_t(const float* __restrict__ W, int K, int N, bf16_t* __restrict__ Wt, int swiglu, int& cursor, float* tile, int perm) {
;     ...
;     for (; id < last; id += G) {
;         const int tl = (id - first) % nt; const int k0 = (tl / ntn) * 64, n0 = (tl % ntn) * 256;
; #pragma unroll
;         for (int i = 0; i < 8; ++i) { const int idx = tid + 512 * i; const int row = idx >> 6, c4 = idx & 63; float* d = tile + row * 257 + 4 * c4; d[0] = v[i].x; d[1] = v[i].y; d[2] = v[i].z; d[3] = v[i].w; }
;         __syncthreads();
;         if (id + G < last) { const int tl2 = (id + G - first) % nt; const int k2 = (tl2 / ntn) * 64, n2 = (tl2 % ntn) * 256;
; #pragma unroll
;             for (int i = 0; i < 8; ++i) { const int idx = tid + 512 * i; const int row = idx >> 6, c4 = idx & 63; v[i] = *(const float4*)(W + (size_t)(k2 + row) * N + n2 + 4 * c4); } }
.LBB0_35:
	s_add_i32 s22, s30, s20
	s_add_i32 s18, s22, 0xfd0
	s_cmpk_gt_i32 s18, 0x10cf
	s_cselect_b64 s[18:19], -1, 0
	s_and_b64 vcc, exec, s[18:19]
	s_waitcnt vmcnt(11)
	ds_write2_b32 v67, v2, v3 offset1:1
	ds_write2_b32 v67, v4, v5 offset0:2 offset1:3
	s_waitcnt vmcnt(10)
	ds_write2_b32 v68, v6, v7 offset1:1
	ds_write2_b32 v68, v8, v9 offset0:2 offset1:3
	s_waitcnt vmcnt(9)
	ds_write2_b32 v69, v10, v11 offset1:1
	ds_write2_b32 v69, v12, v13 offset0:2 offset1:3
	s_waitcnt vmcnt(8)
	ds_write2_b32 v70, v14, v15 offset1:1
	ds_write2_b32 v70, v16, v17 offset0:2 offset1:3
	s_waitcnt vmcnt(7)
	ds_write2_b32 v71, v18, v19 offset1:1
	ds_write2_b32 v71, v20, v21 offset0:2 offset1:3
	s_waitcnt vmcnt(6)
	ds_write2_b32 v72, v22, v23 offset1:1
	ds_write2_b32 v72, v24, v25 offset0:2 offset1:3
	s_waitcnt vmcnt(5)
	ds_write2_b32 v73, v26, v27 offset1:1
	ds_write2_b32 v73, v28, v29 offset0:2 offset1:3
	s_waitcnt vmcnt(4)
	ds_write2_b32 v74, v30, v31 offset1:1
	ds_write2_b32 v74, v32, v33 offset0:2 offset1:3
	s_waitcnt lgkmcnt(0)
	s_barrier
	s_cbranch_vccnz .LBB0_34
	s_ashr_i32 s21, s22, 31
	s_lshr_b32 s21, s21, 24
	s_add_i32 s21, s22, s21
	s_and_b32 s21, s21, 0xff00
	s_sub_i32 s21, s22, s21
	s_sext_i32_i16 s23, s21
	s_bfe_u32 s23, s23, 0x3001c
	s_add_i32 s23, s21, s23
	s_sext_i32_i16 s31, s23
	s_and_b32 s23, s23, 0xfff8
	s_lshl_b32 s31, s31, 3
	s_sub_i32 s21, s21, s23
	s_andn2_b32 s31, s31, 63
	s_sext_i32_i16 s21, s21
	s_lshl_b32 s36, s21, 8
	v_add_u32_e32 v2, s31, v1
	s_ashr_i32 s37, s36, 31
	v_ashrrev_i32_e32 v3, 31, v2
	v_lshl_add_u64 v[26:27], s[36:37], 2, v[36:37]
	v_lshlrev_b64 v[2:3], 13, v[2:3]
	v_lshl_add_u64 v[10:11], v[26:27], 0, v[2:3]
	v_add_u32_e32 v2, s31, v52
	v_ashrrev_i32_e32 v3, 31, v2
	v_lshlrev_b64 v[2:3], 13, v[2:3]
	v_lshl_add_u64 v[12:13], v[26:27], 0, v[2:3]
	global_load_dwordx4 v[2:5], v[10:11], off
	global_load_dwordx4 v[6:9], v[12:13], off
	v_add_u32_e32 v10, s31, v53
	v_ashrrev_i32_e32 v11, 31, v10
	v_lshlrev_b64 v[10:11], 13, v[10:11]
	v_lshl_add_u64 v[18:19], v[26:27], 0, v[10:11]
	v_add_u32_e32 v10, s31, v54
	v_ashrrev_i32_e32 v11, 31, v10
	v_lshlrev_b64 v[10:11], 13, v[10:11]
	v_lshl_add_u64 v[20:21], v[26:27], 0, v[10:11]
	global_load_dwordx4 v[10:13], v[18:19], off
	global_load_dwordx4 v[14:17], v[20:21], off
	v_add_u32_e32 v18, s31, v55
	v_ashrrev_i32_e32 v19, 31, v18
	v_lshlrev_b64 v[18:19], 13, v[18:19]
	v_lshl_add_u64 v[28:29], v[26:27], 0, v[18:19]
	v_add_u32_e32 v18, s31, v56
	v_ashrrev_i32_e32 v19, 31, v18
	v_lshlrev_b64 v[18:19], 13, v[18:19]
	v_lshl_add_u64 v[30:31], v[26:27], 0, v[18:19]
	global_load_dwordx4 v[18:21], v[28:29], off
	global_load_dwordx4 v[22:25], v[30:31], off
	v_add_u32_e32 v28, s31, v57
	v_ashrrev_i32_e32 v29, 31, v28
	v_lshlrev_b64 v[28:29], 13, v[28:29]
	v_lshl_add_u64 v[76:77], v[26:27], 0, v[28:29]
	v_add_u32_e32 v28, s31, v58
	v_ashrrev_i32_e32 v29, 31, v28
	v_lshlrev_b64 v[28:29], 13, v[28:29]
	v_lshl_add_u64 v[78:79], v[26:27], 0, v[28:29]
	global_load_dwordx4 v[26:29], v[76:77], off
	global_load_dwordx4 v[30:33], v[78:79], off
	s_branch .LBB0_34
; __device__ __forceinline__ unsigned cvt_pk_bf16(float lo, float hi) { unsigned r; asm volatile("v_cvt_pk_bf16_f32 %0, %1, %2" : "=v"(r) : "v"(lo), "v"(hi)); return r; }
; __device__ __forceinline__ void convert_t(const float* __restrict__ W, int K, int N, bf16_t* __restrict__ Wt, int swiglu, int& cursor, float* tile, int perm) {
;     ...
;     const int tid = tix_, G = gdim_; const int ntn = N / 256, nt = (K / 64) * ntn;
;     const int first = cursor; cursor += nt;
;     int id = first + (((int)bid_ - (first % G)) + G) % G;
;     const int last = first + nt * CONV_REP;
;     float4 v[8];
;     if (id < last) { const int tl = (id - first) % nt; const int k0 = (tl / ntn) * 64, n0 = (tl % ntn) * 256;
; #pragma unroll
;         for (int i = 0; i < 8; ++i) { const int idx = tid + 512 * i; const int row = idx >> 6, c4 = idx & 63; v[i] = *(const float4*)(W + (size_t)(k0 + row) * N + n0 + 4 * c4); } }
;     ...
;         for (int p = 0; p < 4; ++p) { const int nl = (tid >> 3) + 64 * p, kq = tid & 7; const float* s = tile + (8 * kq) * 257 + nl;
;             u32x4 w; w.x = cvt_pk_bf16(s[0], s[257]); w.y = cvt_pk_bf16(s[2 * 257], s[3 * 257]); w.z = cvt_pk_bf16(s[4 * 257], s[5 * 257]); w.w = cvt_pk_bf16(s[6 * 257], s[7 * 257]);
;             int n = n0 + nl; if (swiglu) { const int half = n >= DFF ? 1 : 0; const int c = n - half * DFF; n = (c >> 7) * 256 + half * 128 + (c & 127); }
;             { const int pn = n >> 8, half = (n >> 7) & 1, r = n & 127, c5 = r & 31;
;               const int R = perm ? ((r & ~31) + 16 * ((c5 >> 2) & 1) + 4 * (c5 >> 3) + (c5 & 3)) : r;
;               *(u32x4*)((unsigned char*)Wt + ((size_t)pn * (K >> 6) + (k0 >> 6)) * 32768 + half * 16384 + pg8::lds_byte(R, 8 * kq)) = w; } }
.LBB0_37:
	s_mov_b32 s14, s2
	s_mov_b32 s20, s40
	s_abs_i32 s15, s20
	v_cvt_f32_u32_e32 v1, s15
	s_sub_i32 s18, 0, s15
	v_mov_b32_e32 v38, v228
	v_rcp_iflag_f32_e32 v1, v1
	s_nop 0
	v_mul_f32_e32 v1, 0x4f7ffffe, v1
	v_cvt_u32_f32_e32 v1, v1
	s_nop 0
	v_readfirstlane_b32 s19, v1
	s_mul_i32 s18, s18, s19
	s_mul_hi_u32 s18, s19, s18
	s_add_i32 s19, s19, s18
	s_mul_hi_u32 s18, s19, 0x10d0
	s_mul_i32 s18, s18, s15
	s_sub_i32 s18, 0x10d0, s18
	s_sub_i32 s21, s18, s15
	s_cmp_ge_u32 s18, s15
	s_cselect_b32 s18, s21, s18
	s_sub_i32 s21, s18, s15
	s_cmp_ge_u32 s18, s15
	s_cselect_b32 s18, s21, s18
	s_add_i32 s14, s20, s14
	s_sub_i32 s14, s14, s18
	s_ashr_i32 s18, s14, 31
	s_abs_i32 s14, s14
	s_mul_hi_u32 s19, s14, s19
	s_mul_i32 s19, s19, s15
	s_sub_i32 s14, s14, s19
	s_sub_i32 s19, s14, s15
	s_cmp_ge_u32 s14, s15
	s_cselect_b32 s14, s19, s14
	s_sub_i32 s19, s14, s15
	s_cmp_ge_u32 s14, s15
	s_cselect_b32 s14, s19, s14
	s_xor_b32 s14, s14, s18
	s_sub_i32 s18, s14, s18
	s_cmpk_gt_i32 s18, 0x55f
	s_cbranch_scc1 .LBB0_42
	s_add_u32 s14, s26, 0x8680000
	s_mul_hi_i32 s19, s18, 0x2fa0be83
	s_addc_u32 s15, s27, 0
	s_lshr_b32 s21, s19, 31
	s_ashr_i32 s19, s19, 8
	s_add_i32 s19, s19, s21
	s_mulk_i32 s19, 0x560
	s_sub_i32 s19, s18, s19
	s_sext_i32_i16 s21, s19
	s_mulk_i32 s21, 0x2fa1
	s_lshr_b32 s22, s21, 31
	s_ashr_i32 s21, s21, 19
	s_add_i32 s21, s21, s22
	s_sext_i32_i16 s22, s21
	s_mul_i32 s21, s21, 43
	s_sub_i32 s19, s19, s21
	s_sext_i32_i16 s19, s19
	s_lshl_b32 s30, s22, 6
	s_lshl_b32 s22, s19, 8
	s_ashr_i32 s23, s22, 31
	s_lshl_b64 s[22:23], s[22:23], 2
	s_add_u32 s22, s4, s22
	v_lshlrev_b32_e32 v39, 4, v38
	s_addc_u32 s23, s5, s23
	v_and_b32_e32 v34, 0x3f0, v39
	v_mov_b32_e32 v35, 0
	v_ashrrev_i32_e32 v1, 6, v38
	s_waitcnt vmcnt(5)
	v_lshl_add_u64 v[26:27], s[22:23], 0, v[34:35]
	v_add_u32_e32 v2, s30, v1
	s_mov_b32 s21, 0xac00
	v_mad_i64_i32 v[10:11], s[22:23], v2, s21, v[26:27]
	v_add_u32_e32 v2, 0x200, v38
	v_ashrrev_i32_e32 v44, 6, v2
	v_add_u32_e32 v2, s30, v44
	v_mad_i64_i32 v[12:13], s[22:23], v2, s21, v[26:27]
	global_load_dwordx4 v[2:5], v[10:11], off
	global_load_dwordx4 v[6:9], v[12:13], off
	v_add_u32_e32 v10, 0x400, v38
	v_ashrrev_i32_e32 v45, 6, v10
	v_add_u32_e32 v10, s30, v45
	v_mad_i64_i32 v[18:19], s[22:23], v10, s21, v[26:27]
	v_add_u32_e32 v10, 0x600, v38
	v_ashrrev_i32_e32 v46, 6, v10
	v_add_u32_e32 v10, s30, v46
	v_mad_i64_i32 v[20:21], s[22:23], v10, s21, v[26:27]
	global_load_dwordx4 v[10:13], v[18:19], off
	global_load_dwordx4 v[14:17], v[20:21], off
	v_add_u32_e32 v18, 0x800, v38
	v_ashrrev_i32_e32 v47, 6, v18
	v_add_u32_e32 v18, s30, v47
	v_mad_i64_i32 v[28:29], s[22:23], v18, s21, v[26:27]
	v_add_u32_e32 v18, 0xa00, v38
	v_ashrrev_i32_e32 v48, 6, v18
	v_add_u32_e32 v18, s30, v48
	s_waitcnt vmcnt(8)
	v_mad_i64_i32 v[30:31], s[22:23], v18, s21, v[26:27]
	global_load_dwordx4 v[18:21], v[28:29], off
	global_load_dwordx4 v[22:25], v[30:31], off
	v_add_u32_e32 v28, 0xc00, v38
	v_ashrrev_i32_e32 v49, 6, v28
	v_add_u32_e32 v28, s30, v49
	v_mad_i64_i32 v[36:37], s[22:23], v28, s21, v[26:27]
	v_add_u32_e32 v28, 0xe00, v38
	v_ashrrev_i32_e32 v50, 6, v28
	v_add_u32_e32 v28, s30, v50
	v_mad_i64_i32 v[40:41], s[22:23], v28, s21, v[26:27]
	global_load_dwordx4 v[26:29], v[36:37], off
	global_load_dwordx4 v[30:33], v[40:41], off
	v_add_u32_e32 v62, 0, v34
	v_lshl_add_u64 v[36:37], s[4:5], 0, v[34:35]
	v_lshlrev_b32_e32 v34, 3, v38
	v_ashrrev_i32_e32 v51, 3, v38
	v_and_b32_e32 v38, 56, v34
	v_mul_u32_u24_e32 v38, 0x404, v38
	v_lshlrev_b32_e32 v40, 2, v51
	v_add3_u32 v52, 0, v38, v40
	v_and_b32_e32 v38, 0x60, v51
	v_and_or_b32 v38, v40, 16, v38
	v_lshrrev_b32_e32 v40, 1, v51
	v_and_b32_e32 v41, 3, v51
	v_and_b32_e32 v39, 48, v39
	v_add_u32_e32 v53, 64, v51
	v_add_u32_e32 v54, 0xc0, v51
	v_and_or_b32 v40, v40, 12, v41
	v_lshl_or_b32 v42, v40, 6, v39
	v_and_b32_e32 v40, 0x60, v53
	v_lshlrev_b32_e32 v41, 2, v53
	v_and_b32_e32 v64, 0x60, v54
	v_lshlrev_b32_e32 v65, 2, v54
	v_and_or_b32 v40, v41, 16, v40
	v_and_or_b32 v64, v65, 16, v64
	v_bfe_u32 v34, v34, 5, 1
	v_lshrrev_b32_e32 v38, 3, v38
	v_lshrrev_b32_e32 v40, 3, v40
	v_lshrrev_b32_e32 v64, 3, v64
	s_movk_i32 s4, 0x404
	v_or_b32_e32 v38, v38, v34
	v_lshlrev_b32_e32 v39, 1, v51
	v_or_b32_e32 v40, v40, v34
	v_or_b32_e32 v34, v64, v34
	v_mul_lo_u32 v55, v1, s4
	v_mul_lo_u32 v56, v44, s4
	v_mul_lo_u32 v57, v45, s4
	v_mul_lo_u32 v58, v46, s4
	v_mul_lo_u32 v59, v47, s4
	v_mul_lo_u32 v60, v48, s4
	v_mul_lo_u32 v61, v49, s4
	v_mul_lo_u32 v63, v50, s4
	v_lshlrev_b32_e32 v38, 10, v38
	v_and_b32_e32 v43, 32, v39
	v_lshlrev_b32_e32 v40, 10, v40
	v_lshlrev_b32_e32 v34, 10, v34
	v_bitop3_b32 v38, v38, v42, v43 bitop3:0xf6
	v_mov_b32_e32 v39, v35
	v_bitop3_b32 v40, v40, v42, v43 bitop3:0xf6
	v_mov_b32_e32 v41, v35
	v_bitop3_b32 v42, v34, v42, v43 bitop3:0xf6
	v_mov_b32_e32 v43, v35
	v_add_u32_e32 v55, v62, v55
	v_add_u32_e32 v56, v62, v56
	v_add_u32_e32 v57, v62, v57
	v_add_u32_e32 v58, v62, v58
	v_add_u32_e32 v59, v62, v59
	v_add_u32_e32 v60, v62, v60
	v_add_u32_e32 v61, v62, v61
	v_add_u32_e32 v62, v62, v63
	s_movk_i32 s22, 0x157f
	v_mov_b32_e32 v63, 0xffffea80
	v_mov_b32_e32 v64, 0x4000
	s_waitcnt vmcnt(0)
	s_branch .LBB0_40

; __device__ __forceinline__ void convert_t(const float* __restrict__ W, int K, int N, bf16_t* __restrict__ Wt, int swiglu, int& cursor, float* tile, int perm) {
;     ...
;     for (; id < last; id += G) {
;         const int tl = (id - first) % nt; const int k0 = (tl / ntn) * 64, n0 = (tl % ntn) * 256;
; #pragma unroll
;         for (int i = 0; i < 8; ++i) { const int idx = tid + 512 * i; const int row = idx >> 6, c4 = idx & 63; float* d = tile + row * 257 + 4 * c4; d[0] = v[i].x; d[1] = v[i].y; d[2] = v[i].z; d[3] = v[i].w; }
;         __syncthreads();
;         if (id + G < last) { const int tl2 = (id + G - first) % nt; const int k2 = (tl2 / ntn) * 64, n2 = (tl2 % ntn) * 256;
; #pragma unroll
;             for (int i = 0; i < 8; ++i) { const int idx = tid + 512 * i; const int row = idx >> 6, c4 = idx & 63; v[i] = *(const float4*)(W + (size_t)(k2 + row) * N + n2 + 4 * c4); } }
.LBB0_40:
	s_add_i32 s23, s20, s18
	s_add_i32 s4, s23, 0x10d0
	s_cmpk_gt_i32 s4, 0x162f
	s_cselect_b64 s[4:5], -1, 0
	s_and_b64 vcc, exec, s[4:5]
	s_waitcnt vmcnt(11)
	ds_write2_b32 v55, v2, v3 offset1:1
	ds_write2_b32 v55, v4, v5 offset0:2 offset1:3
	s_waitcnt vmcnt(10)
	ds_write2_b32 v56, v6, v7 offset1:1
	ds_write2_b32 v56, v8, v9 offset0:2 offset1:3
	s_waitcnt vmcnt(9)
	ds_write2_b32 v57, v10, v11 offset1:1
	ds_write2_b32 v57, v12, v13 offset0:2 offset1:3
	s_waitcnt vmcnt(8)
	ds_write2_b32 v58, v14, v15 offset1:1
	ds_write2_b32 v58, v16, v17 offset0:2 offset1:3
	s_waitcnt vmcnt(7)
	ds_write2_b32 v59, v18, v19 offset1:1
	ds_write2_b32 v59, v20, v21 offset0:2 offset1:3
	s_waitcnt vmcnt(6)
	ds_write2_b32 v60, v22, v23 offset1:1
	ds_write2_b32 v60, v24, v25 offset0:2 offset1:3
	s_waitcnt vmcnt(5)
	ds_write2_b32 v61, v26, v27 offset1:1
	ds_write2_b32 v61, v28, v29 offset0:2 offset1:3
	s_waitcnt vmcnt(4)
	ds_write2_b32 v62, v30, v31 offset1:1
	ds_write2_b32 v62, v32, v33 offset0:2 offset1:3
	s_waitcnt lgkmcnt(0)
	s_barrier
	s_cbranch_vccnz .LBB0_39
	s_mul_hi_i32 s19, s23, 0x2fa0be83
	s_lshr_b32 s30, s19, 31
	s_ashr_i32 s19, s19, 8
	s_add_i32 s19, s19, s30
	s_mulk_i32 s19, 0x560
	s_sub_i32 s19, s23, s19
	s_sext_i32_i16 s30, s19
	s_mulk_i32 s30, 0x2fa1
	s_lshr_b32 s31, s30, 31
	s_ashr_i32 s30, s30, 19
	s_add_i32 s30, s30, s31
	s_lshl_b32 s36, s30, 6
	s_mul_i32 s30, s30, 43
	s_sub_i32 s19, s19, s30
	s_sext_i32_i16 s19, s19
	s_lshl_b32 s30, s19, 8
	s_ashr_i32 s31, s30, 31
	v_lshl_add_u64 v[26:27], s[30:31], 2, v[36:37]
	v_add_u32_e32 v2, s36, v1
	v_mad_i64_i32 v[10:11], s[30:31], v2, s21, v[26:27]
	v_add_u32_e32 v2, s36, v44
	v_mad_i64_i32 v[12:13], s[30:31], v2, s21, v[26:27]
	global_load_dwordx4 v[2:5], v[10:11], off
	global_load_dwordx4 v[6:9], v[12:13], off
	v_add_u32_e32 v10, s36, v45
	v_mad_i64_i32 v[18:19], s[30:31], v10, s21, v[26:27]
	v_add_u32_e32 v10, s36, v46
	v_mad_i64_i32 v[20:21], s[30:31], v10, s21, v[26:27]
	global_load_dwordx4 v[10:13], v[18:19], off
	global_load_dwordx4 v[14:17], v[20:21], off
	v_add_u32_e32 v18, s36, v47
	v_mad_i64_i32 v[28:29], s[30:31], v18, s21, v[26:27]
	v_add_u32_e32 v18, s36, v48
	v_mad_i64_i32 v[30:31], s[30:31], v18, s21, v[26:27]
	global_load_dwordx4 v[18:21], v[28:29], off
	global_load_dwordx4 v[22:25], v[30:31], off
	v_add_u32_e32 v28, s36, v49
	v_mad_i64_i32 v[66:67], s[30:31], v28, s21, v[26:27]
	v_add_u32_e32 v28, s36, v50
	v_mad_i64_i32 v[68:69], s[30:31], v28, s21, v[26:27]
	global_load_dwordx4 v[26:29], v[66:67], off
	global_load_dwordx4 v[30:33], v[68:69], off
	s_branch .LBB0_39
; __device__ __forceinline__ unsigned cvt_pk_bf16(float lo, float hi) { unsigned r; asm volatile("v_cvt_pk_bf16_f32 %0, %1, %2" : "=v"(r) : "v"(lo), "v"(hi)); return r; }
; __device__ __forceinline__ void convert_t(const float* __restrict__ W, int K, int N, bf16_t* __restrict__ Wt, int swiglu, int& cursor, float* tile, int perm) {
;     ...
;     const int tid = tix_, G = gdim_; const int ntn = N / 256, nt = (K / 64) * ntn;
;     const int first = cursor; cursor += nt;
;     int id = first + (((int)bid_ - (first % G)) + G) % G;
;     const int last = first + nt * CONV_REP;
;     float4 v[8];
;     if (id < last) { const int tl = (id - first) % nt; const int k0 = (tl / ntn) * 64, n0 = (tl % ntn) * 256;
; #pragma unroll
;         for (int i = 0; i < 8; ++i) { const int idx = tid + 512 * i; const int row = idx >> 6, c4 = idx & 63; v[i] = *(const float4*)(W + (size_t)(k0 + row) * N + n0 + 4 * c4); } }
;     ...
;         for (int p = 0; p < 4; ++p) { const int nl = (tid >> 3) + 64 * p, kq = tid & 7; const float* s = tile + (8 * kq) * 257 + nl;
;             u32x4 w; w.x = cvt_pk_bf16(s[0], s[257]); w.y = cvt_pk_bf16(s[2 * 257], s[3 * 257]); w.z = cvt_pk_bf16(s[4 * 257], s[5 * 257]); w.w = cvt_pk_bf16(s[6 * 257], s[7 * 257]);
;             int n = n0 + nl; if (swiglu) { const int half = n >= DFF ? 1 : 0; const int c = n - half * DFF; n = (c >> 7) * 256 + half * 128 + (c & 127); }
;             { const int pn = n >> 8, half = (n >> 7) & 1, r = n & 127, c5 = r & 31;
;               const int R = perm ? ((r & ~31) + 16 * ((c5 >> 2) & 1) + 4 * (c5 >> 3) + (c5 & 3)) : r;
;               *(u32x4*)((unsigned char*)Wt + ((size_t)pn * (K >> 6) + (k0 >> 6)) * 32768 + half * 16384 + pg8::lds_byte(R, 8 * kq)) = w; } }
.LBB0_42:
	s_mov_b32 s4, s2
	s_mov_b32 s14, s40
	s_abs_i32 s5, s14
	v_cvt_f32_u32_e32 v1, s5
	s_sub_i32 s15, 0, s5
	v_mov_b32_e32 v38, v228
	v_rcp_iflag_f32_e32 v1, v1
	s_nop 0
	v_mul_f32_e32 v1, 0x4f7ffffe, v1
	v_cvt_u32_f32_e32 v1, v1
	s_nop 0
	v_readfirstlane_b32 s18, v1
	s_mul_i32 s15, s15, s18
	s_mul_hi_u32 s15, s18, s15
	s_add_i32 s18, s18, s15
	s_mul_hi_u32 s15, s18, 0x1630
	s_mul_i32 s15, s15, s5
	s_sub_i32 s15, 0x1630, s15
	s_sub_i32 s19, s15, s5
	s_cmp_ge_u32 s15, s5
	s_cselect_b32 s15, s19, s15
	s_sub_i32 s19, s15, s5
	s_cmp_ge_u32 s15, s5
	s_cselect_b32 s15, s19, s15
	s_add_i32 s4, s14, s4
	s_sub_i32 s4, s4, s15
	s_ashr_i32 s15, s4, 31
	s_abs_i32 s4, s4
	s_mul_hi_u32 s18, s4, s18
	s_mul_i32 s18, s18, s5
	s_sub_i32 s4, s4, s18
	s_sub_i32 s18, s4, s5
	s_cmp_ge_u32 s4, s5
	s_cselect_b32 s4, s18, s4
	s_sub_i32 s18, s4, s5
	s_cmp_ge_u32 s4, s5
	s_cselect_b32 s4, s18, s4
	s_xor_b32 s4, s4, s15
	s_sub_i32 s15, s4, s15
	s_cmpk_gt_i32 s15, 0x2af
	s_cbranch_scc1 .LBB0_47
	s_add_u32 s4, s26, 0xb180000
	s_mul_hi_i32 s18, s15, 0x2fa0be83
	s_addc_u32 s5, s27, 0
	s_lshr_b32 s19, s18, 31
	s_ashr_i32 s18, s18, 7
	s_add_i32 s18, s18, s19
	s_mulk_i32 s18, 0x2b0
	s_sub_i32 s18, s15, s18
	s_sext_i32_i16 s19, s18
	s_bfe_u32 s19, s19, 0x3001c
	s_add_i32 s19, s18, s19
	s_sext_i32_i16 s20, s19
	s_and_b32 s19, s19, 0xfff8
	s_sub_i32 s18, s18, s19
	s_sext_i32_i16 s18, s18
	s_lshl_b32 s18, s18, 8
	s_lshl_b32 s20, s20, 3
	s_ashr_i32 s19, s18, 31
	s_andn2_b32 s20, s20, 63
	s_lshl_b64 s[18:19], s[18:19], 2
	v_ashrrev_i32_e32 v1, 6, v38
	s_add_u32 s18, s6, s18
	v_lshlrev_b32_e32 v39, 4, v38
	s_waitcnt vmcnt(11)
	v_add_u32_e32 v2, s20, v1
	s_addc_u32 s19, s7, s19
	v_and_b32_e32 v34, 0x3f0, v39
	v_mov_b32_e32 v35, 0
	v_ashrrev_i32_e32 v3, 31, v2
	s_waitcnt vmcnt(5)
	v_lshl_add_u64 v[26:27], s[18:19], 0, v[34:35]
	v_lshlrev_b64 v[2:3], 13, v[2:3]
	v_lshl_add_u64 v[10:11], v[26:27], 0, v[2:3]
	v_add_u32_e32 v2, 0x200, v38
	v_ashrrev_i32_e32 v46, 6, v2
	v_add_u32_e32 v2, s20, v46
	v_ashrrev_i32_e32 v3, 31, v2
	v_lshlrev_b64 v[2:3], 13, v[2:3]
	v_lshl_add_u64 v[12:13], v[26:27], 0, v[2:3]
	global_load_dwordx4 v[2:5], v[10:11], off
	global_load_dwordx4 v[6:9], v[12:13], off
	v_add_u32_e32 v10, 0x400, v38
	v_ashrrev_i32_e32 v47, 6, v10
	v_add_u32_e32 v10, s20, v47
	v_ashrrev_i32_e32 v11, 31, v10
	v_lshlrev_b64 v[10:11], 13, v[10:11]
	v_lshl_add_u64 v[18:19], v[26:27], 0, v[10:11]
	v_add_u32_e32 v10, 0x600, v38
	v_ashrrev_i32_e32 v48, 6, v10
	v_add_u32_e32 v10, s20, v48
	v_ashrrev_i32_e32 v11, 31, v10
	v_lshlrev_b64 v[10:11], 13, v[10:11]
	v_lshl_add_u64 v[20:21], v[26:27], 0, v[10:11]
	global_load_dwordx4 v[10:13], v[18:19], off
	global_load_dwordx4 v[14:17], v[20:21], off
	v_add_u32_e32 v18, 0x800, v38
	v_ashrrev_i32_e32 v49, 6, v18
	v_add_u32_e32 v18, s20, v49
	v_ashrrev_i32_e32 v19, 31, v18
	v_lshlrev_b64 v[18:19], 13, v[18:19]
	v_lshl_add_u64 v[28:29], v[26:27], 0, v[18:19]
	v_add_u32_e32 v18, 0xa00, v38
	v_ashrrev_i32_e32 v50, 6, v18
	v_add_u32_e32 v18, s20, v50
	v_ashrrev_i32_e32 v19, 31, v18
	v_lshlrev_b64 v[18:19], 13, v[18:19]
	s_waitcnt vmcnt(8)
	v_lshl_add_u64 v[30:31], v[26:27], 0, v[18:19]
	global_load_dwordx4 v[18:21], v[28:29], off
	global_load_dwordx4 v[22:25], v[30:31], off
	v_add_u32_e32 v28, 0xc00, v38
	v_ashrrev_i32_e32 v51, 6, v28
	v_add_u32_e32 v28, s20, v51
	v_ashrrev_i32_e32 v29, 31, v28
	v_lshlrev_b64 v[28:29], 13, v[28:29]
	v_lshl_add_u64 v[36:37], v[26:27], 0, v[28:29]
	v_add_u32_e32 v28, 0xe00, v38
	v_ashrrev_i32_e32 v52, 6, v28
	v_add_u32_e32 v28, s20, v52
	v_ashrrev_i32_e32 v29, 31, v28
	v_lshlrev_b64 v[28:29], 13, v[28:29]
	v_lshl_add_u64 v[40:41], v[26:27], 0, v[28:29]
	global_load_dwordx4 v[26:29], v[36:37], off
	global_load_dwordx4 v[30:33], v[40:41], off
	v_add_u32_e32 v68, 0, v34
	v_lshl_add_u64 v[36:37], s[6:7], 0, v[34:35]
	v_lshlrev_b32_e32 v34, 3, v38
	v_ashrrev_i32_e32 v53, 3, v38
	v_and_b32_e32 v38, 56, v34
	v_mul_u32_u24_e32 v38, 0x404, v38
	v_bfe_u32 v54, v34, 5, 1
	v_lshlrev_b32_e32 v34, 2, v53
	v_add3_u32 v55, 0, v38, v34
	v_lshrrev_b32_e32 v34, 1, v53
	v_and_b32_e32 v38, 3, v53
	v_and_or_b32 v41, v34, 12, v38
	v_lshlrev_b32_e32 v34, 7, v53
	v_and_b32_e32 v34, 0x4000, v34
	v_and_b32_e32 v40, 48, v39
	v_lshl_add_u64 v[38:39], s[4:5], 0, v[34:35]
	v_lshlrev_b32_e32 v34, 6, v41
	v_lshlrev_b32_e32 v41, 1, v53
	v_add_u32_e32 v56, 64, v53
	v_and_b32_e32 v71, 32, v41
	v_or_b32_e32 v70, v34, v40
	v_bitop3_b32 v60, v34, v71, v40 bitop3:0x36
	v_and_b32_e32 v34, 0x60, v56
	v_lshlrev_b32_e32 v40, 2, v56
	v_and_or_b32 v42, v40, 16, v34
	v_lshlrev_b32_e32 v34, 7, v56
	v_and_b32_e32 v34, 0x4000, v34
	v_lshl_add_u64 v[40:41], s[4:5], 0, v[34:35]
	v_lshrrev_b32_e32 v34, 3, v42
	v_or_b32_e32 v34, v34, v54
	v_lshlrev_b32_e32 v34, 10, v34
	v_add_u32_e32 v57, 0x80, v53
	v_bitop3_b32 v34, v34, v70, v71 bitop3:0xf6
	v_and_b32_e32 v59, 0x60, v53
	v_lshl_add_u64 v[40:41], v[40:41], 0, v[34:35]
	v_lshlrev_b32_e32 v34, 2, v57
	v_and_or_b32 v44, v34, 16, v59
	v_lshlrev_b32_e32 v34, 7, v57
	v_and_b32_e32 v34, 0x4000, v34
	v_lshl_add_u64 v[42:43], s[4:5], 0, v[34:35]
	v_lshrrev_b32_e32 v34, 3, v44
	v_or_b32_e32 v34, v34, v54
	v_lshlrev_b32_e32 v34, 10, v34
	v_add_u32_e32 v58, 0xc0, v53
	v_bitop3_b32 v34, v34, v70, v71 bitop3:0xf6
	v_lshl_add_u64 v[42:43], v[42:43], 0, v[34:35]
	v_and_b32_e32 v34, 0x60, v58
	v_lshlrev_b32_e32 v44, 2, v58
	v_and_or_b32 v72, v44, 16, v34
	v_lshlrev_b32_e32 v34, 7, v58
	v_and_b32_e32 v34, 0x4000, v34
	v_lshl_add_u64 v[44:45], s[4:5], 0, v[34:35]
	v_lshrrev_b32_e32 v34, 3, v72
	v_or_b32_e32 v34, v34, v54
	s_movk_i32 s6, 0x404
	v_lshlrev_b32_e32 v34, 10, v34
	v_mul_lo_u32 v61, v1, s6
	v_mul_lo_u32 v62, v46, s6
	v_mul_lo_u32 v63, v47, s6
	v_mul_lo_u32 v64, v48, s6
	v_mul_lo_u32 v65, v49, s6
	v_mul_lo_u32 v66, v50, s6
	v_mul_lo_u32 v67, v51, s6
	v_mul_lo_u32 v69, v52, s6
	v_bitop3_b32 v34, v34, v70, v71 bitop3:0xf6
	v_lshl_add_u64 v[44:45], v[44:45], 0, v[34:35]
	v_add_u32_e32 v61, v68, v61
	v_add_u32_e32 v62, v68, v62
	v_add_u32_e32 v63, v68, v63
	v_add_u32_e32 v64, v68, v64
	v_add_u32_e32 v65, v68, v65
	v_add_u32_e32 v66, v68, v66
	v_add_u32_e32 v67, v68, v67
	v_add_u32_e32 v68, v68, v69
	s_waitcnt vmcnt(0)
	s_branch .LBB0_45

; __device__ __forceinline__ void convert_t(const float* __restrict__ W, int K, int N, bf16_t* __restrict__ Wt, int swiglu, int& cursor, float* tile, int perm) {
;     ...
;     for (; id < last; id += G) {
;         const int tl = (id - first) % nt; const int k0 = (tl / ntn) * 64, n0 = (tl % ntn) * 256;
; #pragma unroll
;         for (int i = 0; i < 8; ++i) { const int idx = tid + 512 * i; const int row = idx >> 6, c4 = idx & 63; float* d = tile + row * 257 + 4 * c4; d[0] = v[i].x; d[1] = v[i].y; d[2] = v[i].z; d[3] = v[i].w; }
;         __syncthreads();
;         if (id + G < last) { const int tl2 = (id + G - first) % nt; const int k2 = (tl2 / ntn) * 64, n2 = (tl2 % ntn) * 256;
; #pragma unroll
;             for (int i = 0; i < 8; ++i) { const int idx = tid + 512 * i; const int row = idx >> 6, c4 = idx & 63; v[i] = *(const float4*)(W + (size_t)(k2 + row) * N + n2 + 4 * c4); } }
.LBB0_45:
	s_add_i32 s18, s14, s15
	s_add_i32 s4, s18, 0x1630
	s_cmpk_gt_i32 s4, 0x18df
	s_cselect_b64 s[4:5], -1, 0
	s_and_b64 vcc, exec, s[4:5]
	s_waitcnt vmcnt(11)
	ds_write2_b32 v61, v2, v3 offset1:1
	ds_write2_b32 v61, v4, v5 offset0:2 offset1:3
	s_waitcnt vmcnt(10)
	ds_write2_b32 v62, v6, v7 offset1:1
	ds_write2_b32 v62, v8, v9 offset0:2 offset1:3
	s_waitcnt vmcnt(9)
	ds_write2_b32 v63, v10, v11 offset1:1
	ds_write2_b32 v63, v12, v13 offset0:2 offset1:3
	s_waitcnt vmcnt(8)
	ds_write2_b32 v64, v14, v15 offset1:1
	ds_write2_b32 v64, v16, v17 offset0:2 offset1:3
	s_waitcnt vmcnt(7)
	ds_write2_b32 v65, v18, v19 offset1:1
	ds_write2_b32 v65, v20, v21 offset0:2 offset1:3
	s_waitcnt vmcnt(6)
	ds_write2_b32 v66, v22, v23 offset1:1
	ds_write2_b32 v66, v24, v25 offset0:2 offset1:3
	s_waitcnt vmcnt(5)
	ds_write2_b32 v67, v26, v27 offset1:1
	ds_write2_b32 v67, v28, v29 offset0:2 offset1:3
	s_waitcnt vmcnt(4)
	ds_write2_b32 v68, v30, v31 offset1:1
	ds_write2_b32 v68, v32, v33 offset0:2 offset1:3
	s_waitcnt lgkmcnt(0)
	s_barrier
	s_cbranch_vccnz .LBB0_44
	s_mul_hi_i32 s6, s18, 0x2fa0be83
	s_lshr_b32 s7, s6, 31
	s_ashr_i32 s6, s6, 7
	s_add_i32 s6, s6, s7
	s_mulk_i32 s6, 0x2b0
	s_sub_i32 s6, s18, s6
	s_sext_i32_i16 s7, s6
	s_bfe_u32 s7, s7, 0x3001c
	s_add_i32 s7, s6, s7
	s_sext_i32_i16 s19, s7
	s_and_b32 s7, s7, 0xfff8
	s_lshl_b32 s19, s19, 3
	s_sub_i32 s6, s6, s7
	s_andn2_b32 s19, s19, 63
	s_sext_i32_i16 s6, s6
	s_lshl_b32 s6, s6, 8
	v_add_u32_e32 v2, s19, v1
	s_ashr_i32 s7, s6, 31
	v_ashrrev_i32_e32 v3, 31, v2
	v_lshl_add_u64 v[26:27], s[6:7], 2, v[36:37]
	v_lshlrev_b64 v[2:3], 13, v[2:3]
	v_lshl_add_u64 v[10:11], v[26:27], 0, v[2:3]
	v_add_u32_e32 v2, s19, v46
	v_ashrrev_i32_e32 v3, 31, v2
	v_lshlrev_b64 v[2:3], 13, v[2:3]
	v_lshl_add_u64 v[12:13], v[26:27], 0, v[2:3]
	global_load_dwordx4 v[2:5], v[10:11], off
	global_load_dwordx4 v[6:9], v[12:13], off
	v_add_u32_e32 v10, s19, v47
	v_ashrrev_i32_e32 v11, 31, v10
	v_lshlrev_b64 v[10:11], 13, v[10:11]
	v_lshl_add_u64 v[18:19], v[26:27], 0, v[10:11]
	v_add_u32_e32 v10, s19, v48
	v_ashrrev_i32_e32 v11, 31, v10
	v_lshlrev_b64 v[10:11], 13, v[10:11]
	v_lshl_add_u64 v[20:21], v[26:27], 0, v[10:11]
	global_load_dwordx4 v[10:13], v[18:19], off
	global_load_dwordx4 v[14:17], v[20:21], off
	v_add_u32_e32 v18, s19, v49
	v_ashrrev_i32_e32 v19, 31, v18
	v_lshlrev_b64 v[18:19], 13, v[18:19]
	v_lshl_add_u64 v[28:29], v[26:27], 0, v[18:19]
	v_add_u32_e32 v18, s19, v50
	v_ashrrev_i32_e32 v19, 31, v18
	v_lshlrev_b64 v[18:19], 13, v[18:19]
	v_lshl_add_u64 v[30:31], v[26:27], 0, v[18:19]
	global_load_dwordx4 v[18:21], v[28:29], off
	global_load_dwordx4 v[22:25], v[30:31], off
	v_add_u32_e32 v28, s19, v51
	v_ashrrev_i32_e32 v29, 31, v28
	v_lshlrev_b64 v[28:29], 13, v[28:29]
	v_lshl_add_u64 v[70:71], v[26:27], 0, v[28:29]
	v_add_u32_e32 v28, s19, v52
	v_ashrrev_i32_e32 v29, 31, v28
	v_lshlrev_b64 v[28:29], 13, v[28:29]
	v_lshl_add_u64 v[72:73], v[26:27], 0, v[28:29]
	global_load_dwordx4 v[26:29], v[70:71], off
	global_load_dwordx4 v[30:33], v[72:73], off
	s_branch .LBB0_44

; __device__ __forceinline__ unsigned cvt_pk_bf16(float lo, float hi) { unsigned r; asm volatile("v_cvt_pk_bf16_f32 %0, %1, %2" : "=v"(r) : "v"(lo), "v"(hi)); return r; }
; __device__ __forceinline__ void convert_t(const float* __restrict__ W, int K, int N, bf16_t* __restrict__ Wt, int swiglu, int& cursor, float* tile, int perm) {
;     ...
;     const int tid = tix_, G = gdim_; const int ntn = N / 256, nt = (K / 64) * ntn;
;     const int first = cursor; cursor += nt;
;     int id = first + (((int)bid_ - (first % G)) + G) % G;
;     const int last = first + nt * CONV_REP;
;     float4 v[8];
;     if (id < last) { const int tl = (id - first) % nt; const int k0 = (tl / ntn) * 64, n0 = (tl % ntn) * 256;
; #pragma unroll
;         for (int i = 0; i < 8; ++i) { const int idx = tid + 512 * i; const int row = idx >> 6, c4 = idx & 63; v[i] = *(const float4*)(W + (size_t)(k0 + row) * N + n0 + 4 * c4); } }
;     ...
;         for (int p = 0; p < 4; ++p) { const int nl = (tid >> 3) + 64 * p, kq = tid & 7; const float* s = tile + (8 * kq) * 257 + nl;
;             u32x4 w; w.x = cvt_pk_bf16(s[0], s[257]); w.y = cvt_pk_bf16(s[2 * 257], s[3 * 257]); w.z = cvt_pk_bf16(s[4 * 257], s[5 * 257]); w.w = cvt_pk_bf16(s[6 * 257], s[7 * 257]);
;             int n = n0 + nl; if (swiglu) { const int half = n >= DFF ? 1 : 0; const int c = n - half * DFF; n = (c >> 7) * 256 + half * 128 + (c & 127); }
;             { const int pn = n >> 8, half = (n >> 7) & 1, r = n & 127, c5 = r & 31;
;               const int R = perm ? ((r & ~31) + 16 * ((c5 >> 2) & 1) + 4 * (c5 >> 3) + (c5 & 3)) : r;
;               *(u32x4*)((unsigned char*)Wt + ((size_t)pn * (K >> 6) + (k0 >> 6)) * 32768 + half * 16384 + pg8::lds_byte(R, 8 * kq)) = w; } }
.LBB0_1037:
	s_or_b64 exec, exec, s[4:5]
	s_mov_b64 s[30:31], s[0:1]
	s_waitcnt lgkmcnt(0)
	s_barrier
	s_load_dwordx8 s[8:15], s[30:31], 0x8
	s_load_dwordx2 s[28:29], s[30:31], 0x30
	s_load_dwordx2 s[26:27], s[30:31], 0x48
	s_load_dwordx8 s[16:23], s[30:31], 0x60
	s_load_dwordx4 s[4:7], s[30:31], 0x88
	s_load_dwordx2 s[24:25], s[30:31], 0xa8
	s_mov_b32 s30, s40
	s_mov_b32 s31, s2
	s_mov_b32 s30, s2
	s_mov_b32 s36, s40
	s_abs_i32 s31, s36
	v_cvt_f32_u32_e32 v0, s31
	s_sub_i32 s38, 0, s31
	s_add_i32 s30, s36, s30
	s_ashr_i32 s37, s30, 31
	v_rcp_iflag_f32_e32 v0, v0
	s_abs_i32 s30, s30
	v_mov_b32_e32 v36, v228
	v_mul_f32_e32 v0, 0x4f7ffffe, v0
	v_cvt_u32_f32_e32 v0, v0
	s_nop 0
	v_readfirstlane_b32 s39, v0
	s_mul_i32 s38, s38, s39
	s_mul_hi_u32 s38, s39, s38
	s_add_i32 s39, s39, s38
	s_mul_hi_u32 s38, s30, s39
	s_mul_i32 s38, s38, s31
	s_sub_i32 s30, s30, s38
	s_sub_i32 s38, s30, s31
	s_cmp_ge_u32 s30, s31
	s_cselect_b32 s30, s38, s30
	s_sub_i32 s38, s30, s31
	s_cmp_ge_u32 s30, s31
	s_cselect_b32 s30, s38, s30
	s_xor_b32 s30, s30, s37
	s_sub_i32 s30, s30, s37
	s_cmpk_gt_i32 s30, 0x55f
	s_cbranch_scc1 .LBB0_1042
	s_waitcnt lgkmcnt(0)
	s_add_u32 s12, s12, 0x5600000
	s_mul_hi_i32 s31, s30, 0x2fa0be83
	s_addc_u32 s13, s13, 0
	s_lshr_b32 s37, s31, 31
	s_ashr_i32 s31, s31, 8
	s_add_i32 s31, s31, s37
	s_mulk_i32 s31, 0x560
	s_sub_i32 s31, s30, s31
	s_sext_i32_i16 s37, s31
	s_mulk_i32 s37, 0x2fa1
	s_lshr_b32 s38, s37, 31
	s_ashr_i32 s37, s37, 19
	s_add_i32 s37, s37, s38
	s_sext_i32_i16 s38, s37
	s_mul_i32 s37, s37, 43
	s_sub_i32 s31, s31, s37
	s_sext_i32_i16 s31, s31
	s_lshl_b32 s46, s38, 6
	s_lshl_b32 s38, s31, 8
	s_ashr_i32 s39, s38, 31
	s_lshl_b64 s[38:39], s[38:39], 2
	s_add_u32 s38, s12, s38
	v_lshlrev_b32_e32 v37, 4, v36
	s_addc_u32 s39, s13, s39
	v_and_b32_e32 v32, 0x3f0, v37
	v_mov_b32_e32 v33, 0
	v_ashrrev_i32_e32 v42, 6, v36
	v_lshl_add_u64 v[24:25], s[38:39], 0, v[32:33]
	v_add_u32_e32 v0, s46, v42
	s_mov_b32 s37, 0xac00
	v_mad_i64_i32 v[8:9], s[38:39], v0, s37, v[24:25]
	v_add_u32_e32 v0, 0x200, v36
	v_ashrrev_i32_e32 v43, 6, v0
	v_add_u32_e32 v0, s46, v43
	v_mad_i64_i32 v[10:11], s[38:39], v0, s37, v[24:25]
	global_load_dwordx4 v[0:3], v[8:9], off
	global_load_dwordx4 v[4:7], v[10:11], off
	v_add_u32_e32 v8, 0x400, v36
	v_ashrrev_i32_e32 v44, 6, v8
	v_add_u32_e32 v8, s46, v44
	v_mad_i64_i32 v[16:17], s[38:39], v8, s37, v[24:25]
	v_add_u32_e32 v8, 0x600, v36
	v_ashrrev_i32_e32 v45, 6, v8
	v_add_u32_e32 v8, s46, v45
	v_mad_i64_i32 v[18:19], s[38:39], v8, s37, v[24:25]
	global_load_dwordx4 v[8:11], v[16:17], off
	global_load_dwordx4 v[12:15], v[18:19], off
	v_add_u32_e32 v16, 0x800, v36
	v_ashrrev_i32_e32 v46, 6, v16
	v_add_u32_e32 v16, s46, v46
	v_mad_i64_i32 v[26:27], s[38:39], v16, s37, v[24:25]
	v_add_u32_e32 v16, 0xa00, v36
	v_ashrrev_i32_e32 v47, 6, v16
	v_add_u32_e32 v16, s46, v47
	v_mad_i64_i32 v[28:29], s[38:39], v16, s37, v[24:25]
	global_load_dwordx4 v[16:19], v[26:27], off
	global_load_dwordx4 v[20:23], v[28:29], off
	v_add_u32_e32 v26, 0xc00, v36
	v_ashrrev_i32_e32 v48, 6, v26
	v_add_u32_e32 v26, s46, v48
	v_mad_i64_i32 v[34:35], s[38:39], v26, s37, v[24:25]
	v_add_u32_e32 v26, 0xe00, v36
	v_ashrrev_i32_e32 v49, 6, v26
	v_add_u32_e32 v26, s46, v49
	v_mad_i64_i32 v[38:39], s[38:39], v26, s37, v[24:25]
	global_load_dwordx4 v[24:27], v[34:35], off
	global_load_dwordx4 v[28:31], v[38:39], off
	v_add_u32_e32 v61, 0, v32
	v_lshl_add_u64 v[34:35], s[12:13], 0, v[32:33]
	v_lshlrev_b32_e32 v32, 3, v36
	v_ashrrev_i32_e32 v50, 3, v36
	v_and_b32_e32 v36, 56, v32
	v_mul_u32_u24_e32 v36, 0x404, v36
	v_lshlrev_b32_e32 v38, 2, v50
	v_add3_u32 v51, 0, v36, v38
	v_and_b32_e32 v36, 0x60, v50
	v_and_or_b32 v36, v38, 16, v36
	v_lshrrev_b32_e32 v38, 1, v50
	v_and_b32_e32 v39, 3, v50
	v_and_b32_e32 v37, 48, v37
	v_add_u32_e32 v52, 64, v50
	v_add_u32_e32 v53, 0xc0, v50
	v_and_or_b32 v38, v38, 12, v39
	v_lshl_or_b32 v40, v38, 6, v37
	v_and_b32_e32 v38, 0x60, v52
	v_lshlrev_b32_e32 v39, 2, v52
	v_and_b32_e32 v63, 0x60, v53
	v_lshlrev_b32_e32 v64, 2, v53
	v_and_or_b32 v38, v39, 16, v38
	v_and_or_b32 v63, v64, 16, v63
	v_bfe_u32 v32, v32, 5, 1
	v_lshrrev_b32_e32 v36, 3, v36
	v_lshrrev_b32_e32 v38, 3, v38
	v_lshrrev_b32_e32 v63, 3, v63
	s_movk_i32 s12, 0x404
	v_or_b32_e32 v36, v36, v32
	v_lshlrev_b32_e32 v37, 1, v50
	v_or_b32_e32 v38, v38, v32
	v_or_b32_e32 v32, v63, v32
	v_mul_lo_u32 v54, v42, s12
	v_mul_lo_u32 v55, v43, s12
	v_mul_lo_u32 v56, v44, s12
	v_mul_lo_u32 v57, v45, s12
	v_mul_lo_u32 v58, v46, s12
	v_mul_lo_u32 v59, v47, s12
	v_mul_lo_u32 v60, v48, s12
	v_mul_lo_u32 v62, v49, s12
	v_lshlrev_b32_e32 v36, 10, v36
	v_and_b32_e32 v41, 32, v37
	v_lshlrev_b32_e32 v38, 10, v38
	v_lshlrev_b32_e32 v32, 10, v32
	v_bitop3_b32 v36, v36, v40, v41 bitop3:0xf6
	v_mov_b32_e32 v37, v33
	v_bitop3_b32 v38, v38, v40, v41 bitop3:0xf6
	v_mov_b32_e32 v39, v33
	v_bitop3_b32 v40, v32, v40, v41 bitop3:0xf6
	v_mov_b32_e32 v41, v33
	v_add_u32_e32 v54, v61, v54
	v_add_u32_e32 v55, v61, v55
	v_add_u32_e32 v56, v61, v56
	v_add_u32_e32 v57, v61, v57
	v_add_u32_e32 v58, v61, v58
	v_add_u32_e32 v59, v61, v59
	v_add_u32_e32 v60, v61, v60
	v_add_u32_e32 v61, v61, v62
	s_movk_i32 s38, 0x157f
	v_mov_b32_e32 v62, 0xffffea80
	v_mov_b32_e32 v63, 0x4000
	s_waitcnt vmcnt(0)
	s_branch .LBB0_1040

; __device__ __forceinline__ void convert_t(const float* __restrict__ W, int K, int N, bf16_t* __restrict__ Wt, int swiglu, int& cursor, float* tile, int perm) {
;     ...
;     for (; id < last; id += G) {
;         const int tl = (id - first) % nt; const int k0 = (tl / ntn) * 64, n0 = (tl % ntn) * 256;
; #pragma unroll
;         for (int i = 0; i < 8; ++i) { const int idx = tid + 512 * i; const int row = idx >> 6, c4 = idx & 63; float* d = tile + row * 257 + 4 * c4; d[0] = v[i].x; d[1] = v[i].y; d[2] = v[i].z; d[3] = v[i].w; }
;         __syncthreads();
;         if (id + G < last) { const int tl2 = (id + G - first) % nt; const int k2 = (tl2 / ntn) * 64, n2 = (tl2 % ntn) * 256;
; #pragma unroll
;             for (int i = 0; i < 8; ++i) { const int idx = tid + 512 * i; const int row = idx >> 6, c4 = idx & 63; v[i] = *(const float4*)(W + (size_t)(k2 + row) * N + n2 + 4 * c4); } }
.LBB0_1040:
	s_add_i32 s39, s30, s36
	s_cmpk_gt_i32 s39, 0x55f
	s_cselect_b64 s[12:13], -1, 0
	s_and_b64 vcc, exec, s[12:13]
	s_waitcnt vmcnt(11)
	ds_write2_b32 v54, v0, v1 offset1:1
	ds_write2_b32 v54, v2, v3 offset0:2 offset1:3
	s_waitcnt vmcnt(10)
	ds_write2_b32 v55, v4, v5 offset1:1
	ds_write2_b32 v55, v6, v7 offset0:2 offset1:3
	s_waitcnt vmcnt(9)
	ds_write2_b32 v56, v8, v9 offset1:1
	ds_write2_b32 v56, v10, v11 offset0:2 offset1:3
	s_waitcnt vmcnt(8)
	ds_write2_b32 v57, v12, v13 offset1:1
	ds_write2_b32 v57, v14, v15 offset0:2 offset1:3
	s_waitcnt vmcnt(7)
	ds_write2_b32 v58, v16, v17 offset1:1
	ds_write2_b32 v58, v18, v19 offset0:2 offset1:3
	s_waitcnt vmcnt(6)
	ds_write2_b32 v59, v20, v21 offset1:1
	ds_write2_b32 v59, v22, v23 offset0:2 offset1:3
	s_waitcnt vmcnt(5)
	ds_write2_b32 v60, v24, v25 offset1:1
	ds_write2_b32 v60, v26, v27 offset0:2 offset1:3
	s_waitcnt vmcnt(4)
	ds_write2_b32 v61, v28, v29 offset1:1
	ds_write2_b32 v61, v30, v31 offset0:2 offset1:3
	s_waitcnt lgkmcnt(0)
	s_barrier
	s_cbranch_vccnz .LBB0_1039
	s_mul_hi_i32 s31, s39, 0x2fa0be83
	s_lshr_b32 s46, s31, 31
	s_ashr_i32 s31, s31, 8
	s_add_i32 s31, s31, s46
	s_mulk_i32 s31, 0x560
	s_sub_i32 s31, s39, s31
	s_sext_i32_i16 s46, s31
	s_mulk_i32 s46, 0x2fa1
	s_lshr_b32 s47, s46, 31
	s_ashr_i32 s46, s46, 19
	s_add_i32 s46, s46, s47
	s_lshl_b32 s48, s46, 6
	s_mul_i32 s46, s46, 43
	s_sub_i32 s31, s31, s46
	s_sext_i32_i16 s31, s31
	s_lshl_b32 s46, s31, 8
	s_ashr_i32 s47, s46, 31
	v_lshl_add_u64 v[24:25], s[46:47], 2, v[34:35]
	v_add_u32_e32 v0, s48, v42
	v_mad_i64_i32 v[8:9], s[46:47], v0, s37, v[24:25]
	v_add_u32_e32 v0, s48, v43
	v_mad_i64_i32 v[10:11], s[46:47], v0, s37, v[24:25]
	global_load_dwordx4 v[0:3], v[8:9], off
	global_load_dwordx4 v[4:7], v[10:11], off
	v_add_u32_e32 v8, s48, v44
	v_mad_i64_i32 v[16:17], s[46:47], v8, s37, v[24:25]
	v_add_u32_e32 v8, s48, v45
	v_mad_i64_i32 v[18:19], s[46:47], v8, s37, v[24:25]
	global_load_dwordx4 v[8:11], v[16:17], off
	global_load_dwordx4 v[12:15], v[18:19], off
	v_add_u32_e32 v16, s48, v46
	v_mad_i64_i32 v[26:27], s[46:47], v16, s37, v[24:25]
	v_add_u32_e32 v16, s48, v47
	v_mad_i64_i32 v[28:29], s[46:47], v16, s37, v[24:25]
	global_load_dwordx4 v[16:19], v[26:27], off
	global_load_dwordx4 v[20:23], v[28:29], off
	v_add_u32_e32 v26, s48, v48
	v_mad_i64_i32 v[64:65], s[46:47], v26, s37, v[24:25]
	v_add_u32_e32 v26, s48, v49
	v_mad_i64_i32 v[66:67], s[46:47], v26, s37, v[24:25]
	global_load_dwordx4 v[24:27], v[64:65], off
	global_load_dwordx4 v[28:31], v[66:67], off
	s_branch .LBB0_1039
; __device__ __forceinline__ unsigned cvt_pk_bf16(float lo, float hi) { unsigned r; asm volatile("v_cvt_pk_bf16_f32 %0, %1, %2" : "=v"(r) : "v"(lo), "v"(hi)); return r; }
; __device__ __forceinline__ void convert_t(const float* __restrict__ W, int K, int N, bf16_t* __restrict__ Wt, int swiglu, int& cursor, float* tile, int perm) {
;     ...
;     const int tid = tix_, G = gdim_; const int ntn = N / 256, nt = (K / 64) * ntn;
;     const int first = cursor; cursor += nt;
;     int id = first + (((int)bid_ - (first % G)) + G) % G;
;     const int last = first + nt * CONV_REP;
;     float4 v[8];
;     if (id < last) { const int tl = (id - first) % nt; const int k0 = (tl / ntn) * 64, n0 = (tl % ntn) * 256;
; #pragma unroll
;         for (int i = 0; i < 8; ++i) { const int idx = tid + 512 * i; const int row = idx >> 6, c4 = idx & 63; v[i] = *(const float4*)(W + (size_t)(k0 + row) * N + n0 + 4 * c4); } }
;     ...
;         for (int p = 0; p < 4; ++p) { const int nl = (tid >> 3) + 64 * p, kq = tid & 7; const float* s = tile + (8 * kq) * 257 + nl;
;             u32x4 w; w.x = cvt_pk_bf16(s[0], s[257]); w.y = cvt_pk_bf16(s[2 * 257], s[3 * 257]); w.z = cvt_pk_bf16(s[4 * 257], s[5 * 257]); w.w = cvt_pk_bf16(s[6 * 257], s[7 * 257]);
;             int n = n0 + nl; if (swiglu) { const int half = n >= DFF ? 1 : 0; const int c = n - half * DFF; n = (c >> 7) * 256 + half * 128 + (c & 127); }
;             { const int pn = n >> 8, half = (n >> 7) & 1, r = n & 127, c5 = r & 31;
;               const int R = perm ? ((r & ~31) + 16 * ((c5 >> 2) & 1) + 4 * (c5 >> 3) + (c5 & 3)) : r;
;               *(u32x4*)((unsigned char*)Wt + ((size_t)pn * (K >> 6) + (k0 >> 6)) * 32768 + half * 16384 + pg8::lds_byte(R, 8 * kq)) = w; } }
.LBB0_1042:
	s_waitcnt lgkmcnt(0)
	s_mov_b32 s12, s2
	s_mov_b32 s30, s40
	s_abs_i32 s13, s30
	s_waitcnt vmcnt(11)
	v_cvt_f32_u32_e32 v0, s13
	s_sub_i32 s31, 0, s13
	v_mov_b32_e32 v36, v228
	v_rcp_iflag_f32_e32 v0, v0
	s_nop 0
	v_mul_f32_e32 v0, 0x4f7ffffe, v0
	v_cvt_u32_f32_e32 v0, v0
	s_nop 0
	v_readfirstlane_b32 s36, v0
	s_mul_i32 s31, s31, s36
	s_mul_hi_u32 s31, s36, s31
	s_add_i32 s36, s36, s31
	s_mul_hi_u32 s31, s36, 0x560
	s_mul_i32 s31, s31, s13
	s_sub_i32 s31, 0x560, s31
	s_sub_i32 s37, s31, s13
	s_cmp_ge_u32 s31, s13
	s_cselect_b32 s31, s37, s31
	s_sub_i32 s37, s31, s13
	s_cmp_ge_u32 s31, s13
	s_cselect_b32 s31, s37, s31
	s_add_i32 s12, s30, s12
	s_sub_i32 s12, s12, s31
	s_ashr_i32 s31, s12, 31
	s_abs_i32 s12, s12
	s_mul_hi_u32 s36, s12, s36
	s_mul_i32 s36, s36, s13
	s_sub_i32 s12, s12, s36
	s_sub_i32 s36, s12, s13
	s_cmp_ge_u32 s12, s13
	s_cselect_b32 s12, s36, s12
	s_sub_i32 s36, s12, s13
	s_cmp_ge_u32 s12, s13
	s_cselect_b32 s12, s36, s12
	s_xor_b32 s12, s12, s31
	s_sub_i32 s31, s12, s31
	s_cmpk_gt_i32 s31, 0x2af
	s_cbranch_scc1 .LBB0_1047
	s_add_u32 s12, s24, 0x2b00000
	s_addc_u32 s13, s25, 0
	s_add_u32 s14, s14, 0x2b00000
	s_mul_hi_i32 s36, s31, 0x2fa0be83
	s_addc_u32 s15, s15, 0
	s_lshr_b32 s37, s36, 31
	s_ashr_i32 s36, s36, 7
	s_add_i32 s36, s36, s37
	s_mulk_i32 s36, 0x2b0
	s_sub_i32 s36, s31, s36
	s_sext_i32_i16 s37, s36
	s_bfe_u32 s37, s37, 0x3001c
	s_add_i32 s37, s36, s37
	s_sext_i32_i16 s38, s37
	s_and_b32 s37, s37, 0xfff8
	s_sub_i32 s36, s36, s37
	s_sext_i32_i16 s36, s36
	s_lshl_b32 s36, s36, 8
	s_lshl_b32 s38, s38, 3
	s_ashr_i32 s37, s36, 31
	s_andn2_b32 s38, s38, 63
	s_lshl_b64 s[36:37], s[36:37], 2
	v_ashrrev_i32_e32 v44, 6, v36
	s_add_u32 s36, s14, s36
	v_lshlrev_b32_e32 v37, 4, v36
	v_add_u32_e32 v0, s38, v44
	s_addc_u32 s37, s15, s37
	v_and_b32_e32 v32, 0x3f0, v37
	v_mov_b32_e32 v33, 0
	v_ashrrev_i32_e32 v1, 31, v0
	s_waitcnt vmcnt(5)
	v_lshl_add_u64 v[24:25], s[36:37], 0, v[32:33]
	v_lshlrev_b64 v[0:1], 13, v[0:1]
	v_lshl_add_u64 v[8:9], v[24:25], 0, v[0:1]
	v_add_u32_e32 v0, 0x200, v36
	v_ashrrev_i32_e32 v45, 6, v0
	v_add_u32_e32 v0, s38, v45
	v_ashrrev_i32_e32 v1, 31, v0
	v_lshlrev_b64 v[0:1], 13, v[0:1]
	v_lshl_add_u64 v[10:11], v[24:25], 0, v[0:1]
	global_load_dwordx4 v[0:3], v[8:9], off
	global_load_dwordx4 v[4:7], v[10:11], off
	v_add_u32_e32 v8, 0x400, v36
	v_ashrrev_i32_e32 v46, 6, v8
	v_add_u32_e32 v8, s38, v46
	v_ashrrev_i32_e32 v9, 31, v8
	v_lshlrev_b64 v[8:9], 13, v[8:9]
	v_lshl_add_u64 v[16:17], v[24:25], 0, v[8:9]
	v_add_u32_e32 v8, 0x600, v36
	v_ashrrev_i32_e32 v47, 6, v8
	v_add_u32_e32 v8, s38, v47
	v_ashrrev_i32_e32 v9, 31, v8
	v_lshlrev_b64 v[8:9], 13, v[8:9]
	v_lshl_add_u64 v[18:19], v[24:25], 0, v[8:9]
	global_load_dwordx4 v[8:11], v[16:17], off
	global_load_dwordx4 v[12:15], v[18:19], off
	v_add_u32_e32 v16, 0x800, v36
	v_ashrrev_i32_e32 v48, 6, v16
	v_add_u32_e32 v16, s38, v48
	v_ashrrev_i32_e32 v17, 31, v16
	v_lshlrev_b64 v[16:17], 13, v[16:17]
	v_lshl_add_u64 v[26:27], v[24:25], 0, v[16:17]
	v_add_u32_e32 v16, 0xa00, v36
	v_ashrrev_i32_e32 v49, 6, v16
	v_add_u32_e32 v16, s38, v49
	v_ashrrev_i32_e32 v17, 31, v16
	v_lshlrev_b64 v[16:17], 13, v[16:17]
	s_waitcnt vmcnt(8)
	v_lshl_add_u64 v[28:29], v[24:25], 0, v[16:17]
	global_load_dwordx4 v[16:19], v[26:27], off
	global_load_dwordx4 v[20:23], v[28:29], off
	v_add_u32_e32 v26, 0xc00, v36
	v_ashrrev_i32_e32 v50, 6, v26
	v_add_u32_e32 v26, s38, v50
	v_ashrrev_i32_e32 v27, 31, v26
	v_lshlrev_b64 v[26:27], 13, v[26:27]
	v_lshl_add_u64 v[34:35], v[24:25], 0, v[26:27]
	v_add_u32_e32 v26, 0xe00, v36
	v_ashrrev_i32_e32 v51, 6, v26
	v_add_u32_e32 v26, s38, v51
	v_ashrrev_i32_e32 v27, 31, v26
	v_lshlrev_b64 v[26:27], 13, v[26:27]
	v_lshl_add_u64 v[38:39], v[24:25], 0, v[26:27]
	global_load_dwordx4 v[24:27], v[34:35], off
	global_load_dwordx4 v[28:31], v[38:39], off
	v_add_u32_e32 v67, 0, v32
	v_lshl_add_u64 v[34:35], s[14:15], 0, v[32:33]
	v_lshlrev_b32_e32 v32, 3, v36
	v_ashrrev_i32_e32 v52, 3, v36
	v_and_b32_e32 v36, 56, v32
	v_mul_u32_u24_e32 v36, 0x404, v36
	v_bfe_u32 v53, v32, 5, 1
	v_lshlrev_b32_e32 v32, 2, v52
	v_add3_u32 v54, 0, v36, v32
	v_lshrrev_b32_e32 v32, 1, v52
	v_and_b32_e32 v36, 3, v52
	v_and_or_b32 v39, v32, 12, v36
	v_lshlrev_b32_e32 v32, 7, v52
	v_and_b32_e32 v32, 0x4000, v32
	v_and_b32_e32 v38, 48, v37
	v_lshl_add_u64 v[36:37], s[12:13], 0, v[32:33]
	v_lshlrev_b32_e32 v32, 6, v39
	v_lshlrev_b32_e32 v39, 1, v52
	v_add_u32_e32 v55, 64, v52
	v_and_b32_e32 v70, 32, v39
	v_or_b32_e32 v69, v32, v38
	v_bitop3_b32 v59, v32, v70, v38 bitop3:0x36
	v_and_b32_e32 v32, 0x60, v55
	v_lshlrev_b32_e32 v38, 2, v55
	v_and_or_b32 v40, v38, 16, v32
	v_lshlrev_b32_e32 v32, 7, v55
	v_and_b32_e32 v32, 0x4000, v32
	v_lshl_add_u64 v[38:39], s[12:13], 0, v[32:33]
	v_lshrrev_b32_e32 v32, 3, v40
	v_or_b32_e32 v32, v32, v53
	v_lshlrev_b32_e32 v32, 10, v32
	v_add_u32_e32 v56, 0x80, v52
	v_bitop3_b32 v32, v32, v69, v70 bitop3:0xf6
	v_and_b32_e32 v58, 0x60, v52
	v_lshl_add_u64 v[38:39], v[38:39], 0, v[32:33]
	v_lshlrev_b32_e32 v32, 2, v56
	v_and_or_b32 v42, v32, 16, v58
	v_lshlrev_b32_e32 v32, 7, v56
	v_and_b32_e32 v32, 0x4000, v32
	v_lshl_add_u64 v[40:41], s[12:13], 0, v[32:33]
	v_lshrrev_b32_e32 v32, 3, v42
	v_or_b32_e32 v32, v32, v53
	v_lshlrev_b32_e32 v32, 10, v32
	v_add_u32_e32 v57, 0xc0, v52
	v_bitop3_b32 v32, v32, v69, v70 bitop3:0xf6
	v_lshl_add_u64 v[40:41], v[40:41], 0, v[32:33]
	v_and_b32_e32 v32, 0x60, v57
	v_lshlrev_b32_e32 v42, 2, v57
	v_and_or_b32 v71, v42, 16, v32
	v_lshlrev_b32_e32 v32, 7, v57
	v_and_b32_e32 v32, 0x4000, v32
	v_lshl_add_u64 v[42:43], s[12:13], 0, v[32:33]
	v_lshrrev_b32_e32 v32, 3, v71
	v_or_b32_e32 v32, v32, v53
	s_movk_i32 s14, 0x404
	v_lshlrev_b32_e32 v32, 10, v32
	v_mul_lo_u32 v60, v44, s14
	v_mul_lo_u32 v61, v45, s14
	v_mul_lo_u32 v62, v46, s14
	v_mul_lo_u32 v63, v47, s14
	v_mul_lo_u32 v64, v48, s14
	v_mul_lo_u32 v65, v49, s14
	v_mul_lo_u32 v66, v50, s14
	v_mul_lo_u32 v68, v51, s14
	v_bitop3_b32 v32, v32, v69, v70 bitop3:0xf6
	v_lshl_add_u64 v[42:43], v[42:43], 0, v[32:33]
	v_add_u32_e32 v60, v67, v60
	v_add_u32_e32 v61, v67, v61
	v_add_u32_e32 v62, v67, v62
	v_add_u32_e32 v63, v67, v63
	v_add_u32_e32 v64, v67, v64
	v_add_u32_e32 v65, v67, v65
	v_add_u32_e32 v66, v67, v66
	v_add_u32_e32 v67, v67, v68
	s_waitcnt vmcnt(0)
	s_branch .LBB0_1045

; __device__ __forceinline__ void convert_t(const float* __restrict__ W, int K, int N, bf16_t* __restrict__ Wt, int swiglu, int& cursor, float* tile, int perm) {
;     ...
;     for (; id < last; id += G) {
;         const int tl = (id - first) % nt; const int k0 = (tl / ntn) * 64, n0 = (tl % ntn) * 256;
; #pragma unroll
;         for (int i = 0; i < 8; ++i) { const int idx = tid + 512 * i; const int row = idx >> 6, c4 = idx & 63; float* d = tile + row * 257 + 4 * c4; d[0] = v[i].x; d[1] = v[i].y; d[2] = v[i].z; d[3] = v[i].w; }
;         __syncthreads();
;         if (id + G < last) { const int tl2 = (id + G - first) % nt; const int k2 = (tl2 / ntn) * 64, n2 = (tl2 % ntn) * 256;
; #pragma unroll
;             for (int i = 0; i < 8; ++i) { const int idx = tid + 512 * i; const int row = idx >> 6, c4 = idx & 63; v[i] = *(const float4*)(W + (size_t)(k2 + row) * N + n2 + 4 * c4); } }
.LBB0_1045:
	s_add_i32 s36, s30, s31
	s_add_i32 s12, s36, 0x560
	s_cmpk_gt_i32 s12, 0x80f
	s_cselect_b64 s[12:13], -1, 0
	s_and_b64 vcc, exec, s[12:13]
	s_waitcnt vmcnt(11)
	ds_write2_b32 v60, v0, v1 offset1:1
	ds_write2_b32 v60, v2, v3 offset0:2 offset1:3
	s_waitcnt vmcnt(10)
	ds_write2_b32 v61, v4, v5 offset1:1
	ds_write2_b32 v61, v6, v7 offset0:2 offset1:3
	s_waitcnt vmcnt(9)
	ds_write2_b32 v62, v8, v9 offset1:1
	ds_write2_b32 v62, v10, v11 offset0:2 offset1:3
	s_waitcnt vmcnt(8)
	ds_write2_b32 v63, v12, v13 offset1:1
	ds_write2_b32 v63, v14, v15 offset0:2 offset1:3
	s_waitcnt vmcnt(7)
	ds_write2_b32 v64, v16, v17 offset1:1
	ds_write2_b32 v64, v18, v19 offset0:2 offset1:3
	s_waitcnt vmcnt(6)
	ds_write2_b32 v65, v20, v21 offset1:1
	ds_write2_b32 v65, v22, v23 offset0:2 offset1:3
	s_waitcnt vmcnt(5)
	ds_write2_b32 v66, v24, v25 offset1:1
	ds_write2_b32 v66, v26, v27 offset0:2 offset1:3
	s_waitcnt vmcnt(4)
	ds_write2_b32 v67, v28, v29 offset1:1
	ds_write2_b32 v67, v30, v31 offset0:2 offset1:3
	s_waitcnt lgkmcnt(0)
	s_barrier
	s_cbranch_vccnz .LBB0_1044
	s_mul_hi_i32 s14, s36, 0x2fa0be83
	s_lshr_b32 s15, s14, 31
	s_ashr_i32 s14, s14, 7
	s_add_i32 s14, s14, s15
	s_mulk_i32 s14, 0x2b0
	s_sub_i32 s14, s36, s14
	s_sext_i32_i16 s15, s14
	s_bfe_u32 s15, s15, 0x3001c
	s_add_i32 s15, s14, s15
	s_sext_i32_i16 s37, s15
	s_and_b32 s15, s15, 0xfff8
	s_lshl_b32 s37, s37, 3
	s_sub_i32 s14, s14, s15
	s_andn2_b32 s37, s37, 63
	s_sext_i32_i16 s14, s14
	s_lshl_b32 s14, s14, 8
	v_add_u32_e32 v0, s37, v44
	s_ashr_i32 s15, s14, 31
	v_ashrrev_i32_e32 v1, 31, v0
	v_lshl_add_u64 v[24:25], s[14:15], 2, v[34:35]
	v_lshlrev_b64 v[0:1], 13, v[0:1]
	v_lshl_add_u64 v[8:9], v[24:25], 0, v[0:1]
	v_add_u32_e32 v0, s37, v45
	v_ashrrev_i32_e32 v1, 31, v0
	v_lshlrev_b64 v[0:1], 13, v[0:1]
	v_lshl_add_u64 v[10:11], v[24:25], 0, v[0:1]
	global_load_dwordx4 v[0:3], v[8:9], off
	global_load_dwordx4 v[4:7], v[10:11], off
	v_add_u32_e32 v8, s37, v46
	v_ashrrev_i32_e32 v9, 31, v8
	v_lshlrev_b64 v[8:9], 13, v[8:9]
	v_lshl_add_u64 v[16:17], v[24:25], 0, v[8:9]
	v_add_u32_e32 v8, s37, v47
	v_ashrrev_i32_e32 v9, 31, v8
	v_lshlrev_b64 v[8:9], 13, v[8:9]
	v_lshl_add_u64 v[18:19], v[24:25], 0, v[8:9]
	global_load_dwordx4 v[8:11], v[16:17], off
	global_load_dwordx4 v[12:15], v[18:19], off
	v_add_u32_e32 v16, s37, v48
	v_ashrrev_i32_e32 v17, 31, v16
	v_lshlrev_b64 v[16:17], 13, v[16:17]
	v_lshl_add_u64 v[26:27], v[24:25], 0, v[16:17]
	v_add_u32_e32 v16, s37, v49
	v_ashrrev_i32_e32 v17, 31, v16
	v_lshlrev_b64 v[16:17], 13, v[16:17]
	v_lshl_add_u64 v[28:29], v[24:25], 0, v[16:17]
	global_load_dwordx4 v[16:19], v[26:27], off
	global_load_dwordx4 v[20:23], v[28:29], off
	v_add_u32_e32 v26, s37, v50
	v_ashrrev_i32_e32 v27, 31, v26
	v_lshlrev_b64 v[26:27], 13, v[26:27]
	v_lshl_add_u64 v[68:69], v[24:25], 0, v[26:27]
	v_add_u32_e32 v26, s37, v51
	v_ashrrev_i32_e32 v27, 31, v26
	v_lshlrev_b64 v[26:27], 13, v[26:27]
	v_lshl_add_u64 v[70:71], v[24:25], 0, v[26:27]
	global_load_dwordx4 v[24:27], v[68:69], off
	global_load_dwordx4 v[28:31], v[70:71], off
	s_branch .LBB0_1044
; __device__ __forceinline__ unsigned cvt_pk_bf16(float lo, float hi) { unsigned r; asm volatile("v_cvt_pk_bf16_f32 %0, %1, %2" : "=v"(r) : "v"(lo), "v"(hi)); return r; }
; __device__ __forceinline__ void convert_t(const float* __restrict__ W, int K, int N, bf16_t* __restrict__ Wt, int swiglu, int& cursor, float* tile, int perm) {
;     ...
;     const int tid = tix_, G = gdim_; const int ntn = N / 256, nt = (K / 64) * ntn;
;     const int first = cursor; cursor += nt;
;     int id = first + (((int)bid_ - (first % G)) + G) % G;
;     const int last = first + nt * CONV_REP;
;     float4 v[8];
;     if (id < last) { const int tl = (id - first) % nt; const int k0 = (tl / ntn) * 64, n0 = (tl % ntn) * 256;
; #pragma unroll
;         for (int i = 0; i < 8; ++i) { const int idx = tid + 512 * i; const int row = idx >> 6, c4 = idx & 63; v[i] = *(const float4*)(W + (size_t)(k0 + row) * N + n0 + 4 * c4); } }
;     ...
;         for (int p = 0; p < 4; ++p) { const int nl = (tid >> 3) + 64 * p, kq = tid & 7; const float* s = tile + (8 * kq) * 257 + nl;
;             u32x4 w; w.x = cvt_pk_bf16(s[0], s[257]); w.y = cvt_pk_bf16(s[2 * 257], s[3 * 257]); w.z = cvt_pk_bf16(s[4 * 257], s[5 * 257]); w.w = cvt_pk_bf16(s[6 * 257], s[7 * 257]);
;             int n = n0 + nl; if (swiglu) { const int half = n >= DFF ? 1 : 0; const int c = n - half * DFF; n = (c >> 7) * 256 + half * 128 + (c & 127); }
;             { const int pn = n >> 8, half = (n >> 7) & 1, r = n & 127, c5 = r & 31;
;               const int R = perm ? ((r & ~31) + 16 * ((c5 >> 2) & 1) + 4 * (c5 >> 3) + (c5 & 3)) : r;
;               *(u32x4*)((unsigned char*)Wt + ((size_t)pn * (K >> 6) + (k0 >> 6)) * 32768 + half * 16384 + pg8::lds_byte(R, 8 * kq)) = w; } }
.LBB0_1047:
	s_mov_b32 s12, s2
	s_mov_b32 s30, s40
	s_abs_i32 s13, s30
	s_waitcnt vmcnt(11)
	v_cvt_f32_u32_e32 v0, s13
	s_sub_i32 s14, 0, s13
	v_mov_b32_e32 v36, v228
	v_rcp_iflag_f32_e32 v0, v0
	s_nop 0
	v_mul_f32_e32 v0, 0x4f7ffffe, v0
	v_cvt_u32_f32_e32 v0, v0
	s_nop 0
	v_readfirstlane_b32 s15, v0
	s_mul_i32 s14, s14, s15
	s_mul_hi_u32 s14, s15, s14
	s_add_i32 s15, s15, s14
	s_mul_hi_u32 s14, s15, 0x810
	s_mul_i32 s14, s14, s13
	s_sub_i32 s14, 0x810, s14
	s_sub_i32 s31, s14, s13
	s_cmp_ge_u32 s14, s13
	s_cselect_b32 s14, s31, s14
	s_sub_i32 s31, s14, s13
	s_cmp_ge_u32 s14, s13
	s_cselect_b32 s14, s31, s14
	s_add_i32 s12, s30, s12
	s_sub_i32 s12, s12, s14
	s_ashr_i32 s14, s12, 31
	s_abs_i32 s12, s12
	s_mul_hi_u32 s15, s12, s15
	s_mul_i32 s15, s15, s13
	s_sub_i32 s12, s12, s15
	s_sub_i32 s15, s12, s13
	s_cmp_ge_u32 s12, s13
	s_cselect_b32 s12, s15, s12
	s_sub_i32 s15, s12, s13
	s_cmp_ge_u32 s12, s13
	s_cselect_b32 s12, s15, s12
	s_xor_b32 s12, s12, s14
	s_sub_i32 s36, s12, s14
	s_cmpk_gt_i32 s36, 0x53f
	s_cbranch_scc1 .LBB0_1052
	s_add_u32 s12, s24, 0x4080000
	s_addc_u32 s13, s25, 0
	s_add_u32 s14, s28, 0x5400000
	s_mul_hi_i32 s28, s36, 0x30c30c31
	s_addc_u32 s15, s29, 0
	s_lshr_b32 s29, s28, 31
	s_ashr_i32 s28, s28, 8
	s_add_i32 s28, s28, s29
	s_mulk_i32 s28, 0x540
	s_sub_i32 s28, s36, s28
	s_sext_i32_i16 s29, s28
	s_mulk_i32 s29, 0xc30d
	s_lshr_b32 s29, s29, 16
	s_add_i32 s29, s29, s28
	s_sext_i32_i16 s31, s29
	s_ashr_i32 s31, s31, 5
	s_bfe_u32 s29, s29, 0x1000f
	s_add_i32 s29, s31, s29
	s_sext_i32_i16 s31, s29
	s_mul_i32 s29, s29, 42
	s_sub_i32 s28, s28, s29
	s_sext_i32_i16 s28, s28
	s_lshl_b32 s28, s28, 8
	s_ashr_i32 s29, s28, 31
	s_lshl_b32 s37, s31, 6
	s_lshl_b64 s[28:29], s[28:29], 2
	s_add_u32 s28, s14, s28
	v_lshlrev_b32_e32 v37, 4, v36
	s_addc_u32 s29, s15, s29
	v_and_b32_e32 v32, 0x3f0, v37
	v_mov_b32_e32 v33, 0
	v_ashrrev_i32_e32 v50, 6, v36
	s_waitcnt vmcnt(5)
	v_lshl_add_u64 v[24:25], s[28:29], 0, v[32:33]
	v_add_u32_e32 v0, s37, v50
	s_mov_b32 s31, 0xa800
	v_mad_i64_i32 v[8:9], s[28:29], v0, s31, v[24:25]
	v_add_u32_e32 v0, 0x200, v36
	v_ashrrev_i32_e32 v51, 6, v0
	v_add_u32_e32 v0, s37, v51
	v_mad_i64_i32 v[10:11], s[28:29], v0, s31, v[24:25]
	global_load_dwordx4 v[0:3], v[8:9], off
	global_load_dwordx4 v[4:7], v[10:11], off
	v_add_u32_e32 v8, 0x400, v36
	v_ashrrev_i32_e32 v52, 6, v8
	v_add_u32_e32 v8, s37, v52
	v_mad_i64_i32 v[16:17], s[28:29], v8, s31, v[24:25]
	v_add_u32_e32 v8, 0x600, v36
	v_ashrrev_i32_e32 v53, 6, v8
	v_add_u32_e32 v8, s37, v53
	v_mad_i64_i32 v[18:19], s[28:29], v8, s31, v[24:25]
	global_load_dwordx4 v[8:11], v[16:17], off
	global_load_dwordx4 v[12:15], v[18:19], off
	v_add_u32_e32 v16, 0x800, v36
	v_ashrrev_i32_e32 v54, 6, v16
	v_add_u32_e32 v16, s37, v54
	v_mad_i64_i32 v[26:27], s[28:29], v16, s31, v[24:25]
	v_add_u32_e32 v16, 0xa00, v36
	v_ashrrev_i32_e32 v55, 6, v16
	v_add_u32_e32 v16, s37, v55
	s_waitcnt vmcnt(8)
	v_mad_i64_i32 v[28:29], s[28:29], v16, s31, v[24:25]
	global_load_dwordx4 v[16:19], v[26:27], off
	global_load_dwordx4 v[20:23], v[28:29], off
	v_add_u32_e32 v26, 0xc00, v36
	v_ashrrev_i32_e32 v56, 6, v26
	v_add_u32_e32 v26, s37, v56
	v_mad_i64_i32 v[34:35], s[28:29], v26, s31, v[24:25]
	v_add_u32_e32 v26, 0xe00, v36
	v_ashrrev_i32_e32 v57, 6, v26
	v_add_u32_e32 v26, s37, v57
	v_mad_i64_i32 v[38:39], s[28:29], v26, s31, v[24:25]
	global_load_dwordx4 v[24:27], v[34:35], off
	global_load_dwordx4 v[28:31], v[38:39], off
	v_add_u32_e32 v73, 0, v32
	v_lshl_add_u64 v[34:35], s[14:15], 0, v[32:33]
	v_lshlrev_b32_e32 v32, 3, v36
	v_ashrrev_i32_e32 v58, 3, v36
	v_and_b32_e32 v36, 56, v32
	v_mul_u32_u24_e32 v36, 0x404, v36
	v_bfe_u32 v59, v32, 5, 1
	v_and_b32_e32 v32, 48, v37
	v_lshlrev_b32_e32 v37, 2, v58
	v_add3_u32 v60, 0, v36, v37
	v_lshrrev_b32_e32 v36, 1, v58
	v_and_b32_e32 v37, 3, v58
	v_and_or_b32 v38, v36, 12, v37
	v_lshlrev_b32_e32 v39, 1, v58
	v_add_u32_e32 v61, 64, v58
	v_lshlrev_b32_e32 v38, 6, v38
	v_and_b32_e32 v49, 32, v39
	v_or_b32_e32 v48, v38, v32
	v_bitop3_b32 v65, v38, v49, v32 bitop3:0x36
	v_and_b32_e32 v32, 0x60, v61
	v_lshlrev_b32_e32 v38, 2, v61
	v_and_or_b32 v32, v38, 16, v32
	v_lshrrev_b32_e32 v32, 3, v32
	v_or_b32_e32 v32, v32, v59
	v_add_u32_e32 v62, 0x80, v58
	v_lshlrev_b32_e32 v32, 10, v32
	v_and_b32_e32 v64, 0x60, v58
	v_bitop3_b32 v40, v32, v48, v49 bitop3:0xf6
	v_lshlrev_b32_e32 v32, 2, v62
	v_and_or_b32 v32, v32, 16, v64
	v_lshrrev_b32_e32 v32, 3, v32
	v_or_b32_e32 v32, v32, v59
	v_add_u32_e32 v63, 0xc0, v58
	v_lshlrev_b32_e32 v32, 10, v32
	v_bitop3_b32 v44, v32, v48, v49 bitop3:0xf6
	v_and_b32_e32 v32, 0x60, v63
	v_lshlrev_b32_e32 v46, 2, v63
	v_and_or_b32 v32, v46, 16, v32
	v_lshrrev_b32_e32 v32, 3, v32
	s_movk_i32 s14, 0x404
	v_or_b32_e32 v32, v32, v59
	v_mul_lo_u32 v66, v50, s14
	v_mul_lo_u32 v67, v51, s14
	v_mul_lo_u32 v68, v52, s14
	v_mul_lo_u32 v69, v53, s14
	v_mul_lo_u32 v70, v54, s14
	v_mul_lo_u32 v71, v55, s14
	v_mul_lo_u32 v72, v56, s14
	v_mul_lo_u32 v74, v57, s14
	v_lshlrev_b32_e32 v36, 7, v58
	v_lshlrev_b32_e32 v38, 7, v61
	v_lshlrev_b32_e32 v42, 7, v62
	v_lshlrev_b32_e32 v46, 7, v63
	v_lshlrev_b32_e32 v32, 10, v32
	v_and_b32_e32 v36, 0x4000, v36
	v_mov_b32_e32 v37, v33
	v_and_b32_e32 v38, 0x4000, v38
	v_mov_b32_e32 v39, v33
	v_mov_b32_e32 v41, v33
	v_and_b32_e32 v42, 0x4000, v42
	v_mov_b32_e32 v43, v33
	v_mov_b32_e32 v45, v33
	v_and_b32_e32 v46, 0x4000, v46
	v_mov_b32_e32 v47, v33
	v_bitop3_b32 v48, v32, v48, v49 bitop3:0xf6
	v_mov_b32_e32 v49, v33
	v_add_u32_e32 v66, v73, v66
	v_add_u32_e32 v67, v73, v67
	v_add_u32_e32 v68, v73, v68
	v_add_u32_e32 v69, v73, v69
	v_add_u32_e32 v70, v73, v70
	v_add_u32_e32 v71, v73, v71
	v_add_u32_e32 v72, v73, v72
	v_add_u32_e32 v73, v73, v74
	s_waitcnt vmcnt(0)
	s_branch .LBB0_1050

; __device__ __forceinline__ void convert_t(const float* __restrict__ W, int K, int N, bf16_t* __restrict__ Wt, int swiglu, int& cursor, float* tile, int perm) {
;     ...
;     for (; id < last; id += G) {
;         const int tl = (id - first) % nt; const int k0 = (tl / ntn) * 64, n0 = (tl % ntn) * 256;
; #pragma unroll
;         for (int i = 0; i < 8; ++i) { const int idx = tid + 512 * i; const int row = idx >> 6, c4 = idx & 63; float* d = tile + row * 257 + 4 * c4; d[0] = v[i].x; d[1] = v[i].y; d[2] = v[i].z; d[3] = v[i].w; }
;         __syncthreads();
;         if (id + G < last) { const int tl2 = (id + G - first) % nt; const int k2 = (tl2 / ntn) * 64, n2 = (tl2 % ntn) * 256;
; #pragma unroll
;             for (int i = 0; i < 8; ++i) { const int idx = tid + 512 * i; const int row = idx >> 6, c4 = idx & 63; v[i] = *(const float4*)(W + (size_t)(k2 + row) * N + n2 + 4 * c4); } }
.LBB0_1050:
	s_add_i32 s37, s30, s36
	s_add_i32 s14, s37, 0x810
	s_cmpk_gt_i32 s14, 0xd4f
	s_cselect_b64 s[14:15], -1, 0
	s_and_b64 vcc, exec, s[14:15]
	s_waitcnt vmcnt(11)
	ds_write2_b32 v66, v0, v1 offset1:1
	ds_write2_b32 v66, v2, v3 offset0:2 offset1:3
	s_waitcnt vmcnt(10)
	ds_write2_b32 v67, v4, v5 offset1:1
	ds_write2_b32 v67, v6, v7 offset0:2 offset1:3
	s_waitcnt vmcnt(9)
	ds_write2_b32 v68, v8, v9 offset1:1
	ds_write2_b32 v68, v10, v11 offset0:2 offset1:3
	s_waitcnt vmcnt(8)
	ds_write2_b32 v69, v12, v13 offset1:1
	ds_write2_b32 v69, v14, v15 offset0:2 offset1:3
	s_waitcnt vmcnt(7)
	ds_write2_b32 v70, v16, v17 offset1:1
	ds_write2_b32 v70, v18, v19 offset0:2 offset1:3
	s_waitcnt vmcnt(6)
	ds_write2_b32 v71, v20, v21 offset1:1
	ds_write2_b32 v71, v22, v23 offset0:2 offset1:3
	s_waitcnt vmcnt(5)
	ds_write2_b32 v72, v24, v25 offset1:1
	ds_write2_b32 v72, v26, v27 offset0:2 offset1:3
	s_waitcnt vmcnt(4)
	ds_write2_b32 v73, v28, v29 offset1:1
	ds_write2_b32 v73, v30, v31 offset0:2 offset1:3
	s_waitcnt lgkmcnt(0)
	s_barrier
	s_cbranch_vccnz .LBB0_1049
	s_mul_hi_i32 s28, s37, 0x30c30c31
	s_lshr_b32 s29, s28, 31
	s_ashr_i32 s28, s28, 8
	s_add_i32 s28, s28, s29
	s_mulk_i32 s28, 0x540
	s_sub_i32 s28, s37, s28
	s_sext_i32_i16 s29, s28
	s_mulk_i32 s29, 0xc30d
	s_lshr_b32 s29, s29, 16
	s_add_i32 s29, s29, s28
	s_sext_i32_i16 s38, s29
	s_ashr_i32 s38, s38, 5
	s_bfe_u32 s29, s29, 0x1000f
	s_add_i32 s29, s38, s29
	s_sext_i32_i16 s38, s29
	s_mul_i32 s29, s29, 42
	s_sub_i32 s28, s28, s29
	s_sext_i32_i16 s28, s28
	s_lshl_b32 s28, s28, 8
	s_lshl_b32 s38, s38, 6
	s_ashr_i32 s29, s28, 31
	v_lshl_add_u64 v[24:25], s[28:29], 2, v[34:35]
	v_add_u32_e32 v0, s38, v50
	v_mad_i64_i32 v[8:9], s[28:29], v0, s31, v[24:25]
	v_add_u32_e32 v0, s38, v51
	v_mad_i64_i32 v[10:11], s[28:29], v0, s31, v[24:25]
	global_load_dwordx4 v[0:3], v[8:9], off
	global_load_dwordx4 v[4:7], v[10:11], off
	v_add_u32_e32 v8, s38, v52
	v_mad_i64_i32 v[16:17], s[28:29], v8, s31, v[24:25]
	v_add_u32_e32 v8, s38, v53
	v_mad_i64_i32 v[18:19], s[28:29], v8, s31, v[24:25]
	global_load_dwordx4 v[8:11], v[16:17], off
	global_load_dwordx4 v[12:15], v[18:19], off
	v_add_u32_e32 v16, s38, v54
	v_mad_i64_i32 v[26:27], s[28:29], v16, s31, v[24:25]
	v_add_u32_e32 v16, s38, v55
	v_mad_i64_i32 v[28:29], s[28:29], v16, s31, v[24:25]
	global_load_dwordx4 v[16:19], v[26:27], off
	global_load_dwordx4 v[20:23], v[28:29], off
	v_add_u32_e32 v26, s38, v56
	v_mad_i64_i32 v[74:75], s[28:29], v26, s31, v[24:25]
	v_add_u32_e32 v26, s38, v57
	v_mad_i64_i32 v[76:77], s[28:29], v26, s31, v[24:25]
	global_load_dwordx4 v[24:27], v[74:75], off
	global_load_dwordx4 v[28:31], v[76:77], off
	s_branch .LBB0_1049
; __device__ __forceinline__ unsigned cvt_pk_bf16(float lo, float hi) { unsigned r; asm volatile("v_cvt_pk_bf16_f32 %0, %1, %2" : "=v"(r) : "v"(lo), "v"(hi)); return r; }
; __device__ __forceinline__ void convert_t(const float* __restrict__ W, int K, int N, bf16_t* __restrict__ Wt, int swiglu, int& cursor, float* tile, int perm) {
;     ...
;     const int tid = tix_, G = gdim_; const int ntn = N / 256, nt = (K / 64) * ntn;
;     const int first = cursor; cursor += nt;
;     int id = first + (((int)bid_ - (first % G)) + G) % G;
;     const int last = first + nt * CONV_REP;
;     float4 v[8];
;     if (id < last) { const int tl = (id - first) % nt; const int k0 = (tl / ntn) * 64, n0 = (tl % ntn) * 256;
; #pragma unroll
;         for (int i = 0; i < 8; ++i) { const int idx = tid + 512 * i; const int row = idx >> 6, c4 = idx & 63; v[i] = *(const float4*)(W + (size_t)(k0 + row) * N + n0 + 4 * c4); } }
;     ...
;         for (int p = 0; p < 4; ++p) { const int nl = (tid >> 3) + 64 * p, kq = tid & 7; const float* s = tile + (8 * kq) * 257 + nl;
;             u32x4 w; w.x = cvt_pk_bf16(s[0], s[257]); w.y = cvt_pk_bf16(s[2 * 257], s[3 * 257]); w.z = cvt_pk_bf16(s[4 * 257], s[5 * 257]); w.w = cvt_pk_bf16(s[6 * 257], s[7 * 257]);
;             int n = n0 + nl; if (swiglu) { const int half = n >= DFF ? 1 : 0; const int c = n - half * DFF; n = (c >> 7) * 256 + half * 128 + (c & 127); }
;             { const int pn = n >> 8, half = (n >> 7) & 1, r = n & 127, c5 = r & 31;
;               const int R = perm ? ((r & ~31) + 16 * ((c5 >> 2) & 1) + 4 * (c5 >> 3) + (c5 & 3)) : r;
;               *(u32x4*)((unsigned char*)Wt + ((size_t)pn * (K >> 6) + (k0 >> 6)) * 32768 + half * 16384 + pg8::lds_byte(R, 8 * kq)) = w; } }
.LBB0_1052:
	s_mov_b32 s12, s2
	s_mov_b32 s28, s40
	s_abs_i32 s13, s28
	s_waitcnt vmcnt(11)
	v_cvt_f32_u32_e32 v0, s13
	s_sub_i32 s14, 0, s13
	v_mov_b32_e32 v36, v228
	v_rcp_iflag_f32_e32 v0, v0
	s_nop 0
	v_mul_f32_e32 v0, 0x4f7ffffe, v0
	v_cvt_u32_f32_e32 v0, v0
	s_nop 0
	v_readfirstlane_b32 s15, v0
	s_mul_i32 s14, s14, s15
	s_mul_hi_u32 s14, s15, s14
	s_add_i32 s15, s15, s14
	s_mul_hi_u32 s14, s15, 0xd50
	s_mul_i32 s14, s14, s13
	s_sub_i32 s14, 0xd50, s14
	s_sub_i32 s29, s14, s13
	s_cmp_ge_u32 s14, s13
	s_cselect_b32 s14, s29, s14
	s_sub_i32 s29, s14, s13
	s_cmp_ge_u32 s14, s13
	s_cselect_b32 s14, s29, s14
	s_add_i32 s12, s28, s12
	s_sub_i32 s12, s12, s14
	s_ashr_i32 s14, s12, 31
	s_abs_i32 s12, s12
	s_mul_hi_u32 s15, s12, s15
	s_mul_i32 s15, s15, s13
	s_sub_i32 s12, s12, s15
	s_sub_i32 s15, s12, s13
	s_cmp_ge_u32 s12, s13
	s_cselect_b32 s12, s15, s12
	s_sub_i32 s15, s12, s13
	s_cmp_ge_u32 s12, s13
	s_cselect_b32 s12, s15, s12
	s_xor_b32 s12, s12, s14
	s_sub_i32 s29, s12, s14
	s_cmpk_gt_i32 s29, 0xff
	s_cbranch_scc1 .LBB0_1057
	s_add_u32 s12, s24, 0x6a80000
	s_addc_u32 s13, s25, 0
	s_add_u32 s14, s18, 0x1000000
	s_addc_u32 s15, s19, 0
	s_ashr_i32 s18, s29, 31
	s_lshr_b32 s18, s18, 24
	s_add_i32 s18, s29, s18
	s_and_b32 s18, s18, 0xff00
	s_sub_i32 s18, s29, s18
	s_sext_i32_i16 s19, s18
	s_bfe_u32 s19, s19, 0x3001c
	s_add_i32 s19, s18, s19
	s_sext_i32_i16 s30, s19
	s_and_b32 s19, s19, 0xfff8
	s_sub_i32 s18, s18, s19
	s_sext_i32_i16 s18, s18
	s_lshl_b32 s18, s18, 8
	s_lshl_b32 s30, s30, 3
	s_ashr_i32 s19, s18, 31
	s_andn2_b32 s30, s30, 63
	s_lshl_b64 s[18:19], s[18:19], 2
	v_ashrrev_i32_e32 v50, 6, v36
	s_add_u32 s18, s14, s18
	v_lshlrev_b32_e32 v37, 4, v36
	v_add_u32_e32 v0, s30, v50
	s_addc_u32 s19, s15, s19
	v_and_b32_e32 v32, 0x3f0, v37
	v_mov_b32_e32 v33, 0
	v_ashrrev_i32_e32 v1, 31, v0
	s_waitcnt vmcnt(5)
	v_lshl_add_u64 v[24:25], s[18:19], 0, v[32:33]
	v_lshlrev_b64 v[0:1], 13, v[0:1]
	v_lshl_add_u64 v[8:9], v[24:25], 0, v[0:1]
	v_add_u32_e32 v0, 0x200, v36
	v_ashrrev_i32_e32 v51, 6, v0
	v_add_u32_e32 v0, s30, v51
	v_ashrrev_i32_e32 v1, 31, v0
	v_lshlrev_b64 v[0:1], 13, v[0:1]
	v_lshl_add_u64 v[10:11], v[24:25], 0, v[0:1]
	global_load_dwordx4 v[0:3], v[8:9], off
	global_load_dwordx4 v[4:7], v[10:11], off
	v_add_u32_e32 v8, 0x400, v36
	v_ashrrev_i32_e32 v52, 6, v8
	v_add_u32_e32 v8, s30, v52
	v_ashrrev_i32_e32 v9, 31, v8
	v_lshlrev_b64 v[8:9], 13, v[8:9]
	v_lshl_add_u64 v[16:17], v[24:25], 0, v[8:9]
	v_add_u32_e32 v8, 0x600, v36
	v_ashrrev_i32_e32 v53, 6, v8
	v_add_u32_e32 v8, s30, v53
	v_ashrrev_i32_e32 v9, 31, v8
	v_lshlrev_b64 v[8:9], 13, v[8:9]
	v_lshl_add_u64 v[18:19], v[24:25], 0, v[8:9]
	global_load_dwordx4 v[8:11], v[16:17], off
	global_load_dwordx4 v[12:15], v[18:19], off
	v_add_u32_e32 v16, 0x800, v36
	v_ashrrev_i32_e32 v54, 6, v16
	v_add_u32_e32 v16, s30, v54
	v_ashrrev_i32_e32 v17, 31, v16
	v_lshlrev_b64 v[16:17], 13, v[16:17]
	v_lshl_add_u64 v[26:27], v[24:25], 0, v[16:17]
	v_add_u32_e32 v16, 0xa00, v36
	v_ashrrev_i32_e32 v55, 6, v16
	v_add_u32_e32 v16, s30, v55
	v_ashrrev_i32_e32 v17, 31, v16
	v_lshlrev_b64 v[16:17], 13, v[16:17]
	s_waitcnt vmcnt(8)
	v_lshl_add_u64 v[28:29], v[24:25], 0, v[16:17]
	global_load_dwordx4 v[16:19], v[26:27], off
	global_load_dwordx4 v[20:23], v[28:29], off
	v_add_u32_e32 v26, 0xc00, v36
	v_ashrrev_i32_e32 v56, 6, v26
	v_add_u32_e32 v26, s30, v56
	v_ashrrev_i32_e32 v27, 31, v26
	v_lshlrev_b64 v[26:27], 13, v[26:27]
	v_lshl_add_u64 v[34:35], v[24:25], 0, v[26:27]
	v_add_u32_e32 v26, 0xe00, v36
	v_ashrrev_i32_e32 v57, 6, v26
	v_add_u32_e32 v26, s30, v57
	v_ashrrev_i32_e32 v27, 31, v26
	v_lshlrev_b64 v[26:27], 13, v[26:27]
	v_lshl_add_u64 v[38:39], v[24:25], 0, v[26:27]
	global_load_dwordx4 v[24:27], v[34:35], off
	global_load_dwordx4 v[28:31], v[38:39], off
	v_add_u32_e32 v73, 0, v32
	v_lshl_add_u64 v[34:35], s[14:15], 0, v[32:33]
	v_lshlrev_b32_e32 v32, 3, v36
	v_ashrrev_i32_e32 v58, 3, v36
	v_and_b32_e32 v36, 56, v32
	v_mul_u32_u24_e32 v36, 0x404, v36
	v_bfe_u32 v59, v32, 5, 1
	v_and_b32_e32 v32, 48, v37
	v_lshlrev_b32_e32 v37, 2, v58
	v_add3_u32 v60, 0, v36, v37
	v_lshrrev_b32_e32 v36, 1, v58
	v_and_b32_e32 v37, 3, v58
	v_and_or_b32 v38, v36, 12, v37
	v_lshlrev_b32_e32 v39, 1, v58
	v_add_u32_e32 v61, 64, v58
	v_lshlrev_b32_e32 v38, 6, v38
	v_and_b32_e32 v49, 32, v39
	v_or_b32_e32 v48, v38, v32
	v_bitop3_b32 v65, v38, v49, v32 bitop3:0x36
	v_and_b32_e32 v32, 0x60, v61
	v_lshlrev_b32_e32 v38, 2, v61
	v_and_or_b32 v32, v38, 16, v32
	v_lshrrev_b32_e32 v32, 3, v32
	v_or_b32_e32 v32, v32, v59
	v_add_u32_e32 v62, 0x80, v58
	v_lshlrev_b32_e32 v32, 10, v32
	v_and_b32_e32 v64, 0x60, v58
	v_bitop3_b32 v40, v32, v48, v49 bitop3:0xf6
	v_lshlrev_b32_e32 v32, 2, v62
	v_and_or_b32 v32, v32, 16, v64
	v_lshrrev_b32_e32 v32, 3, v32
	v_or_b32_e32 v32, v32, v59
	v_add_u32_e32 v63, 0xc0, v58
	v_lshlrev_b32_e32 v32, 10, v32
	v_bitop3_b32 v44, v32, v48, v49 bitop3:0xf6
	v_and_b32_e32 v32, 0x60, v63
	v_lshlrev_b32_e32 v46, 2, v63
	v_and_or_b32 v32, v46, 16, v32
	v_lshrrev_b32_e32 v32, 3, v32
	s_movk_i32 s14, 0x404
	v_or_b32_e32 v32, v32, v59
	v_mul_lo_u32 v66, v50, s14
	v_mul_lo_u32 v67, v51, s14
	v_mul_lo_u32 v68, v52, s14
	v_mul_lo_u32 v69, v53, s14
	v_mul_lo_u32 v70, v54, s14
	v_mul_lo_u32 v71, v55, s14
	v_mul_lo_u32 v72, v56, s14
	v_mul_lo_u32 v74, v57, s14
	v_lshlrev_b32_e32 v36, 7, v58
	v_lshlrev_b32_e32 v38, 7, v61
	v_lshlrev_b32_e32 v42, 7, v62
	v_lshlrev_b32_e32 v46, 7, v63
	v_lshlrev_b32_e32 v32, 10, v32
	v_and_b32_e32 v36, 0x4000, v36
	v_mov_b32_e32 v37, v33
	v_and_b32_e32 v38, 0x4000, v38
	v_mov_b32_e32 v39, v33
	v_mov_b32_e32 v41, v33
	v_and_b32_e32 v42, 0x4000, v42
	v_mov_b32_e32 v43, v33
	v_mov_b32_e32 v45, v33
	v_and_b32_e32 v46, 0x4000, v46
	v_mov_b32_e32 v47, v33
	v_bitop3_b32 v48, v32, v48, v49 bitop3:0xf6
	v_mov_b32_e32 v49, v33
	v_add_u32_e32 v66, v73, v66
	v_add_u32_e32 v67, v73, v67
	v_add_u32_e32 v68, v73, v68
	v_add_u32_e32 v69, v73, v69
	v_add_u32_e32 v70, v73, v70
	v_add_u32_e32 v71, v73, v71
	v_add_u32_e32 v72, v73, v72
	v_add_u32_e32 v73, v73, v74
	s_waitcnt vmcnt(0)
	s_branch .LBB0_1055

; __device__ __forceinline__ void convert_t(const float* __restrict__ W, int K, int N, bf16_t* __restrict__ Wt, int swiglu, int& cursor, float* tile, int perm) {
;     ...
;     for (; id < last; id += G) {
;         const int tl = (id - first) % nt; const int k0 = (tl / ntn) * 64, n0 = (tl % ntn) * 256;
; #pragma unroll
;         for (int i = 0; i < 8; ++i) { const int idx = tid + 512 * i; const int row = idx >> 6, c4 = idx & 63; float* d = tile + row * 257 + 4 * c4; d[0] = v[i].x; d[1] = v[i].y; d[2] = v[i].z; d[3] = v[i].w; }
;         __syncthreads();
;         if (id + G < last) { const int tl2 = (id + G - first) % nt; const int k2 = (tl2 / ntn) * 64, n2 = (tl2 % ntn) * 256;
; #pragma unroll
;             for (int i = 0; i < 8; ++i) { const int idx = tid + 512 * i; const int row = idx >> 6, c4 = idx & 63; v[i] = *(const float4*)(W + (size_t)(k2 + row) * N + n2 + 4 * c4); } }
.LBB0_1055:
	s_add_i32 s30, s28, s29
	s_add_i32 s14, s30, 0xd50
	s_cmpk_gt_i32 s14, 0xe4f
	s_cselect_b64 s[14:15], -1, 0
	s_and_b64 vcc, exec, s[14:15]
	s_waitcnt vmcnt(11)
	ds_write2_b32 v66, v0, v1 offset1:1
	ds_write2_b32 v66, v2, v3 offset0:2 offset1:3
	s_waitcnt vmcnt(10)
	ds_write2_b32 v67, v4, v5 offset1:1
	ds_write2_b32 v67, v6, v7 offset0:2 offset1:3
	s_waitcnt vmcnt(9)
	ds_write2_b32 v68, v8, v9 offset1:1
	ds_write2_b32 v68, v10, v11 offset0:2 offset1:3
	s_waitcnt vmcnt(8)
	ds_write2_b32 v69, v12, v13 offset1:1
	ds_write2_b32 v69, v14, v15 offset0:2 offset1:3
	s_waitcnt vmcnt(7)
	ds_write2_b32 v70, v16, v17 offset1:1
	ds_write2_b32 v70, v18, v19 offset0:2 offset1:3
	s_waitcnt vmcnt(6)
	ds_write2_b32 v71, v20, v21 offset1:1
	ds_write2_b32 v71, v22, v23 offset0:2 offset1:3
	s_waitcnt vmcnt(5)
	ds_write2_b32 v72, v24, v25 offset1:1
	ds_write2_b32 v72, v26, v27 offset0:2 offset1:3
	s_waitcnt vmcnt(4)
	ds_write2_b32 v73, v28, v29 offset1:1
	ds_write2_b32 v73, v30, v31 offset0:2 offset1:3
	s_waitcnt lgkmcnt(0)
	s_barrier
	s_cbranch_vccnz .LBB0_1054
	s_ashr_i32 s18, s30, 31
	s_lshr_b32 s18, s18, 24
	s_add_i32 s18, s30, s18
	s_and_b32 s18, s18, 0xff00
	s_sub_i32 s18, s30, s18
	s_sext_i32_i16 s19, s18
	s_bfe_u32 s19, s19, 0x3001c
	s_add_i32 s19, s18, s19
	s_sext_i32_i16 s31, s19
	s_and_b32 s19, s19, 0xfff8
	s_lshl_b32 s31, s31, 3
	s_sub_i32 s18, s18, s19
	s_andn2_b32 s31, s31, 63
	s_sext_i32_i16 s18, s18
	s_lshl_b32 s18, s18, 8
	v_add_u32_e32 v0, s31, v50
	s_ashr_i32 s19, s18, 31
	v_ashrrev_i32_e32 v1, 31, v0
	v_lshl_add_u64 v[24:25], s[18:19], 2, v[34:35]
	v_lshlrev_b64 v[0:1], 13, v[0:1]
	v_lshl_add_u64 v[8:9], v[24:25], 0, v[0:1]
	v_add_u32_e32 v0, s31, v51
	v_ashrrev_i32_e32 v1, 31, v0
	v_lshlrev_b64 v[0:1], 13, v[0:1]
	v_lshl_add_u64 v[10:11], v[24:25], 0, v[0:1]
	global_load_dwordx4 v[0:3], v[8:9], off
	global_load_dwordx4 v[4:7], v[10:11], off
	v_add_u32_e32 v8, s31, v52
	v_ashrrev_i32_e32 v9, 31, v8
	v_lshlrev_b64 v[8:9], 13, v[8:9]
	v_lshl_add_u64 v[16:17], v[24:25], 0, v[8:9]
	v_add_u32_e32 v8, s31, v53
	v_ashrrev_i32_e32 v9, 31, v8
	v_lshlrev_b64 v[8:9], 13, v[8:9]
	v_lshl_add_u64 v[18:19], v[24:25], 0, v[8:9]
	global_load_dwordx4 v[8:11], v[16:17], off
	global_load_dwordx4 v[12:15], v[18:19], off
	v_add_u32_e32 v16, s31, v54
	v_ashrrev_i32_e32 v17, 31, v16
	v_lshlrev_b64 v[16:17], 13, v[16:17]
	v_lshl_add_u64 v[26:27], v[24:25], 0, v[16:17]
	v_add_u32_e32 v16, s31, v55
	v_ashrrev_i32_e32 v17, 31, v16
	v_lshlrev_b64 v[16:17], 13, v[16:17]
	v_lshl_add_u64 v[28:29], v[24:25], 0, v[16:17]
	global_load_dwordx4 v[16:19], v[26:27], off
	global_load_dwordx4 v[20:23], v[28:29], off
	v_add_u32_e32 v26, s31, v56
	v_ashrrev_i32_e32 v27, 31, v26
	v_lshlrev_b64 v[26:27], 13, v[26:27]
	v_lshl_add_u64 v[74:75], v[24:25], 0, v[26:27]
	v_add_u32_e32 v26, s31, v57
	v_ashrrev_i32_e32 v27, 31, v26
	v_lshlrev_b64 v[26:27], 13, v[26:27]
	v_lshl_add_u64 v[76:77], v[24:25], 0, v[26:27]
	global_load_dwordx4 v[24:27], v[74:75], off
	global_load_dwordx4 v[28:31], v[76:77], off
	s_branch .LBB0_1054

; __device__ __forceinline__ unsigned cvt_pk_bf16(float lo, float hi) { unsigned r; asm volatile("v_cvt_pk_bf16_f32 %0, %1, %2" : "=v"(r) : "v"(lo), "v"(hi)); return r; }
; __device__ __forceinline__ void convert_t(const float* __restrict__ W, int K, int N, bf16_t* __restrict__ Wt, int swiglu, int& cursor, float* tile, int perm) {
;     ...
;     const int tid = tix_, G = gdim_; const int ntn = N / 256, nt = (K / 64) * ntn;
;     const int first = cursor; cursor += nt;
;     int id = first + (((int)bid_ - (first % G)) + G) % G;
;     const int last = first + nt * CONV_REP;
;     float4 v[8];
;     if (id < last) { const int tl = (id - first) % nt; const int k0 = (tl / ntn) * 64, n0 = (tl % ntn) * 256;
; #pragma unroll
;         for (int i = 0; i < 8; ++i) { const int idx = tid + 512 * i; const int row = idx >> 6, c4 = idx & 63; v[i] = *(const float4*)(W + (size_t)(k0 + row) * N + n0 + 4 * c4); } }
;     ...
;         for (int p = 0; p < 4; ++p) { const int nl = (tid >> 3) + 64 * p, kq = tid & 7; const float* s = tile + (8 * kq) * 257 + nl;
;             u32x4 w; w.x = cvt_pk_bf16(s[0], s[257]); w.y = cvt_pk_bf16(s[2 * 257], s[3 * 257]); w.z = cvt_pk_bf16(s[4 * 257], s[5 * 257]); w.w = cvt_pk_bf16(s[6 * 257], s[7 * 257]);
;             int n = n0 + nl; if (swiglu) { const int half = n >= DFF ? 1 : 0; const int c = n - half * DFF; n = (c >> 7) * 256 + half * 128 + (c & 127); }
;             { const int pn = n >> 8, half = (n >> 7) & 1, r = n & 127, c5 = r & 31;
;               const int R = perm ? ((r & ~31) + 16 * ((c5 >> 2) & 1) + 4 * (c5 >> 3) + (c5 & 3)) : r;
;               *(u32x4*)((unsigned char*)Wt + ((size_t)pn * (K >> 6) + (k0 >> 6)) * 32768 + half * 16384 + pg8::lds_byte(R, 8 * kq)) = w; } }
.LBB0_1059:
	s_mov_b32 s14, s2
	s_mov_b32 s36, s40
	s_abs_i32 s15, s36
	s_waitcnt vmcnt(11)
	v_cvt_f32_u32_e32 v0, s15
	s_sub_i32 s18, 0, s15
	s_add_i32 s37, s30, 0x80
	v_mov_b32_e32 v36, v228
	v_rcp_iflag_f32_e32 v0, v0
	s_nop 0
	v_mul_f32_e32 v0, 0x4f7ffffe, v0
	v_cvt_u32_f32_e32 v0, v0
	s_nop 0
	v_readfirstlane_b32 s19, v0
	s_mul_i32 s18, s18, s19
	s_mul_hi_u32 s18, s19, s18
	s_add_i32 s19, s19, s18
	s_mul_hi_u32 s18, s30, s19
	s_mul_i32 s18, s18, s15
	s_sub_i32 s18, s30, s18
	s_sub_i32 s38, s18, s15
	s_cmp_ge_u32 s18, s15
	s_cselect_b32 s18, s38, s18
	s_sub_i32 s38, s18, s15
	s_cmp_ge_u32 s18, s15
	s_cselect_b32 s18, s38, s18
	s_add_i32 s14, s36, s14
	s_sub_i32 s14, s14, s18
	s_ashr_i32 s39, s14, 31
	s_abs_i32 s14, s14
	s_mul_hi_u32 s18, s14, s19
	s_mul_i32 s18, s18, s15
	s_sub_i32 s14, s14, s18
	s_sub_i32 s18, s14, s15
	s_cmp_ge_u32 s14, s15
	s_cselect_b32 s14, s18, s14
	s_sub_i32 s18, s14, s15
	s_cmp_ge_u32 s14, s15
	s_cselect_b32 s14, s18, s14
	s_xor_b32 s46, s14, s39
	s_sub_i32 s38, s46, s39
	s_cmpk_gt_i32 s38, 0x7f
	s_cbranch_scc1 .LBB0_1058
	s_lshl_b64 s[14:15], s[12:13], 22
	s_add_u32 s14, s28, s14
	s_addc_u32 s15, s29, s15
	s_lshl_b64 s[18:19], s[12:13], 23
	s_add_u32 s18, s20, s18
	s_addc_u32 s19, s21, s19
	s_add_u32 s18, s18, 0x1800000
	s_addc_u32 s19, s19, 0
	s_ashr_i32 s47, s38, 31
	s_lshr_b32 s47, s47, 25
	s_add_i32 s47, s38, s47
	s_and_b32 s47, s47, 0xff80
	s_sub_i32 s47, s38, s47
	s_bfe_i32 s48, s47, 0x80000
	s_bfe_u32 s48, s48, 0x3000c
	s_add_i32 s48, s47, s48
	s_bfe_i32 s49, s48, 0x80000
	s_and_b32 s48, s48, 0xf8
	s_sub_i32 s47, s47, s48
	s_sext_i32_i16 s49, s49
	s_sext_i32_i8 s47, s47
	s_lshl_b32 s49, s49, 3
	s_lshl_b32 s48, s47, 8
	s_and_b32 s50, s49, 0xffffffc0
	s_ashr_i32 s49, s48, 31
	s_lshl_b64 s[48:49], s[48:49], 2
	v_ashrrev_i32_e32 v50, 6, v36
	s_add_u32 s48, s18, s48
	v_lshlrev_b32_e32 v37, 4, v36
	v_add_u32_e32 v0, s50, v50
	s_addc_u32 s49, s19, s49
	v_and_b32_e32 v32, 0x3f0, v37
	v_ashrrev_i32_e32 v1, 31, v0
	s_waitcnt vmcnt(5)
	v_lshl_add_u64 v[24:25], s[48:49], 0, v[32:33]
	v_lshlrev_b64 v[0:1], 13, v[0:1]
	v_lshl_add_u64 v[8:9], v[24:25], 0, v[0:1]
	v_add_u32_e32 v0, 0x200, v36
	v_ashrrev_i32_e32 v51, 6, v0
	v_add_u32_e32 v0, s50, v51
	v_ashrrev_i32_e32 v1, 31, v0
	v_lshlrev_b64 v[0:1], 13, v[0:1]
	v_lshl_add_u64 v[10:11], v[24:25], 0, v[0:1]
	global_load_dwordx4 v[0:3], v[8:9], off
	global_load_dwordx4 v[4:7], v[10:11], off
	v_add_u32_e32 v8, 0x400, v36
	v_ashrrev_i32_e32 v52, 6, v8
	v_add_u32_e32 v8, s50, v52
	v_ashrrev_i32_e32 v9, 31, v8
	v_lshlrev_b64 v[8:9], 13, v[8:9]
	v_lshl_add_u64 v[16:17], v[24:25], 0, v[8:9]
	v_add_u32_e32 v8, 0x600, v36
	v_ashrrev_i32_e32 v53, 6, v8
	v_add_u32_e32 v8, s50, v53
	v_ashrrev_i32_e32 v9, 31, v8
	v_lshlrev_b64 v[8:9], 13, v[8:9]
	v_lshl_add_u64 v[18:19], v[24:25], 0, v[8:9]
	global_load_dwordx4 v[8:11], v[16:17], off
	global_load_dwordx4 v[12:15], v[18:19], off
	v_add_u32_e32 v16, 0x800, v36
	v_ashrrev_i32_e32 v54, 6, v16
	v_add_u32_e32 v16, s50, v54
	v_ashrrev_i32_e32 v17, 31, v16
	v_lshlrev_b64 v[16:17], 13, v[16:17]
	v_lshl_add_u64 v[26:27], v[24:25], 0, v[16:17]
	v_add_u32_e32 v16, 0xa00, v36
	v_ashrrev_i32_e32 v55, 6, v16
	v_add_u32_e32 v16, s50, v55
	v_ashrrev_i32_e32 v17, 31, v16
	v_lshlrev_b64 v[16:17], 13, v[16:17]
	s_waitcnt vmcnt(8)
	v_lshl_add_u64 v[28:29], v[24:25], 0, v[16:17]
	global_load_dwordx4 v[16:19], v[26:27], off
	global_load_dwordx4 v[20:23], v[28:29], off
	v_add_u32_e32 v26, 0xc00, v36
	v_ashrrev_i32_e32 v56, 6, v26
	v_add_u32_e32 v26, s50, v56
	v_ashrrev_i32_e32 v27, 31, v26
	v_lshlrev_b64 v[26:27], 13, v[26:27]
	v_lshl_add_u64 v[34:35], v[24:25], 0, v[26:27]
	v_add_u32_e32 v26, 0xe00, v36
	v_ashrrev_i32_e32 v57, 6, v26
	v_add_u32_e32 v26, s50, v57
	v_ashrrev_i32_e32 v27, 31, v26
	v_lshlrev_b64 v[26:27], 13, v[26:27]
	v_lshl_add_u64 v[38:39], v[24:25], 0, v[26:27]
	global_load_dwordx4 v[24:27], v[34:35], off
	global_load_dwordx4 v[28:31], v[38:39], off
	v_add_u32_e32 v73, 0, v32
	v_lshl_add_u64 v[34:35], s[18:19], 0, v[32:33]
	v_lshlrev_b32_e32 v32, 3, v36
	v_ashrrev_i32_e32 v58, 3, v36
	v_and_b32_e32 v36, 56, v32
	v_mul_u32_u24_e32 v36, 0x404, v36
	v_bfe_u32 v59, v32, 5, 1
	v_and_b32_e32 v32, 48, v37
	v_lshlrev_b32_e32 v37, 2, v58
	v_add3_u32 v60, 0, v36, v37
	v_lshrrev_b32_e32 v36, 1, v58
	v_and_b32_e32 v37, 3, v58
	v_and_or_b32 v38, v36, 12, v37
	v_lshlrev_b32_e32 v39, 1, v58
	v_add_u32_e32 v61, 64, v58
	v_lshlrev_b32_e32 v38, 6, v38
	v_and_b32_e32 v49, 32, v39
	v_or_b32_e32 v48, v38, v32
	v_bitop3_b32 v65, v38, v49, v32 bitop3:0x36
	v_and_b32_e32 v32, 0x60, v61
	v_lshlrev_b32_e32 v38, 2, v61
	v_and_or_b32 v32, v38, 16, v32
	v_lshrrev_b32_e32 v32, 3, v32
	v_or_b32_e32 v32, v32, v59
	v_add_u32_e32 v62, 0x80, v58
	v_lshlrev_b32_e32 v32, 10, v32
	v_and_b32_e32 v64, 0x60, v58
	v_bitop3_b32 v40, v32, v48, v49 bitop3:0xf6
	v_lshlrev_b32_e32 v32, 2, v62
	v_and_or_b32 v32, v32, 16, v64
	v_lshrrev_b32_e32 v32, 3, v32
	v_or_b32_e32 v32, v32, v59
	v_add_u32_e32 v63, 0xc0, v58
	v_lshlrev_b32_e32 v32, 10, v32
	v_bitop3_b32 v44, v32, v48, v49 bitop3:0xf6
	v_and_b32_e32 v32, 0x60, v63
	v_lshlrev_b32_e32 v46, 2, v63
	v_and_or_b32 v32, v46, 16, v32
	v_lshrrev_b32_e32 v32, 3, v32
	v_or_b32_e32 v32, v32, v59
	v_mul_lo_u32 v66, v50, s31
	v_mul_lo_u32 v67, v51, s31
	v_mul_lo_u32 v68, v52, s31
	v_mul_lo_u32 v69, v53, s31
	v_mul_lo_u32 v70, v54, s31
	v_mul_lo_u32 v71, v55, s31
	v_mul_lo_u32 v72, v56, s31
	v_mul_lo_u32 v74, v57, s31
	v_lshlrev_b32_e32 v36, 7, v58
	v_lshlrev_b32_e32 v38, 7, v61
	v_lshlrev_b32_e32 v42, 7, v62
	v_lshlrev_b32_e32 v46, 7, v63
	v_lshlrev_b32_e32 v32, 10, v32
	s_add_i32 s18, s36, s46
	v_and_b32_e32 v36, 0x4000, v36
	v_mov_b32_e32 v37, v33
	v_and_b32_e32 v38, 0x4000, v38
	v_mov_b32_e32 v39, v33
	v_mov_b32_e32 v41, v33
	v_and_b32_e32 v42, 0x4000, v42
	v_mov_b32_e32 v43, v33
	v_mov_b32_e32 v45, v33
	v_and_b32_e32 v46, 0x4000, v46
	v_mov_b32_e32 v47, v33
	v_bitop3_b32 v48, v32, v48, v49 bitop3:0xf6
	v_mov_b32_e32 v49, v33
	s_sub_i32 s39, s18, s39
	v_add_u32_e32 v66, v73, v66
	v_add_u32_e32 v67, v73, v67
	v_add_u32_e32 v68, v73, v68
	v_add_u32_e32 v69, v73, v69
	v_add_u32_e32 v70, v73, v70
	v_add_u32_e32 v71, v73, v71
	v_add_u32_e32 v72, v73, v72
	v_add_u32_e32 v73, v73, v74
	s_waitcnt vmcnt(0)
	s_branch .LBB0_1062

; __device__ __forceinline__ void convert_t(const float* __restrict__ W, int K, int N, bf16_t* __restrict__ Wt, int swiglu, int& cursor, float* tile, int perm) {
;     ...
;     for (; id < last; id += G) {
;         const int tl = (id - first) % nt; const int k0 = (tl / ntn) * 64, n0 = (tl % ntn) * 256;
; #pragma unroll
;         for (int i = 0; i < 8; ++i) { const int idx = tid + 512 * i; const int row = idx >> 6, c4 = idx & 63; float* d = tile + row * 257 + 4 * c4; d[0] = v[i].x; d[1] = v[i].y; d[2] = v[i].z; d[3] = v[i].w; }
;         __syncthreads();
;         if (id + G < last) { const int tl2 = (id + G - first) % nt; const int k2 = (tl2 / ntn) * 64, n2 = (tl2 % ntn) * 256;
; #pragma unroll
;             for (int i = 0; i < 8; ++i) { const int idx = tid + 512 * i; const int row = idx >> 6, c4 = idx & 63; v[i] = *(const float4*)(W + (size_t)(k2 + row) * N + n2 + 4 * c4); } }
.LBB0_1062:
	s_add_i32 s18, s30, s39
	s_cmp_ge_i32 s18, s37
	s_waitcnt vmcnt(11)
	ds_write2_b32 v66, v0, v1 offset1:1
	ds_write2_b32 v66, v2, v3 offset0:2 offset1:3
	s_waitcnt vmcnt(10)
	ds_write2_b32 v67, v4, v5 offset1:1
	ds_write2_b32 v67, v6, v7 offset0:2 offset1:3
	s_waitcnt vmcnt(9)
	ds_write2_b32 v68, v8, v9 offset1:1
	ds_write2_b32 v68, v10, v11 offset0:2 offset1:3
	s_waitcnt vmcnt(8)
	ds_write2_b32 v69, v12, v13 offset1:1
	ds_write2_b32 v69, v14, v15 offset0:2 offset1:3
	s_waitcnt vmcnt(7)
	ds_write2_b32 v70, v16, v17 offset1:1
	ds_write2_b32 v70, v18, v19 offset0:2 offset1:3
	s_waitcnt vmcnt(6)
	ds_write2_b32 v71, v20, v21 offset1:1
	ds_write2_b32 v71, v22, v23 offset0:2 offset1:3
	s_waitcnt vmcnt(5)
	ds_write2_b32 v72, v24, v25 offset1:1
	ds_write2_b32 v72, v26, v27 offset0:2 offset1:3
	s_waitcnt vmcnt(4)
	ds_write2_b32 v73, v28, v29 offset1:1
	ds_write2_b32 v73, v30, v31 offset0:2 offset1:3
	s_waitcnt lgkmcnt(0)
	s_barrier
	s_cbranch_scc1 .LBB0_1061
	s_ashr_i32 s18, s39, 31
	s_lshr_b32 s18, s18, 25
	s_add_i32 s18, s39, s18
	s_and_b32 s18, s18, 0xff80
	s_sub_i32 s18, s39, s18
	s_bfe_i32 s19, s18, 0x80000
	s_bfe_u32 s19, s19, 0x3000c
	s_add_i32 s19, s18, s19
	s_bfe_i32 s46, s19, 0x80000
	s_sext_i32_i16 s46, s46
	s_and_b32 s19, s19, 0xf8
	s_lshl_b32 s46, s46, 3
	s_sub_i32 s18, s18, s19
	s_andn2_b32 s46, s46, 63
	s_sext_i32_i8 s18, s18
	s_lshl_b32 s18, s18, 8
	v_add_u32_e32 v0, s46, v50
	s_ashr_i32 s19, s18, 31
	v_ashrrev_i32_e32 v1, 31, v0
	v_lshl_add_u64 v[24:25], s[18:19], 2, v[34:35]
	v_lshlrev_b64 v[0:1], 13, v[0:1]
	v_lshl_add_u64 v[8:9], v[24:25], 0, v[0:1]
	v_add_u32_e32 v0, s46, v51
	v_ashrrev_i32_e32 v1, 31, v0
	v_lshlrev_b64 v[0:1], 13, v[0:1]
	v_lshl_add_u64 v[10:11], v[24:25], 0, v[0:1]
	global_load_dwordx4 v[0:3], v[8:9], off
	global_load_dwordx4 v[4:7], v[10:11], off
	v_add_u32_e32 v8, s46, v52
	v_ashrrev_i32_e32 v9, 31, v8
	v_lshlrev_b64 v[8:9], 13, v[8:9]
	v_lshl_add_u64 v[16:17], v[24:25], 0, v[8:9]
	v_add_u32_e32 v8, s46, v53
	v_ashrrev_i32_e32 v9, 31, v8
	v_lshlrev_b64 v[8:9], 13, v[8:9]
	v_lshl_add_u64 v[18:19], v[24:25], 0, v[8:9]
	global_load_dwordx4 v[8:11], v[16:17], off
	global_load_dwordx4 v[12:15], v[18:19], off
	v_add_u32_e32 v16, s46, v54
	v_ashrrev_i32_e32 v17, 31, v16
	v_lshlrev_b64 v[16:17], 13, v[16:17]
	v_lshl_add_u64 v[26:27], v[24:25], 0, v[16:17]
	v_add_u32_e32 v16, s46, v55
	v_ashrrev_i32_e32 v17, 31, v16
	v_lshlrev_b64 v[16:17], 13, v[16:17]
	v_lshl_add_u64 v[28:29], v[24:25], 0, v[16:17]
	global_load_dwordx4 v[16:19], v[26:27], off
	global_load_dwordx4 v[20:23], v[28:29], off
	v_add_u32_e32 v26, s46, v56
	v_ashrrev_i32_e32 v27, 31, v26
	v_lshlrev_b64 v[26:27], 13, v[26:27]
	v_lshl_add_u64 v[74:75], v[24:25], 0, v[26:27]
	v_add_u32_e32 v26, s46, v57
	v_ashrrev_i32_e32 v27, 31, v26
	v_lshlrev_b64 v[26:27], 13, v[26:27]
	v_lshl_add_u64 v[76:77], v[24:25], 0, v[26:27]
	global_load_dwordx4 v[24:27], v[74:75], off
	global_load_dwordx4 v[28:31], v[76:77], off
	s_branch .LBB0_1061
; __device__ __forceinline__ unsigned cvt_pk_bf16(float lo, float hi) { unsigned r; asm volatile("v_cvt_pk_bf16_f32 %0, %1, %2" : "=v"(r) : "v"(lo), "v"(hi)); return r; }
; __device__ __forceinline__ void convert_t(const float* __restrict__ W, int K, int N, bf16_t* __restrict__ Wt, int swiglu, int& cursor, float* tile, int perm) {
;     ...
;     const int tid = tix_, G = gdim_; const int ntn = N / 256, nt = (K / 64) * ntn;
;     const int first = cursor; cursor += nt;
;     int id = first + (((int)bid_ - (first % G)) + G) % G;
;     const int last = first + nt * CONV_REP;
;     float4 v[8];
;     if (id < last) { const int tl = (id - first) % nt; const int k0 = (tl / ntn) * 64, n0 = (tl % ntn) * 256;
; #pragma unroll
;         for (int i = 0; i < 8; ++i) { const int idx = tid + 512 * i; const int row = idx >> 6, c4 = idx & 63; v[i] = *(const float4*)(W + (size_t)(k0 + row) * N + n0 + 4 * c4); } }
;     ...
;         for (int p = 0; p < 4; ++p) { const int nl = (tid >> 3) + 64 * p, kq = tid & 7; const float* s = tile + (8 * kq) * 257 + nl;
;             u32x4 w; w.x = cvt_pk_bf16(s[0], s[257]); w.y = cvt_pk_bf16(s[2 * 257], s[3 * 257]); w.z = cvt_pk_bf16(s[4 * 257], s[5 * 257]); w.w = cvt_pk_bf16(s[6 * 257], s[7 * 257]);
;             int n = n0 + nl; if (swiglu) { const int half = n >= DFF ? 1 : 0; const int c = n - half * DFF; n = (c >> 7) * 256 + half * 128 + (c & 127); }
;             { const int pn = n >> 8, half = (n >> 7) & 1, r = n & 127, c5 = r & 31;
;               const int R = perm ? ((r & ~31) + 16 * ((c5 >> 2) & 1) + 4 * (c5 >> 3) + (c5 & 3)) : r;
;               *(u32x4*)((unsigned char*)Wt + ((size_t)pn * (K >> 6) + (k0 >> 6)) * 32768 + half * 16384 + pg8::lds_byte(R, 8 * kq)) = w; } }
.LBB0_1064:
	s_mov_b32 s12, s2
	s_mov_b32 s20, s40
	s_abs_i32 s13, s20
	s_waitcnt vmcnt(11)
	v_cvt_f32_u32_e32 v0, s13
	s_sub_i32 s14, 0, s13
	v_mov_b32_e32 v36, v228
	v_rcp_iflag_f32_e32 v0, v0
	s_nop 0
	v_mul_f32_e32 v0, 0x4f7ffffe, v0
	v_cvt_u32_f32_e32 v0, v0
	s_nop 0
	v_readfirstlane_b32 s15, v0
	s_mul_i32 s14, s14, s15
	s_mul_hi_u32 s14, s15, s14
	s_add_i32 s15, s15, s14
	s_mul_hi_u32 s14, s15, 0xfd0
	s_mul_i32 s14, s14, s13
	s_sub_i32 s14, 0xfd0, s14
	s_sub_i32 s18, s14, s13
	s_cmp_ge_u32 s14, s13
	s_cselect_b32 s14, s18, s14
	s_sub_i32 s18, s14, s13
	s_cmp_ge_u32 s14, s13
	s_cselect_b32 s14, s18, s14
	s_add_i32 s12, s20, s12
	s_sub_i32 s12, s12, s14
	s_ashr_i32 s14, s12, 31
	s_abs_i32 s12, s12
	s_mul_hi_u32 s15, s12, s15
	s_mul_i32 s15, s15, s13
	s_sub_i32 s12, s12, s15
	s_sub_i32 s15, s12, s13
	s_cmp_ge_u32 s12, s13
	s_cselect_b32 s12, s15, s12
	s_sub_i32 s15, s12, s13
	s_cmp_ge_u32 s12, s13
	s_cselect_b32 s12, s15, s12
	s_xor_b32 s12, s12, s14
	s_sub_i32 s18, s12, s14
	s_cmpk_gt_i32 s18, 0xff
	s_cbranch_scc1 .LBB0_1069
	s_add_u32 s12, s24, 0x7e80000
	s_addc_u32 s13, s25, 0
	s_add_u32 s14, s22, 0x1000000
	s_addc_u32 s15, s23, 0
	s_ashr_i32 s19, s18, 31
	s_lshr_b32 s19, s19, 24
	s_add_i32 s19, s18, s19
	s_and_b32 s19, s19, 0xff00
	s_sub_i32 s19, s18, s19
	s_sext_i32_i16 s21, s19
	s_bfe_u32 s21, s21, 0x3001c
	s_add_i32 s21, s19, s21
	s_sext_i32_i16 s22, s21
	s_and_b32 s21, s21, 0xfff8
	s_sub_i32 s19, s19, s21
	s_lshl_b32 s22, s22, 3
	s_sext_i32_i16 s19, s19
	s_and_b32 s28, s22, 0xffffffc0
	s_lshl_b32 s22, s19, 8
	s_ashr_i32 s23, s22, 31
	s_lshl_b64 s[22:23], s[22:23], 2
	v_ashrrev_i32_e32 v50, 6, v36
	s_add_u32 s22, s14, s22
	v_lshlrev_b32_e32 v37, 4, v36
	v_add_u32_e32 v0, s28, v50
	s_addc_u32 s23, s15, s23
	v_and_b32_e32 v32, 0x3f0, v37
	v_mov_b32_e32 v33, 0
	v_ashrrev_i32_e32 v1, 31, v0
	s_waitcnt vmcnt(5)
	v_lshl_add_u64 v[24:25], s[22:23], 0, v[32:33]
	v_lshlrev_b64 v[0:1], 13, v[0:1]
	v_lshl_add_u64 v[8:9], v[24:25], 0, v[0:1]
	v_add_u32_e32 v0, 0x200, v36
	v_ashrrev_i32_e32 v51, 6, v0
	v_add_u32_e32 v0, s28, v51
	v_ashrrev_i32_e32 v1, 31, v0
	v_lshlrev_b64 v[0:1], 13, v[0:1]
	v_lshl_add_u64 v[10:11], v[24:25], 0, v[0:1]
	global_load_dwordx4 v[0:3], v[8:9], off
	global_load_dwordx4 v[4:7], v[10:11], off
	v_add_u32_e32 v8, 0x400, v36
	v_ashrrev_i32_e32 v52, 6, v8
	v_add_u32_e32 v8, s28, v52
	v_ashrrev_i32_e32 v9, 31, v8
	v_lshlrev_b64 v[8:9], 13, v[8:9]
	v_lshl_add_u64 v[16:17], v[24:25], 0, v[8:9]
	v_add_u32_e32 v8, 0x600, v36
	v_ashrrev_i32_e32 v53, 6, v8
	v_add_u32_e32 v8, s28, v53
	v_ashrrev_i32_e32 v9, 31, v8
	v_lshlrev_b64 v[8:9], 13, v[8:9]
	v_lshl_add_u64 v[18:19], v[24:25], 0, v[8:9]
	global_load_dwordx4 v[8:11], v[16:17], off
	global_load_dwordx4 v[12:15], v[18:19], off
	v_add_u32_e32 v16, 0x800, v36
	v_ashrrev_i32_e32 v54, 6, v16
	v_add_u32_e32 v16, s28, v54
	v_ashrrev_i32_e32 v17, 31, v16
	v_lshlrev_b64 v[16:17], 13, v[16:17]
	v_lshl_add_u64 v[26:27], v[24:25], 0, v[16:17]
	v_add_u32_e32 v16, 0xa00, v36
	v_ashrrev_i32_e32 v55, 6, v16
	v_add_u32_e32 v16, s28, v55
	v_ashrrev_i32_e32 v17, 31, v16
	v_lshlrev_b64 v[16:17], 13, v[16:17]
	s_waitcnt vmcnt(8)
	v_lshl_add_u64 v[28:29], v[24:25], 0, v[16:17]
	global_load_dwordx4 v[16:19], v[26:27], off
	global_load_dwordx4 v[20:23], v[28:29], off
	v_add_u32_e32 v26, 0xc00, v36
	v_ashrrev_i32_e32 v56, 6, v26
	v_add_u32_e32 v26, s28, v56
	v_ashrrev_i32_e32 v27, 31, v26
	v_lshlrev_b64 v[26:27], 13, v[26:27]
	v_lshl_add_u64 v[34:35], v[24:25], 0, v[26:27]
	v_add_u32_e32 v26, 0xe00, v36
	v_ashrrev_i32_e32 v57, 6, v26
	v_add_u32_e32 v26, s28, v57
	v_ashrrev_i32_e32 v27, 31, v26
	v_lshlrev_b64 v[26:27], 13, v[26:27]
	v_lshl_add_u64 v[38:39], v[24:25], 0, v[26:27]
	global_load_dwordx4 v[24:27], v[34:35], off
	global_load_dwordx4 v[28:31], v[38:39], off
	v_add_u32_e32 v73, 0, v32
	v_lshl_add_u64 v[34:35], s[14:15], 0, v[32:33]
	v_lshlrev_b32_e32 v32, 3, v36
	v_ashrrev_i32_e32 v58, 3, v36
	v_and_b32_e32 v36, 56, v32
	v_mul_u32_u24_e32 v36, 0x404, v36
	v_bfe_u32 v59, v32, 5, 1
	v_and_b32_e32 v32, 48, v37
	v_lshlrev_b32_e32 v37, 2, v58
	v_add3_u32 v60, 0, v36, v37
	v_lshrrev_b32_e32 v36, 1, v58
	v_and_b32_e32 v37, 3, v58
	v_and_or_b32 v38, v36, 12, v37
	v_lshlrev_b32_e32 v39, 1, v58
	v_add_u32_e32 v61, 64, v58
	v_lshlrev_b32_e32 v38, 6, v38
	v_and_b32_e32 v49, 32, v39
	v_or_b32_e32 v48, v38, v32
	v_bitop3_b32 v65, v38, v49, v32 bitop3:0x36
	v_and_b32_e32 v32, 0x60, v61
	v_lshlrev_b32_e32 v38, 2, v61
	v_and_or_b32 v32, v38, 16, v32
	v_lshrrev_b32_e32 v32, 3, v32
	v_or_b32_e32 v32, v32, v59
	v_add_u32_e32 v62, 0x80, v58
	v_lshlrev_b32_e32 v32, 10, v32
	v_and_b32_e32 v64, 0x60, v58
	v_bitop3_b32 v40, v32, v48, v49 bitop3:0xf6
	v_lshlrev_b32_e32 v32, 2, v62
	v_and_or_b32 v32, v32, 16, v64
	v_lshrrev_b32_e32 v32, 3, v32
	v_or_b32_e32 v32, v32, v59
	v_add_u32_e32 v63, 0xc0, v58
	v_lshlrev_b32_e32 v32, 10, v32
	v_bitop3_b32 v44, v32, v48, v49 bitop3:0xf6
	v_and_b32_e32 v32, 0x60, v63
	v_lshlrev_b32_e32 v46, 2, v63
	v_and_or_b32 v32, v46, 16, v32
	v_lshrrev_b32_e32 v32, 3, v32
	s_movk_i32 s14, 0x404
	v_or_b32_e32 v32, v32, v59
	v_mul_lo_u32 v66, v50, s14
	v_mul_lo_u32 v67, v51, s14
	v_mul_lo_u32 v68, v52, s14
	v_mul_lo_u32 v69, v53, s14
	v_mul_lo_u32 v70, v54, s14
	v_mul_lo_u32 v71, v55, s14
	v_mul_lo_u32 v72, v56, s14
	v_mul_lo_u32 v74, v57, s14
	v_lshlrev_b32_e32 v36, 7, v58
	v_lshlrev_b32_e32 v38, 7, v61
	v_lshlrev_b32_e32 v42, 7, v62
	v_lshlrev_b32_e32 v46, 7, v63
	v_lshlrev_b32_e32 v32, 10, v32
	v_and_b32_e32 v36, 0x4000, v36
	v_mov_b32_e32 v37, v33
	v_and_b32_e32 v38, 0x4000, v38
	v_mov_b32_e32 v39, v33
	v_mov_b32_e32 v41, v33
	v_and_b32_e32 v42, 0x4000, v42
	v_mov_b32_e32 v43, v33
	v_mov_b32_e32 v45, v33
	v_and_b32_e32 v46, 0x4000, v46
	v_mov_b32_e32 v47, v33
	v_bitop3_b32 v48, v32, v48, v49 bitop3:0xf6
	v_mov_b32_e32 v49, v33
	v_add_u32_e32 v66, v73, v66
	v_add_u32_e32 v67, v73, v67
	v_add_u32_e32 v68, v73, v68
	v_add_u32_e32 v69, v73, v69
	v_add_u32_e32 v70, v73, v70
	v_add_u32_e32 v71, v73, v71
	v_add_u32_e32 v72, v73, v72
	v_add_u32_e32 v73, v73, v74
	s_waitcnt vmcnt(0)
	s_branch .LBB0_1067

; __device__ __forceinline__ void convert_t(const float* __restrict__ W, int K, int N, bf16_t* __restrict__ Wt, int swiglu, int& cursor, float* tile, int perm) {
;     ...
;     for (; id < last; id += G) {
;         const int tl = (id - first) % nt; const int k0 = (tl / ntn) * 64, n0 = (tl % ntn) * 256;
; #pragma unroll
;         for (int i = 0; i < 8; ++i) { const int idx = tid + 512 * i; const int row = idx >> 6, c4 = idx & 63; float* d = tile + row * 257 + 4 * c4; d[0] = v[i].x; d[1] = v[i].y; d[2] = v[i].z; d[3] = v[i].w; }
;         __syncthreads();
;         if (id + G < last) { const int tl2 = (id + G - first) % nt; const int k2 = (tl2 / ntn) * 64, n2 = (tl2 % ntn) * 256;
; #pragma unroll
;             for (int i = 0; i < 8; ++i) { const int idx = tid + 512 * i; const int row = idx >> 6, c4 = idx & 63; v[i] = *(const float4*)(W + (size_t)(k2 + row) * N + n2 + 4 * c4); } }
.LBB0_1067:
	s_add_i32 s21, s20, s18
	s_add_i32 s14, s21, 0xfd0
	s_cmpk_gt_i32 s14, 0x10cf
	s_cselect_b64 s[14:15], -1, 0
	s_and_b64 vcc, exec, s[14:15]
	s_waitcnt vmcnt(11)
	ds_write2_b32 v66, v0, v1 offset1:1
	ds_write2_b32 v66, v2, v3 offset0:2 offset1:3
	s_waitcnt vmcnt(10)
	ds_write2_b32 v67, v4, v5 offset1:1
	ds_write2_b32 v67, v6, v7 offset0:2 offset1:3
	s_waitcnt vmcnt(9)
	ds_write2_b32 v68, v8, v9 offset1:1
	ds_write2_b32 v68, v10, v11 offset0:2 offset1:3
	s_waitcnt vmcnt(8)
	ds_write2_b32 v69, v12, v13 offset1:1
	ds_write2_b32 v69, v14, v15 offset0:2 offset1:3
	s_waitcnt vmcnt(7)
	ds_write2_b32 v70, v16, v17 offset1:1
	ds_write2_b32 v70, v18, v19 offset0:2 offset1:3
	s_waitcnt vmcnt(6)
	ds_write2_b32 v71, v20, v21 offset1:1
	ds_write2_b32 v71, v22, v23 offset0:2 offset1:3
	s_waitcnt vmcnt(5)
	ds_write2_b32 v72, v24, v25 offset1:1
	ds_write2_b32 v72, v26, v27 offset0:2 offset1:3
	s_waitcnt vmcnt(4)
	ds_write2_b32 v73, v28, v29 offset1:1
	ds_write2_b32 v73, v30, v31 offset0:2 offset1:3
	s_waitcnt lgkmcnt(0)
	s_barrier
	s_cbranch_vccnz .LBB0_1066
	s_ashr_i32 s19, s21, 31
	s_lshr_b32 s19, s19, 24
	s_add_i32 s19, s21, s19
	s_and_b32 s19, s19, 0xff00
	s_sub_i32 s19, s21, s19
	s_sext_i32_i16 s22, s19
	s_bfe_u32 s22, s22, 0x3001c
	s_add_i32 s22, s19, s22
	s_sext_i32_i16 s23, s22
	s_and_b32 s22, s22, 0xfff8
	s_lshl_b32 s23, s23, 3
	s_sub_i32 s19, s19, s22
	s_and_b32 s28, s23, 0xffffffc0
	s_sext_i32_i16 s19, s19
	s_lshl_b32 s22, s19, 8
	v_add_u32_e32 v0, s28, v50
	s_ashr_i32 s23, s22, 31
	v_ashrrev_i32_e32 v1, 31, v0
	v_lshl_add_u64 v[24:25], s[22:23], 2, v[34:35]
	v_lshlrev_b64 v[0:1], 13, v[0:1]
	v_lshl_add_u64 v[8:9], v[24:25], 0, v[0:1]
	v_add_u32_e32 v0, s28, v51
	v_ashrrev_i32_e32 v1, 31, v0
	v_lshlrev_b64 v[0:1], 13, v[0:1]
	v_lshl_add_u64 v[10:11], v[24:25], 0, v[0:1]
	global_load_dwordx4 v[0:3], v[8:9], off
	global_load_dwordx4 v[4:7], v[10:11], off
	v_add_u32_e32 v8, s28, v52
	v_ashrrev_i32_e32 v9, 31, v8
	v_lshlrev_b64 v[8:9], 13, v[8:9]
	v_lshl_add_u64 v[16:17], v[24:25], 0, v[8:9]
	v_add_u32_e32 v8, s28, v53
	v_ashrrev_i32_e32 v9, 31, v8
	v_lshlrev_b64 v[8:9], 13, v[8:9]
	v_lshl_add_u64 v[18:19], v[24:25], 0, v[8:9]
	global_load_dwordx4 v[8:11], v[16:17], off
	global_load_dwordx4 v[12:15], v[18:19], off
	v_add_u32_e32 v16, s28, v54
	v_ashrrev_i32_e32 v17, 31, v16
	v_lshlrev_b64 v[16:17], 13, v[16:17]
	v_lshl_add_u64 v[26:27], v[24:25], 0, v[16:17]
	v_add_u32_e32 v16, s28, v55
	v_ashrrev_i32_e32 v17, 31, v16
	v_lshlrev_b64 v[16:17], 13, v[16:17]
	v_lshl_add_u64 v[28:29], v[24:25], 0, v[16:17]
	global_load_dwordx4 v[16:19], v[26:27], off
	global_load_dwordx4 v[20:23], v[28:29], off
	v_add_u32_e32 v26, s28, v56
	v_ashrrev_i32_e32 v27, 31, v26
	v_lshlrev_b64 v[26:27], 13, v[26:27]
	v_lshl_add_u64 v[74:75], v[24:25], 0, v[26:27]
	v_add_u32_e32 v26, s28, v57
	v_ashrrev_i32_e32 v27, 31, v26
	v_lshlrev_b64 v[26:27], 13, v[26:27]
	v_lshl_add_u64 v[76:77], v[24:25], 0, v[26:27]
	global_load_dwordx4 v[24:27], v[74:75], off
	global_load_dwordx4 v[28:31], v[76:77], off
	s_branch .LBB0_1066
; __device__ __forceinline__ unsigned cvt_pk_bf16(float lo, float hi) { unsigned r; asm volatile("v_cvt_pk_bf16_f32 %0, %1, %2" : "=v"(r) : "v"(lo), "v"(hi)); return r; }
; __device__ __forceinline__ void convert_t(const float* __restrict__ W, int K, int N, bf16_t* __restrict__ Wt, int swiglu, int& cursor, float* tile, int perm) {
;     ...
;     const int tid = tix_, G = gdim_; const int ntn = N / 256, nt = (K / 64) * ntn;
;     const int first = cursor; cursor += nt;
;     int id = first + (((int)bid_ - (first % G)) + G) % G;
;     const int last = first + nt * CONV_REP;
;     float4 v[8];
;     if (id < last) { const int tl = (id - first) % nt; const int k0 = (tl / ntn) * 64, n0 = (tl % ntn) * 256;
; #pragma unroll
;         for (int i = 0; i < 8; ++i) { const int idx = tid + 512 * i; const int row = idx >> 6, c4 = idx & 63; v[i] = *(const float4*)(W + (size_t)(k0 + row) * N + n0 + 4 * c4); } }
;     ...
;         for (int p = 0; p < 4; ++p) { const int nl = (tid >> 3) + 64 * p, kq = tid & 7; const float* s = tile + (8 * kq) * 257 + nl;
;             u32x4 w; w.x = cvt_pk_bf16(s[0], s[257]); w.y = cvt_pk_bf16(s[2 * 257], s[3 * 257]); w.z = cvt_pk_bf16(s[4 * 257], s[5 * 257]); w.w = cvt_pk_bf16(s[6 * 257], s[7 * 257]);
;             int n = n0 + nl; if (swiglu) { const int half = n >= DFF ? 1 : 0; const int c = n - half * DFF; n = (c >> 7) * 256 + half * 128 + (c & 127); }
;             { const int pn = n >> 8, half = (n >> 7) & 1, r = n & 127, c5 = r & 31;
;               const int R = perm ? ((r & ~31) + 16 * ((c5 >> 2) & 1) + 4 * (c5 >> 3) + (c5 & 3)) : r;
;               *(u32x4*)((unsigned char*)Wt + ((size_t)pn * (K >> 6) + (k0 >> 6)) * 32768 + half * 16384 + pg8::lds_byte(R, 8 * kq)) = w; } }
.LBB0_1069:
	s_mov_b32 s12, s2
	s_mov_b32 s18, s40
	s_abs_i32 s13, s18
	s_waitcnt vmcnt(11)
	v_cvt_f32_u32_e32 v0, s13
	s_sub_i32 s14, 0, s13
	v_mov_b32_e32 v36, v228
	v_rcp_iflag_f32_e32 v0, v0
	s_nop 0
	v_mul_f32_e32 v0, 0x4f7ffffe, v0
	v_cvt_u32_f32_e32 v0, v0
	s_nop 0
	v_readfirstlane_b32 s15, v0
	s_mul_i32 s14, s14, s15
	s_mul_hi_u32 s14, s15, s14
	s_add_i32 s15, s15, s14
	s_mul_hi_u32 s14, s15, 0x10d0
	s_mul_i32 s14, s14, s13
	s_sub_i32 s14, 0x10d0, s14
	s_sub_i32 s19, s14, s13
	s_cmp_ge_u32 s14, s13
	s_cselect_b32 s14, s19, s14
	s_sub_i32 s19, s14, s13
	s_cmp_ge_u32 s14, s13
	s_cselect_b32 s14, s19, s14
	s_add_i32 s12, s18, s12
	s_sub_i32 s12, s12, s14
	s_ashr_i32 s14, s12, 31
	s_abs_i32 s12, s12
	s_mul_hi_u32 s15, s12, s15
	s_mul_i32 s15, s15, s13
	s_sub_i32 s12, s12, s15
	s_sub_i32 s15, s12, s13
	s_cmp_ge_u32 s12, s13
	s_cselect_b32 s12, s15, s12
	s_sub_i32 s15, s12, s13
	s_cmp_ge_u32 s12, s13
	s_cselect_b32 s12, s15, s12
	s_xor_b32 s12, s12, s14
	s_sub_i32 s14, s12, s14
	s_cmpk_gt_i32 s14, 0x55f
	s_cbranch_scc1 .LBB0_1074
	s_add_u32 s12, s24, 0x8680000
	s_addc_u32 s13, s25, 0
	s_add_u32 s4, s4, 0x5600000
	s_mul_hi_i32 s15, s14, 0x2fa0be83
	s_addc_u32 s5, s5, 0
	s_lshr_b32 s19, s15, 31
	s_ashr_i32 s15, s15, 8
	s_add_i32 s15, s15, s19
	s_mulk_i32 s15, 0x560
	s_sub_i32 s15, s14, s15
	s_sext_i32_i16 s19, s15
	s_mulk_i32 s19, 0x2fa1
	s_lshr_b32 s20, s19, 31
	s_ashr_i32 s19, s19, 19
	s_add_i32 s19, s19, s20
	s_sext_i32_i16 s20, s19
	s_mul_i32 s19, s19, 43
	s_sub_i32 s15, s15, s19
	s_sext_i32_i16 s15, s15
	s_lshl_b32 s22, s20, 6
	s_lshl_b32 s20, s15, 8
	s_ashr_i32 s21, s20, 31
	s_lshl_b64 s[20:21], s[20:21], 2
	s_add_u32 s20, s4, s20
	v_lshlrev_b32_e32 v37, 4, v36
	s_addc_u32 s21, s5, s21
	v_and_b32_e32 v32, 0x3f0, v37
	v_mov_b32_e32 v33, 0
	v_ashrrev_i32_e32 v42, 6, v36
	s_waitcnt vmcnt(5)
	v_lshl_add_u64 v[24:25], s[20:21], 0, v[32:33]
	v_add_u32_e32 v0, s22, v42
	s_mov_b32 s19, 0xac00
	v_mad_i64_i32 v[8:9], s[20:21], v0, s19, v[24:25]
	v_add_u32_e32 v0, 0x200, v36
	v_ashrrev_i32_e32 v43, 6, v0
	v_add_u32_e32 v0, s22, v43
	v_mad_i64_i32 v[10:11], s[20:21], v0, s19, v[24:25]
	global_load_dwordx4 v[0:3], v[8:9], off
	global_load_dwordx4 v[4:7], v[10:11], off
	v_add_u32_e32 v8, 0x400, v36
	v_ashrrev_i32_e32 v44, 6, v8
	v_add_u32_e32 v8, s22, v44
	v_mad_i64_i32 v[16:17], s[20:21], v8, s19, v[24:25]
	v_add_u32_e32 v8, 0x600, v36
	v_ashrrev_i32_e32 v45, 6, v8
	v_add_u32_e32 v8, s22, v45
	v_mad_i64_i32 v[18:19], s[20:21], v8, s19, v[24:25]
	global_load_dwordx4 v[8:11], v[16:17], off
	global_load_dwordx4 v[12:15], v[18:19], off
	v_add_u32_e32 v16, 0x800, v36
	v_ashrrev_i32_e32 v46, 6, v16
	v_add_u32_e32 v16, s22, v46
	v_mad_i64_i32 v[26:27], s[20:21], v16, s19, v[24:25]
	v_add_u32_e32 v16, 0xa00, v36
	v_ashrrev_i32_e32 v47, 6, v16
	v_add_u32_e32 v16, s22, v47
	s_waitcnt vmcnt(8)
	v_mad_i64_i32 v[28:29], s[20:21], v16, s19, v[24:25]
	global_load_dwordx4 v[16:19], v[26:27], off
	global_load_dwordx4 v[20:23], v[28:29], off
	v_add_u32_e32 v26, 0xc00, v36
	v_ashrrev_i32_e32 v48, 6, v26
	v_add_u32_e32 v26, s22, v48
	v_mad_i64_i32 v[34:35], s[20:21], v26, s19, v[24:25]
	v_add_u32_e32 v26, 0xe00, v36
	v_ashrrev_i32_e32 v49, 6, v26
	v_add_u32_e32 v26, s22, v49
	v_mad_i64_i32 v[38:39], s[20:21], v26, s19, v[24:25]
	global_load_dwordx4 v[24:27], v[34:35], off
	global_load_dwordx4 v[28:31], v[38:39], off
	v_add_u32_e32 v61, 0, v32
	v_lshl_add_u64 v[34:35], s[4:5], 0, v[32:33]
	v_lshlrev_b32_e32 v32, 3, v36
	v_ashrrev_i32_e32 v50, 3, v36
	v_and_b32_e32 v36, 56, v32
	v_mul_u32_u24_e32 v36, 0x404, v36
	v_lshlrev_b32_e32 v38, 2, v50
	v_add3_u32 v51, 0, v36, v38
	v_and_b32_e32 v36, 0x60, v50
	v_and_or_b32 v36, v38, 16, v36
	v_lshrrev_b32_e32 v38, 1, v50
	v_and_b32_e32 v39, 3, v50
	v_and_b32_e32 v37, 48, v37
	v_add_u32_e32 v52, 64, v50
	v_add_u32_e32 v53, 0xc0, v50
	v_and_or_b32 v38, v38, 12, v39
	v_lshl_or_b32 v40, v38, 6, v37
	v_and_b32_e32 v38, 0x60, v52
	v_lshlrev_b32_e32 v39, 2, v52
	v_and_b32_e32 v63, 0x60, v53
	v_lshlrev_b32_e32 v64, 2, v53
	v_and_or_b32 v38, v39, 16, v38
	v_and_or_b32 v63, v64, 16, v63
	v_bfe_u32 v32, v32, 5, 1
	v_lshrrev_b32_e32 v36, 3, v36
	v_lshrrev_b32_e32 v38, 3, v38
	v_lshrrev_b32_e32 v63, 3, v63
	s_movk_i32 s4, 0x404
	v_or_b32_e32 v36, v36, v32
	v_lshlrev_b32_e32 v37, 1, v50
	v_or_b32_e32 v38, v38, v32
	v_or_b32_e32 v32, v63, v32
	v_mul_lo_u32 v54, v42, s4
	v_mul_lo_u32 v55, v43, s4
	v_mul_lo_u32 v56, v44, s4
	v_mul_lo_u32 v57, v45, s4
	v_mul_lo_u32 v58, v46, s4
	v_mul_lo_u32 v59, v47, s4
	v_mul_lo_u32 v60, v48, s4
	v_mul_lo_u32 v62, v49, s4
	v_lshlrev_b32_e32 v36, 10, v36
	v_and_b32_e32 v41, 32, v37
	v_lshlrev_b32_e32 v38, 10, v38
	v_lshlrev_b32_e32 v32, 10, v32
	v_bitop3_b32 v36, v36, v40, v41 bitop3:0xf6
	v_mov_b32_e32 v37, v33
	v_bitop3_b32 v38, v38, v40, v41 bitop3:0xf6
	v_mov_b32_e32 v39, v33
	v_bitop3_b32 v40, v32, v40, v41 bitop3:0xf6
	v_mov_b32_e32 v41, v33
	v_add_u32_e32 v54, v61, v54
	v_add_u32_e32 v55, v61, v55
	v_add_u32_e32 v56, v61, v56
	v_add_u32_e32 v57, v61, v57
	v_add_u32_e32 v58, v61, v58
	v_add_u32_e32 v59, v61, v59
	v_add_u32_e32 v60, v61, v60
	v_add_u32_e32 v61, v61, v62
	s_movk_i32 s20, 0x157f
	v_mov_b32_e32 v62, 0xffffea80
	v_mov_b32_e32 v63, 0x4000
	s_waitcnt vmcnt(0)
	s_branch .LBB0_1072

; __device__ __forceinline__ void convert_t(const float* __restrict__ W, int K, int N, bf16_t* __restrict__ Wt, int swiglu, int& cursor, float* tile, int perm) {
;     ...
;     for (; id < last; id += G) {
;         const int tl = (id - first) % nt; const int k0 = (tl / ntn) * 64, n0 = (tl % ntn) * 256;
; #pragma unroll
;         for (int i = 0; i < 8; ++i) { const int idx = tid + 512 * i; const int row = idx >> 6, c4 = idx & 63; float* d = tile + row * 257 + 4 * c4; d[0] = v[i].x; d[1] = v[i].y; d[2] = v[i].z; d[3] = v[i].w; }
;         __syncthreads();
;         if (id + G < last) { const int tl2 = (id + G - first) % nt; const int k2 = (tl2 / ntn) * 64, n2 = (tl2 % ntn) * 256;
; #pragma unroll
;             for (int i = 0; i < 8; ++i) { const int idx = tid + 512 * i; const int row = idx >> 6, c4 = idx & 63; v[i] = *(const float4*)(W + (size_t)(k2 + row) * N + n2 + 4 * c4); } }
.LBB0_1072:
	s_add_i32 s21, s18, s14
	s_add_i32 s4, s21, 0x10d0
	s_cmpk_gt_i32 s4, 0x162f
	s_cselect_b64 s[4:5], -1, 0
	s_and_b64 vcc, exec, s[4:5]
	s_waitcnt vmcnt(11)
	ds_write2_b32 v54, v0, v1 offset1:1
	ds_write2_b32 v54, v2, v3 offset0:2 offset1:3
	s_waitcnt vmcnt(10)
	ds_write2_b32 v55, v4, v5 offset1:1
	ds_write2_b32 v55, v6, v7 offset0:2 offset1:3
	s_waitcnt vmcnt(9)
	ds_write2_b32 v56, v8, v9 offset1:1
	ds_write2_b32 v56, v10, v11 offset0:2 offset1:3
	s_waitcnt vmcnt(8)
	ds_write2_b32 v57, v12, v13 offset1:1
	ds_write2_b32 v57, v14, v15 offset0:2 offset1:3
	s_waitcnt vmcnt(7)
	ds_write2_b32 v58, v16, v17 offset1:1
	ds_write2_b32 v58, v18, v19 offset0:2 offset1:3
	s_waitcnt vmcnt(6)
	ds_write2_b32 v59, v20, v21 offset1:1
	ds_write2_b32 v59, v22, v23 offset0:2 offset1:3
	s_waitcnt vmcnt(5)
	ds_write2_b32 v60, v24, v25 offset1:1
	ds_write2_b32 v60, v26, v27 offset0:2 offset1:3
	s_waitcnt vmcnt(4)
	ds_write2_b32 v61, v28, v29 offset1:1
	ds_write2_b32 v61, v30, v31 offset0:2 offset1:3
	s_waitcnt lgkmcnt(0)
	s_barrier
	s_cbranch_vccnz .LBB0_1071
	s_mul_hi_i32 s15, s21, 0x2fa0be83
	s_lshr_b32 s22, s15, 31
	s_ashr_i32 s15, s15, 8
	s_add_i32 s15, s15, s22
	s_mulk_i32 s15, 0x560
	s_sub_i32 s15, s21, s15
	s_sext_i32_i16 s22, s15
	s_mulk_i32 s22, 0x2fa1
	s_lshr_b32 s23, s22, 31
	s_ashr_i32 s22, s22, 19
	s_add_i32 s22, s22, s23
	s_lshl_b32 s28, s22, 6
	s_mul_i32 s22, s22, 43
	s_sub_i32 s15, s15, s22
	s_sext_i32_i16 s15, s15
	s_lshl_b32 s22, s15, 8
	s_ashr_i32 s23, s22, 31
	v_lshl_add_u64 v[24:25], s[22:23], 2, v[34:35]
	v_add_u32_e32 v0, s28, v42
	v_mad_i64_i32 v[8:9], s[22:23], v0, s19, v[24:25]
	v_add_u32_e32 v0, s28, v43
	v_mad_i64_i32 v[10:11], s[22:23], v0, s19, v[24:25]
	global_load_dwordx4 v[0:3], v[8:9], off
	global_load_dwordx4 v[4:7], v[10:11], off
	v_add_u32_e32 v8, s28, v44
	v_mad_i64_i32 v[16:17], s[22:23], v8, s19, v[24:25]
	v_add_u32_e32 v8, s28, v45
	v_mad_i64_i32 v[18:19], s[22:23], v8, s19, v[24:25]
	global_load_dwordx4 v[8:11], v[16:17], off
	global_load_dwordx4 v[12:15], v[18:19], off
	v_add_u32_e32 v16, s28, v46
	v_mad_i64_i32 v[26:27], s[22:23], v16, s19, v[24:25]
	v_add_u32_e32 v16, s28, v47
	v_mad_i64_i32 v[28:29], s[22:23], v16, s19, v[24:25]
	global_load_dwordx4 v[16:19], v[26:27], off
	global_load_dwordx4 v[20:23], v[28:29], off
	v_add_u32_e32 v26, s28, v48
	v_mad_i64_i32 v[64:65], s[22:23], v26, s19, v[24:25]
	v_add_u32_e32 v26, s28, v49
	v_mad_i64_i32 v[66:67], s[22:23], v26, s19, v[24:25]
	global_load_dwordx4 v[24:27], v[64:65], off
	global_load_dwordx4 v[28:31], v[66:67], off
	s_branch .LBB0_1071
; __device__ __forceinline__ void convert_t(const float* __restrict__ W, int K, int N, bf16_t* __restrict__ Wt, int swiglu, int& cursor, float* tile, int perm) {
;     int bid_ = blockIdx.x, gdim_ = gridDim.x; asm volatile("" : "+s"(bid_), "+s"(gdim_));
;     int tix_ = threadIdx.x; asm volatile("" : "+v"(tix_));
;     const int tid = tix_, G = gdim_; const int ntn = N / 256, nt = (K / 64) * ntn;
;     const int first = cursor; cursor += nt;
;     int id = first + (((int)bid_ - (first % G)) + G) % G;
;     const int last = first + nt * CONV_REP;
;     float4 v[8];
;     if (id < last) { const int tl = (id - first) % nt; const int k0 = (tl / ntn) * 64, n0 = (tl % ntn) * 256;
; #pragma unroll
;         for (int i = 0; i < 8; ++i) { const int idx = tid + 512 * i; const int row = idx >> 6, c4 = idx & 63; v[i] = *(const float4*)(W + (size_t)(k0 + row) * N + n0 + 4 * c4); } }
;     for (; id < last; id += G) {
;         const int tl = (id - first) % nt; const int k0 = (tl / ntn) * 64, n0 = (tl % ntn) * 256;
; #pragma unroll
;         for (int i = 0; i < 8; ++i) { const int idx = tid + 512 * i; const int row = idx >> 6, c4 = idx & 63; float* d = tile + row * 257 + 4 * c4; d[0] = v[i].x; d[1] = v[i].y; d[2] = v[i].z; d[3] = v[i].w; }
;         __syncthreads();
;         if (id + G < last) { const int tl2 = (id + G - first) % nt; const int k2 = (tl2 / ntn) * 64, n2 = (tl2 % ntn) * 256;
; #pragma unroll
;             for (int i = 0; i < 8; ++i) { const int idx = tid + 512 * i; const int row = idx >> 6, c4 = idx & 63; v[i] = *(const float4*)(W + (size_t)(k2 + row) * N + n2 + 4 * c4); } }
; #pragma unroll
;         for (int p = 0; p < 4; ++p) { const int nl = (tid >> 3) + 64 * p, kq = tid & 7; const float* s = tile + (8 * kq) * 257 + nl;
;             u32x4 w; w.x = cvt_pk_bf16(s[0], s[257]); w.y = cvt_pk_bf16(s[2 * 257], s[3 * 257]); w.z = cvt_pk_bf16(s[4 * 257], s[5 * 257]); w.w = cvt_pk_bf16(s[6 * 257], s[7 * 257]);
;             int n = n0 + nl; if (swiglu) { const int half = n >= DFF ? 1 : 0; const int c = n - half * DFF; n = (c >> 7) * 256 + half * 128 + (c & 127); }
;             { const int pn = n >> 8, half = (n >> 7) & 1, r = n & 127, c5 = r & 31;
;               const int R = perm ? ((r & ~31) + 16 * ((c5 >> 2) & 1) + 4 * (c5 >> 3) + (c5 & 3)) : r;
.LBB0_1074:
	s_mov_b32 s12, s40
	s_mov_b32 s4, s2
	s_abs_i32 s5, s12
	s_waitcnt vmcnt(11)
	v_cvt_f32_u32_e32 v0, s5
	s_sub_i32 s13, 0, s5
	v_mov_b32_e32 v36, v228
	v_rcp_iflag_f32_e32 v0, v0
	s_nop 0
	v_mul_f32_e32 v0, 0x4f7ffffe, v0
	v_cvt_u32_f32_e32 v0, v0
	s_nop 0
	v_readfirstlane_b32 s14, v0
	s_mul_i32 s13, s13, s14
	s_mul_hi_u32 s13, s14, s13
	s_add_i32 s14, s14, s13
	s_mul_hi_u32 s13, s14, 0x1630
	s_mul_i32 s13, s13, s5
	s_sub_i32 s13, 0x1630, s13
	s_sub_i32 s15, s13, s5
	s_cmp_ge_u32 s13, s5
	s_cselect_b32 s13, s15, s13
	s_sub_i32 s15, s13, s5
	s_cmp_ge_u32 s13, s5
	s_cselect_b32 s13, s15, s13
	s_add_i32 s4, s12, s4
	s_sub_i32 s4, s4, s13
	s_ashr_i32 s13, s4, 31
	s_abs_i32 s4, s4
	s_mul_hi_u32 s14, s4, s14
	s_mul_i32 s14, s14, s5
	s_sub_i32 s4, s4, s14
	s_sub_i32 s14, s4, s5
	s_cmp_ge_u32 s4, s5
	s_cselect_b32 s4, s14, s4
	s_sub_i32 s14, s4, s5
	s_cmp_ge_u32 s4, s5
	s_cselect_b32 s4, s14, s4
	s_xor_b32 s4, s4, s13
	s_sub_i32 s13, s4, s13
	s_cmpk_gt_i32 s13, 0x2af
	s_cbranch_scc1 .LBB0_1079
	s_add_u32 s4, s24, 0xb180000
	s_addc_u32 s5, s25, 0
	s_add_u32 s6, s6, 0x2b00000
	s_mul_hi_i32 s14, s13, 0x2fa0be83
	s_addc_u32 s7, s7, 0
	s_lshr_b32 s15, s14, 31
	s_ashr_i32 s14, s14, 7
	s_add_i32 s14, s14, s15
	s_mulk_i32 s14, 0x2b0
	s_sub_i32 s14, s13, s14
	s_sext_i32_i16 s15, s14
	s_bfe_u32 s15, s15, 0x3001c
	s_add_i32 s15, s14, s15
	s_sext_i32_i16 s18, s15
	s_and_b32 s15, s15, 0xfff8
	s_sub_i32 s14, s14, s15
	s_sext_i32_i16 s14, s14
	s_lshl_b32 s14, s14, 8
	s_lshl_b32 s18, s18, 3
	s_ashr_i32 s15, s14, 31
	s_andn2_b32 s18, s18, 63
	s_lshl_b64 s[14:15], s[14:15], 2
	v_ashrrev_i32_e32 v44, 6, v36
	s_add_u32 s14, s6, s14
	v_lshlrev_b32_e32 v37, 4, v36
	v_add_u32_e32 v0, s18, v44
	s_addc_u32 s15, s7, s15
	v_and_b32_e32 v32, 0x3f0, v37
	v_mov_b32_e32 v33, 0
	v_ashrrev_i32_e32 v1, 31, v0
	s_waitcnt vmcnt(5)
	v_lshl_add_u64 v[24:25], s[14:15], 0, v[32:33]
	v_lshlrev_b64 v[0:1], 13, v[0:1]
	v_lshl_add_u64 v[8:9], v[24:25], 0, v[0:1]
	v_add_u32_e32 v0, 0x200, v36
	v_ashrrev_i32_e32 v45, 6, v0
	v_add_u32_e32 v0, s18, v45
	v_ashrrev_i32_e32 v1, 31, v0
	v_lshlrev_b64 v[0:1], 13, v[0:1]
	v_lshl_add_u64 v[10:11], v[24:25], 0, v[0:1]
	global_load_dwordx4 v[0:3], v[8:9], off
	global_load_dwordx4 v[4:7], v[10:11], off
	v_add_u32_e32 v8, 0x400, v36
	v_ashrrev_i32_e32 v46, 6, v8
	v_add_u32_e32 v8, s18, v46
	v_ashrrev_i32_e32 v9, 31, v8
	v_lshlrev_b64 v[8:9], 13, v[8:9]
	v_lshl_add_u64 v[16:17], v[24:25], 0, v[8:9]
	v_add_u32_e32 v8, 0x600, v36
	v_ashrrev_i32_e32 v47, 6, v8
	v_add_u32_e32 v8, s18, v47
	v_ashrrev_i32_e32 v9, 31, v8
	v_lshlrev_b64 v[8:9], 13, v[8:9]
	v_lshl_add_u64 v[18:19], v[24:25], 0, v[8:9]
	global_load_dwordx4 v[8:11], v[16:17], off
	global_load_dwordx4 v[12:15], v[18:19], off
	v_add_u32_e32 v16, 0x800, v36
	v_ashrrev_i32_e32 v48, 6, v16
	v_add_u32_e32 v16, s18, v48
	v_ashrrev_i32_e32 v17, 31, v16
	v_lshlrev_b64 v[16:17], 13, v[16:17]
	v_lshl_add_u64 v[26:27], v[24:25], 0, v[16:17]
	v_add_u32_e32 v16, 0xa00, v36
	v_ashrrev_i32_e32 v49, 6, v16
	v_add_u32_e32 v16, s18, v49
	v_ashrrev_i32_e32 v17, 31, v16
	v_lshlrev_b64 v[16:17], 13, v[16:17]
	s_waitcnt vmcnt(8)
	v_lshl_add_u64 v[28:29], v[24:25], 0, v[16:17]
	global_load_dwordx4 v[16:19], v[26:27], off
	global_load_dwordx4 v[20:23], v[28:29], off
	v_add_u32_e32 v26, 0xc00, v36
	v_ashrrev_i32_e32 v50, 6, v26
	v_add_u32_e32 v26, s18, v50
	v_ashrrev_i32_e32 v27, 31, v26
	v_lshlrev_b64 v[26:27], 13, v[26:27]
	v_lshl_add_u64 v[34:35], v[24:25], 0, v[26:27]
	v_add_u32_e32 v26, 0xe00, v36
	v_ashrrev_i32_e32 v51, 6, v26
	v_add_u32_e32 v26, s18, v51
	v_ashrrev_i32_e32 v27, 31, v26
	v_lshlrev_b64 v[26:27], 13, v[26:27]
	v_lshl_add_u64 v[38:39], v[24:25], 0, v[26:27]
	global_load_dwordx4 v[24:27], v[34:35], off
	global_load_dwordx4 v[28:31], v[38:39], off
	v_add_u32_e32 v67, 0, v32
	v_lshl_add_u64 v[34:35], s[6:7], 0, v[32:33]
	v_lshlrev_b32_e32 v32, 3, v36
	v_ashrrev_i32_e32 v52, 3, v36
	v_and_b32_e32 v36, 56, v32
	v_mul_u32_u24_e32 v36, 0x404, v36
	v_bfe_u32 v53, v32, 5, 1
	v_lshlrev_b32_e32 v32, 2, v52
	v_add3_u32 v54, 0, v36, v32
	v_lshrrev_b32_e32 v32, 1, v52
	v_and_b32_e32 v36, 3, v52
	v_and_or_b32 v39, v32, 12, v36
	v_lshlrev_b32_e32 v32, 7, v52
	v_and_b32_e32 v32, 0x4000, v32
	v_and_b32_e32 v38, 48, v37
	v_lshl_add_u64 v[36:37], s[4:5], 0, v[32:33]
	v_lshlrev_b32_e32 v32, 6, v39
	v_lshlrev_b32_e32 v39, 1, v52
	v_add_u32_e32 v55, 64, v52
	v_and_b32_e32 v70, 32, v39
	v_or_b32_e32 v69, v32, v38
	v_bitop3_b32 v59, v32, v70, v38 bitop3:0x36
	v_and_b32_e32 v32, 0x60, v55
	v_lshlrev_b32_e32 v38, 2, v55
	v_and_or_b32 v40, v38, 16, v32
	v_lshlrev_b32_e32 v32, 7, v55
	v_and_b32_e32 v32, 0x4000, v32
	v_lshl_add_u64 v[38:39], s[4:5], 0, v[32:33]
	v_lshrrev_b32_e32 v32, 3, v40
	v_or_b32_e32 v32, v32, v53
	v_lshlrev_b32_e32 v32, 10, v32
	v_add_u32_e32 v56, 0x80, v52
	v_bitop3_b32 v32, v32, v69, v70 bitop3:0xf6
	v_and_b32_e32 v58, 0x60, v52
	v_lshl_add_u64 v[38:39], v[38:39], 0, v[32:33]
	v_lshlrev_b32_e32 v32, 2, v56
	v_and_or_b32 v42, v32, 16, v58
	v_lshlrev_b32_e32 v32, 7, v56
	v_and_b32_e32 v32, 0x4000, v32
	v_lshl_add_u64 v[40:41], s[4:5], 0, v[32:33]
	v_lshrrev_b32_e32 v32, 3, v42
	v_or_b32_e32 v32, v32, v53
	v_lshlrev_b32_e32 v32, 10, v32
	v_add_u32_e32 v57, 0xc0, v52
	v_bitop3_b32 v32, v32, v69, v70 bitop3:0xf6
	v_lshl_add_u64 v[40:41], v[40:41], 0, v[32:33]
	v_and_b32_e32 v32, 0x60, v57
	v_lshlrev_b32_e32 v42, 2, v57
	v_and_or_b32 v71, v42, 16, v32
	v_lshlrev_b32_e32 v32, 7, v57
	v_and_b32_e32 v32, 0x4000, v32
	v_lshl_add_u64 v[42:43], s[4:5], 0, v[32:33]
	v_lshrrev_b32_e32 v32, 3, v71
	v_or_b32_e32 v32, v32, v53
	s_movk_i32 s6, 0x404
	v_lshlrev_b32_e32 v32, 10, v32
	v_mul_lo_u32 v60, v44, s6
	v_mul_lo_u32 v61, v45, s6
	v_mul_lo_u32 v62, v46, s6
	v_mul_lo_u32 v63, v47, s6
	v_mul_lo_u32 v64, v48, s6
	v_mul_lo_u32 v65, v49, s6
	v_mul_lo_u32 v66, v50, s6
	v_mul_lo_u32 v68, v51, s6
	v_bitop3_b32 v32, v32, v69, v70 bitop3:0xf6
	v_lshl_add_u64 v[42:43], v[42:43], 0, v[32:33]
	v_add_u32_e32 v60, v67, v60
	v_add_u32_e32 v61, v67, v61
	v_add_u32_e32 v62, v67, v62
	v_add_u32_e32 v63, v67, v63
	v_add_u32_e32 v64, v67, v64
	v_add_u32_e32 v65, v67, v65
	v_add_u32_e32 v66, v67, v66
	v_add_u32_e32 v67, v67, v68
	s_waitcnt vmcnt(0)
	s_branch .LBB0_1077

; __device__ __forceinline__ unsigned cvt_pk_bf16(float lo, float hi) { unsigned r; asm volatile("v_cvt_pk_bf16_f32 %0, %1, %2" : "=v"(r) : "v"(lo), "v"(hi)); return r; }
; __device__ __forceinline__ void convert_t(const float* __restrict__ W, int K, int N, bf16_t* __restrict__ Wt, int swiglu, int& cursor, float* tile, int perm) {
;     ...
;     for (; id < last; id += G) {
;         const int tl = (id - first) % nt; const int k0 = (tl / ntn) * 64, n0 = (tl % ntn) * 256;
; #pragma unroll
;         for (int i = 0; i < 8; ++i) { const int idx = tid + 512 * i; const int row = idx >> 6, c4 = idx & 63; float* d = tile + row * 257 + 4 * c4; d[0] = v[i].x; d[1] = v[i].y; d[2] = v[i].z; d[3] = v[i].w; }
;         __syncthreads();
;         if (id + G < last) { const int tl2 = (id + G - first) % nt; const int k2 = (tl2 / ntn) * 64, n2 = (tl2 % ntn) * 256;
; #pragma unroll
;             for (int i = 0; i < 8; ++i) { const int idx = tid + 512 * i; const int row = idx >> 6, c4 = idx & 63; v[i] = *(const float4*)(W + (size_t)(k2 + row) * N + n2 + 4 * c4); } }
; #pragma unroll
;         for (int p = 0; p < 4; ++p) { const int nl = (tid >> 3) + 64 * p, kq = tid & 7; const float* s = tile + (8 * kq) * 257 + nl;
;             u32x4 w; w.x = cvt_pk_bf16(s[0], s[257]); w.y = cvt_pk_bf16(s[2 * 257], s[3 * 257]); w.z = cvt_pk_bf16(s[4 * 257], s[5 * 257]); w.w = cvt_pk_bf16(s[6 * 257], s[7 * 257]);
;             int n = n0 + nl; if (swiglu) { const int half = n >= DFF ? 1 : 0; const int c = n - half * DFF; n = (c >> 7) * 256 + half * 128 + (c & 127); }
;             { const int pn = n >> 8, half = (n >> 7) & 1, r = n & 127, c5 = r & 31;
;               const int R = perm ? ((r & ~31) + 16 * ((c5 >> 2) & 1) + 4 * (c5 >> 3) + (c5 & 3)) : r;
;               *(u32x4*)((unsigned char*)Wt + ((size_t)pn * (K >> 6) + (k0 >> 6)) * 32768 + half * 16384 + pg8::lds_byte(R, 8 * kq)) = w; } }
;         __syncthreads();
;     }
.LBB0_1077:
	s_add_i32 s14, s12, s13
	s_add_i32 s4, s14, 0x1630
	s_cmpk_gt_i32 s4, 0x18df
	s_cselect_b64 s[4:5], -1, 0
	s_and_b64 vcc, exec, s[4:5]
	s_waitcnt vmcnt(11)
	ds_write2_b32 v60, v0, v1 offset1:1
	ds_write2_b32 v60, v2, v3 offset0:2 offset1:3
	s_waitcnt vmcnt(10)
	ds_write2_b32 v61, v4, v5 offset1:1
	ds_write2_b32 v61, v6, v7 offset0:2 offset1:3
	s_waitcnt vmcnt(9)
	ds_write2_b32 v62, v8, v9 offset1:1
	ds_write2_b32 v62, v10, v11 offset0:2 offset1:3
	s_waitcnt vmcnt(8)
	ds_write2_b32 v63, v12, v13 offset1:1
	ds_write2_b32 v63, v14, v15 offset0:2 offset1:3
	s_waitcnt vmcnt(7)
	ds_write2_b32 v64, v16, v17 offset1:1
	ds_write2_b32 v64, v18, v19 offset0:2 offset1:3
	s_waitcnt vmcnt(6)
	ds_write2_b32 v65, v20, v21 offset1:1
	ds_write2_b32 v65, v22, v23 offset0:2 offset1:3
	s_waitcnt vmcnt(5)
	ds_write2_b32 v66, v24, v25 offset1:1
	ds_write2_b32 v66, v26, v27 offset0:2 offset1:3
	s_waitcnt vmcnt(4)
	ds_write2_b32 v67, v28, v29 offset1:1
	ds_write2_b32 v67, v30, v31 offset0:2 offset1:3
	s_waitcnt lgkmcnt(0)
	s_barrier
	s_cbranch_vccnz .LBB0_1076
	s_mul_hi_i32 s6, s14, 0x2fa0be83
	s_lshr_b32 s7, s6, 31
	s_ashr_i32 s6, s6, 7
	s_add_i32 s6, s6, s7
	s_mulk_i32 s6, 0x2b0
	s_sub_i32 s6, s14, s6
	s_sext_i32_i16 s7, s6
	s_bfe_u32 s7, s7, 0x3001c
	s_add_i32 s7, s6, s7
	s_sext_i32_i16 s15, s7
	s_and_b32 s7, s7, 0xfff8
	s_lshl_b32 s15, s15, 3
	s_sub_i32 s6, s6, s7
	s_andn2_b32 s15, s15, 63
	s_sext_i32_i16 s6, s6
	s_lshl_b32 s6, s6, 8
	v_add_u32_e32 v0, s15, v44
	s_ashr_i32 s7, s6, 31
	v_ashrrev_i32_e32 v1, 31, v0
	v_lshl_add_u64 v[24:25], s[6:7], 2, v[34:35]
	v_lshlrev_b64 v[0:1], 13, v[0:1]
	v_lshl_add_u64 v[8:9], v[24:25], 0, v[0:1]
	v_add_u32_e32 v0, s15, v45
	v_ashrrev_i32_e32 v1, 31, v0
	v_lshlrev_b64 v[0:1], 13, v[0:1]
	v_lshl_add_u64 v[10:11], v[24:25], 0, v[0:1]
	global_load_dwordx4 v[0:3], v[8:9], off
	global_load_dwordx4 v[4:7], v[10:11], off
	v_add_u32_e32 v8, s15, v46
	v_ashrrev_i32_e32 v9, 31, v8
	v_lshlrev_b64 v[8:9], 13, v[8:9]
	v_lshl_add_u64 v[16:17], v[24:25], 0, v[8:9]
	v_add_u32_e32 v8, s15, v47
	v_ashrrev_i32_e32 v9, 31, v8
	v_lshlrev_b64 v[8:9], 13, v[8:9]
	v_lshl_add_u64 v[18:19], v[24:25], 0, v[8:9]
	global_load_dwordx4 v[8:11], v[16:17], off
	global_load_dwordx4 v[12:15], v[18:19], off
	v_add_u32_e32 v16, s15, v48
	v_ashrrev_i32_e32 v17, 31, v16
	v_lshlrev_b64 v[16:17], 13, v[16:17]
	v_lshl_add_u64 v[26:27], v[24:25], 0, v[16:17]
	v_add_u32_e32 v16, s15, v49
	v_ashrrev_i32_e32 v17, 31, v16
	v_lshlrev_b64 v[16:17], 13, v[16:17]
	v_lshl_add_u64 v[28:29], v[24:25], 0, v[16:17]
	global_load_dwordx4 v[16:19], v[26:27], off
	global_load_dwordx4 v[20:23], v[28:29], off
	v_add_u32_e32 v26, s15, v50
	v_ashrrev_i32_e32 v27, 31, v26
	v_lshlrev_b64 v[26:27], 13, v[26:27]
	v_lshl_add_u64 v[68:69], v[24:25], 0, v[26:27]
	v_add_u32_e32 v26, s15, v51
	v_ashrrev_i32_e32 v27, 31, v26
	v_lshlrev_b64 v[26:27], 13, v[26:27]
	v_lshl_add_u64 v[70:71], v[24:25], 0, v[26:27]
	global_load_dwordx4 v[24:27], v[68:69], off
	global_load_dwordx4 v[28:31], v[70:71], off
	s_branch .LBB0_1076
